# hoist epilogue loads (ss, residual base) ahead of stores in P6,P8,P10,P12,P13 GEMM epilogues; counted vmcnt
# speedup vs baseline: 1.0319x; 1.0319x over previous
.LBB0_952:
	ds_read_b128 v[144:147], v151
	ds_read_b128 v[156:159], v151 offset:1024
	ds_read_b128 v[160:163], v151 offset:2048
	ds_read_b128 v[164:167], v151 offset:3072
	s_add_u32 s26, s24, 0xfff80080
	s_addc_u32 s27, s25, -1
	s_cmp_eq_u32 s49, 28
	s_cselect_b32 s29, s15, s27
	s_cselect_b32 s28, s21, s26
	s_cselect_b32 s27, s13, s48
	s_cselect_b32 s26, s46, s47
	v_lshl_add_u64 v[168:169], s[24:25], 0, v[136:137]
	s_add_i32 m0, s23, 0xc000
	ds_read_b128 v[172:175], v152
	ds_read_b128 v[176:179], v152 offset:1024
	ds_read_b128 v[180:183], v152 offset:2048
	ds_read_b128 v[184:187], v152 offset:3072
	ds_read_b128 v[188:191], v152 offset:4096
	ds_read_b128 v[192:195], v152 offset:5120
	ds_read_b128 v[196:199], v152 offset:6144
	ds_read_b128 v[200:203], v152 offset:7168
	global_load_lds_dwordx4 v[168:169], off
	v_lshl_add_u64 v[168:169], s[24:25], 0, v[138:139]
	s_add_i32 m0, s23, 0xe000
	s_nop 0
	global_load_lds_dwordx4 v[168:169], off
	s_waitcnt lgkmcnt(8)
	s_barrier
	s_waitcnt lgkmcnt(0)
	s_setprio 1
	s_waitcnt lgkmcnt(0)
	v_mfma_f32_16x16x32_bf16 v[124:127], v[144:147], v[172:175], v[124:127]
	v_mfma_f32_16x16x32_bf16 v[120:123], v[160:163], v[172:175], v[120:123]
	v_mfma_f32_16x16x32_bf16 v[108:111], v[144:147], v[180:183], v[108:111]
	v_mfma_f32_16x16x32_bf16 v[104:107], v[160:163], v[180:183], v[104:107]
	v_mfma_f32_16x16x32_bf16 v[92:95], v[144:147], v[188:191], v[92:95]
	v_mfma_f32_16x16x32_bf16 v[88:91], v[160:163], v[188:191], v[88:91]
	v_mfma_f32_16x16x32_bf16 v[76:79], v[144:147], v[196:199], v[76:79]
	v_mfma_f32_16x16x32_bf16 v[72:75], v[160:163], v[196:199], v[72:75]
	v_mfma_f32_16x16x32_bf16 v[124:127], v[156:159], v[176:179], v[124:127]
	v_mfma_f32_16x16x32_bf16 v[120:123], v[164:167], v[176:179], v[120:123]
	v_mfma_f32_16x16x32_bf16 v[108:111], v[156:159], v[184:187], v[108:111]
	v_mfma_f32_16x16x32_bf16 v[104:107], v[164:167], v[184:187], v[104:107]
	v_mfma_f32_16x16x32_bf16 v[92:95], v[156:159], v[192:195], v[92:95]
	v_mfma_f32_16x16x32_bf16 v[88:91], v[164:167], v[192:195], v[88:91]
	v_mfma_f32_16x16x32_bf16 v[76:79], v[156:159], v[200:203], v[76:79]
	v_mfma_f32_16x16x32_bf16 v[72:75], v[164:167], v[200:203], v[72:75]
	s_setprio 0
	s_barrier
	s_add_i32 s50, s44, s34
	v_lshl_add_u64 v[168:169], s[26:27], 0, v[130:131]
	s_mov_b32 m0, s50
	ds_read_b128 v[204:207], v153
	ds_read_b128 v[208:211], v153 offset:1024
	ds_read_b128 v[212:215], v153 offset:2048
	ds_read_b128 v[216:219], v153 offset:3072
	global_load_lds_dwordx4 v[168:169], off
	v_lshl_add_u64 v[220:221], s[26:27], 0, v[134:135]
	s_add_i32 m0, s50, 0x2000
	s_nop 0
	global_load_lds_dwordx4 v[220:221], off
	s_barrier
	s_waitcnt lgkmcnt(0)
	s_setprio 1
	s_waitcnt lgkmcnt(0)
	v_mfma_f32_16x16x32_bf16 v[116:119], v[204:207], v[172:175], v[116:119]
	v_mfma_f32_16x16x32_bf16 v[112:115], v[212:215], v[172:175], v[112:115]
	v_mfma_f32_16x16x32_bf16 v[100:103], v[204:207], v[180:183], v[100:103]
	v_mfma_f32_16x16x32_bf16 v[96:99], v[212:215], v[180:183], v[96:99]
	v_mfma_f32_16x16x32_bf16 v[84:87], v[204:207], v[188:191], v[84:87]
	v_mfma_f32_16x16x32_bf16 v[80:83], v[212:215], v[188:191], v[80:83]
	v_mfma_f32_16x16x32_bf16 v[68:71], v[204:207], v[196:199], v[68:71]
	v_mfma_f32_16x16x32_bf16 v[64:67], v[212:215], v[196:199], v[64:67]
	v_mfma_f32_16x16x32_bf16 v[116:119], v[208:211], v[176:179], v[116:119]
	v_mfma_f32_16x16x32_bf16 v[112:115], v[216:219], v[176:179], v[112:115]
	v_mfma_f32_16x16x32_bf16 v[100:103], v[208:211], v[184:187], v[100:103]
	v_mfma_f32_16x16x32_bf16 v[96:99], v[216:219], v[184:187], v[96:99]
	v_mfma_f32_16x16x32_bf16 v[84:87], v[208:211], v[192:195], v[84:87]
	v_mfma_f32_16x16x32_bf16 v[80:83], v[216:219], v[192:195], v[80:83]
	v_mfma_f32_16x16x32_bf16 v[68:71], v[208:211], v[200:203], v[68:71]
	v_mfma_f32_16x16x32_bf16 v[64:67], v[216:219], v[200:203], v[64:67]
	s_setprio 0
	s_mov_b32 m0, s23
	v_lshl_add_u64 v[222:223], s[28:29], 0, v[128:129]
	s_barrier
	ds_read_b128 v[172:175], v152 offset:16384
	ds_read_b128 v[176:179], v152 offset:17408
	ds_read_b128 v[180:183], v152 offset:18432
	ds_read_b128 v[184:187], v152 offset:19456
	ds_read_b128 v[188:191], v152 offset:20480
	ds_read_b128 v[192:195], v152 offset:21504
	ds_read_b128 v[196:199], v152 offset:22528
	ds_read_b128 v[200:203], v152 offset:23552
	global_load_lds_dwordx4 v[222:223], off
	v_lshl_add_u64 v[224:225], s[28:29], 0, v[132:133]
	s_mov_b32 m0, s35
	s_nop 0
	global_load_lds_dwordx4 v[224:225], off
	s_barrier
	s_waitcnt lgkmcnt(0)
	s_setprio 1
	s_waitcnt lgkmcnt(0)
	v_mfma_f32_16x16x32_bf16 v[60:63], v[144:147], v[172:175], v[60:63]
	v_mfma_f32_16x16x32_bf16 v[56:59], v[160:163], v[172:175], v[56:59]
	v_mfma_f32_16x16x32_bf16 v[44:47], v[144:147], v[180:183], v[44:47]
	v_mfma_f32_16x16x32_bf16 v[40:43], v[160:163], v[180:183], v[40:43]
	v_mfma_f32_16x16x32_bf16 v[28:31], v[144:147], v[188:191], v[28:31]
	v_mfma_f32_16x16x32_bf16 v[24:27], v[160:163], v[188:191], v[24:27]
	v_mfma_f32_16x16x32_bf16 v[12:15], v[144:147], v[196:199], v[12:15]
	v_mfma_f32_16x16x32_bf16 v[8:11], v[160:163], v[196:199], v[8:11]
	v_mfma_f32_16x16x32_bf16 v[60:63], v[156:159], v[176:179], v[60:63]
	v_mfma_f32_16x16x32_bf16 v[56:59], v[164:167], v[176:179], v[56:59]
	v_mfma_f32_16x16x32_bf16 v[44:47], v[156:159], v[184:187], v[44:47]
	v_mfma_f32_16x16x32_bf16 v[40:43], v[164:167], v[184:187], v[40:43]
	v_mfma_f32_16x16x32_bf16 v[28:31], v[156:159], v[192:195], v[28:31]
	v_mfma_f32_16x16x32_bf16 v[24:27], v[164:167], v[192:195], v[24:27]
	v_mfma_f32_16x16x32_bf16 v[12:15], v[156:159], v[200:203], v[12:15]
	v_mfma_f32_16x16x32_bf16 v[8:11], v[164:167], v[200:203], v[8:11]
	s_setprio 0
	s_barrier
	s_add_u32 s50, s26, 0x80000
	s_addc_u32 s51, s27, 0
	s_add_i32 s52, s45, s34
	v_lshl_add_u64 v[144:145], s[50:51], 0, v[130:131]
	s_mov_b32 m0, s52
	s_nop 0
	global_load_lds_dwordx4 v[144:145], off
	v_lshl_add_u64 v[144:145], s[50:51], 0, v[134:135]
	s_add_i32 m0, s52, 0x2000
	s_nop 0
	global_load_lds_dwordx4 v[144:145], off
	s_waitcnt vmcnt(6)
	s_barrier
	s_setprio 1
	v_mfma_f32_16x16x32_bf16 v[52:55], v[204:207], v[172:175], v[52:55]
	v_mfma_f32_16x16x32_bf16 v[48:51], v[212:215], v[172:175], v[48:51]
	v_mfma_f32_16x16x32_bf16 v[36:39], v[204:207], v[180:183], v[36:39]
	v_mfma_f32_16x16x32_bf16 v[32:35], v[212:215], v[180:183], v[32:35]
	v_mfma_f32_16x16x32_bf16 v[20:23], v[204:207], v[188:191], v[20:23]
	v_mfma_f32_16x16x32_bf16 v[16:19], v[212:215], v[188:191], v[16:19]
	v_mfma_f32_16x16x32_bf16 v[4:7], v[204:207], v[196:199], v[4:7]
	v_mfma_f32_16x16x32_bf16 v[0:3], v[212:215], v[196:199], v[0:3]
	v_mfma_f32_16x16x32_bf16 v[52:55], v[208:211], v[176:179], v[52:55]
	v_mfma_f32_16x16x32_bf16 v[48:51], v[216:219], v[176:179], v[48:51]
	v_mfma_f32_16x16x32_bf16 v[36:39], v[208:211], v[184:187], v[36:39]
	v_mfma_f32_16x16x32_bf16 v[32:35], v[216:219], v[184:187], v[32:35]
	v_mfma_f32_16x16x32_bf16 v[20:23], v[208:211], v[192:195], v[20:23]
	v_mfma_f32_16x16x32_bf16 v[16:19], v[216:219], v[192:195], v[16:19]
	v_mfma_f32_16x16x32_bf16 v[4:7], v[208:211], v[200:203], v[4:7]
	v_mfma_f32_16x16x32_bf16 v[0:3], v[216:219], v[200:203], v[0:3]
	s_setprio 0
	s_add_i32 s50, 0, 0x18000
	v_add_u32_e32 v155, s50, v149
	s_barrier
	ds_read_b128 v[144:147], v155
	ds_read_b128 v[156:159], v155 offset:1024
	ds_read_b128 v[160:163], v155 offset:2048
	ds_read_b128 v[164:167], v155 offset:3072
	s_add_u32 s28, s28, 0x80000
	s_addc_u32 s29, s29, 0
	s_mov_b32 m0, s36
	v_lshl_add_u64 v[204:205], s[28:29], 0, v[128:129]
	ds_read_b128 v[172:175], v152 offset:32768
	ds_read_b128 v[176:179], v152 offset:33792
	ds_read_b128 v[180:183], v152 offset:34816
	ds_read_b128 v[184:187], v152 offset:35840
	ds_read_b128 v[188:191], v152 offset:36864
	ds_read_b128 v[192:195], v152 offset:37888
	ds_read_b128 v[196:199], v152 offset:38912
	ds_read_b128 v[200:203], v152 offset:39936
	global_load_lds_dwordx4 v[204:205], off
	v_lshl_add_u64 v[204:205], s[28:29], 0, v[132:133]
	s_mov_b32 m0, s37
	s_nop 0
	global_load_lds_dwordx4 v[204:205], off
	s_waitcnt lgkmcnt(8)
	s_barrier
	s_waitcnt lgkmcnt(0)
	s_setprio 1
	s_waitcnt lgkmcnt(0)
	v_mfma_f32_16x16x32_bf16 v[124:127], v[144:147], v[172:175], v[124:127]
	v_mfma_f32_16x16x32_bf16 v[120:123], v[160:163], v[172:175], v[120:123]
	v_mfma_f32_16x16x32_bf16 v[108:111], v[144:147], v[180:183], v[108:111]
	v_mfma_f32_16x16x32_bf16 v[104:107], v[160:163], v[180:183], v[104:107]
	v_mfma_f32_16x16x32_bf16 v[92:95], v[144:147], v[188:191], v[92:95]
	v_mfma_f32_16x16x32_bf16 v[88:91], v[160:163], v[188:191], v[88:91]
	v_mfma_f32_16x16x32_bf16 v[76:79], v[144:147], v[196:199], v[76:79]
	v_mfma_f32_16x16x32_bf16 v[72:75], v[160:163], v[196:199], v[72:75]
	v_mfma_f32_16x16x32_bf16 v[124:127], v[156:159], v[176:179], v[124:127]
	v_mfma_f32_16x16x32_bf16 v[120:123], v[164:167], v[176:179], v[120:123]
	v_mfma_f32_16x16x32_bf16 v[108:111], v[156:159], v[184:187], v[108:111]
	v_mfma_f32_16x16x32_bf16 v[104:107], v[164:167], v[184:187], v[104:107]
	v_mfma_f32_16x16x32_bf16 v[92:95], v[156:159], v[192:195], v[92:95]
	v_mfma_f32_16x16x32_bf16 v[88:91], v[164:167], v[192:195], v[88:91]
	v_mfma_f32_16x16x32_bf16 v[76:79], v[156:159], v[200:203], v[76:79]
	v_mfma_f32_16x16x32_bf16 v[72:75], v[164:167], v[200:203], v[72:75]
	s_setprio 0
	s_barrier
	s_add_i32 s28, 0, 0x1c000
	s_add_i32 s29, s50, s34
	v_add_u32_e32 v155, s28, v149
	v_lshl_add_u64 v[168:169], v[168:169], 0, s[10:11]
	s_mov_b32 m0, s29
	ds_read_b128 v[204:207], v155
	ds_read_b128 v[208:211], v155 offset:1024
	ds_read_b128 v[212:215], v155 offset:2048
	ds_read_b128 v[216:219], v155 offset:3072
	global_load_lds_dwordx4 v[168:169], off
	v_lshl_add_u64 v[168:169], v[220:221], 0, s[10:11]
	s_add_i32 m0, s29, 0x2000
	s_nop 0
	global_load_lds_dwordx4 v[168:169], off
	s_barrier
	s_waitcnt lgkmcnt(0)
	s_setprio 1
	s_waitcnt lgkmcnt(0)
	v_mfma_f32_16x16x32_bf16 v[116:119], v[204:207], v[172:175], v[116:119]
	v_mfma_f32_16x16x32_bf16 v[112:115], v[212:215], v[172:175], v[112:115]
	v_mfma_f32_16x16x32_bf16 v[100:103], v[204:207], v[180:183], v[100:103]
	v_mfma_f32_16x16x32_bf16 v[96:99], v[212:215], v[180:183], v[96:99]
	v_mfma_f32_16x16x32_bf16 v[84:87], v[204:207], v[188:191], v[84:87]
	v_mfma_f32_16x16x32_bf16 v[80:83], v[212:215], v[188:191], v[80:83]
	v_mfma_f32_16x16x32_bf16 v[68:71], v[204:207], v[196:199], v[68:71]
	v_mfma_f32_16x16x32_bf16 v[64:67], v[212:215], v[196:199], v[64:67]
	v_mfma_f32_16x16x32_bf16 v[116:119], v[208:211], v[176:179], v[116:119]
	v_mfma_f32_16x16x32_bf16 v[112:115], v[216:219], v[176:179], v[112:115]
	v_mfma_f32_16x16x32_bf16 v[100:103], v[208:211], v[184:187], v[100:103]
	v_mfma_f32_16x16x32_bf16 v[96:99], v[216:219], v[184:187], v[96:99]
	v_mfma_f32_16x16x32_bf16 v[84:87], v[208:211], v[192:195], v[84:87]
	v_mfma_f32_16x16x32_bf16 v[80:83], v[216:219], v[192:195], v[80:83]
	v_mfma_f32_16x16x32_bf16 v[68:71], v[208:211], v[200:203], v[68:71]
	v_mfma_f32_16x16x32_bf16 v[64:67], v[216:219], v[200:203], v[64:67]
	s_setprio 0
	s_mov_b32 m0, s41
	v_lshl_add_u64 v[168:169], v[222:223], 0, s[10:11]
	s_barrier
	ds_read_b128 v[172:175], v152 offset:49152
	ds_read_b128 v[176:179], v152 offset:50176
	ds_read_b128 v[180:183], v152 offset:51200
	ds_read_b128 v[184:187], v152 offset:52224
	ds_read_b128 v[188:191], v152 offset:53248
	ds_read_b128 v[192:195], v152 offset:54272
	ds_read_b128 v[196:199], v152 offset:55296
	ds_read_b128 v[200:203], v152 offset:56320
	global_load_lds_dwordx4 v[168:169], off
	v_lshl_add_u64 v[168:169], v[224:225], 0, s[10:11]
	s_mov_b32 m0, s42
	s_nop 0
	global_load_lds_dwordx4 v[168:169], off
	s_barrier
	s_waitcnt lgkmcnt(0)
	s_setprio 1
	s_waitcnt lgkmcnt(0)
	v_mfma_f32_16x16x32_bf16 v[60:63], v[144:147], v[172:175], v[60:63]
	v_mfma_f32_16x16x32_bf16 v[56:59], v[160:163], v[172:175], v[56:59]
	v_mfma_f32_16x16x32_bf16 v[44:47], v[144:147], v[180:183], v[44:47]
	v_mfma_f32_16x16x32_bf16 v[40:43], v[160:163], v[180:183], v[40:43]
	v_mfma_f32_16x16x32_bf16 v[28:31], v[144:147], v[188:191], v[28:31]
	v_mfma_f32_16x16x32_bf16 v[24:27], v[160:163], v[188:191], v[24:27]
	v_mfma_f32_16x16x32_bf16 v[12:15], v[144:147], v[196:199], v[12:15]
	v_mfma_f32_16x16x32_bf16 v[8:11], v[160:163], v[196:199], v[8:11]
	v_mfma_f32_16x16x32_bf16 v[60:63], v[156:159], v[176:179], v[60:63]
	v_mfma_f32_16x16x32_bf16 v[56:59], v[164:167], v[176:179], v[56:59]
	v_mfma_f32_16x16x32_bf16 v[44:47], v[156:159], v[184:187], v[44:47]
	v_mfma_f32_16x16x32_bf16 v[40:43], v[164:167], v[184:187], v[40:43]
	v_mfma_f32_16x16x32_bf16 v[28:31], v[156:159], v[192:195], v[28:31]
	v_mfma_f32_16x16x32_bf16 v[24:27], v[164:167], v[192:195], v[24:27]
	v_mfma_f32_16x16x32_bf16 v[12:15], v[156:159], v[200:203], v[12:15]
	v_mfma_f32_16x16x32_bf16 v[8:11], v[164:167], v[200:203], v[8:11]
	s_setprio 0
	s_barrier
	s_add_u32 s26, s26, 0x80080
	s_addc_u32 s27, s27, 0
	s_add_i32 s28, s28, s34
	v_lshl_add_u64 v[144:145], s[26:27], 0, v[130:131]
	s_mov_b32 m0, s28
	s_nop 0
	global_load_lds_dwordx4 v[144:145], off
	v_lshl_add_u64 v[144:145], s[26:27], 0, v[134:135]
	s_add_i32 m0, s28, 0x2000
	s_nop 0
	global_load_lds_dwordx4 v[144:145], off
	s_waitcnt vmcnt(6)
	s_barrier
	s_setprio 1
	v_mfma_f32_16x16x32_bf16 v[52:55], v[204:207], v[172:175], v[52:55]
	v_mfma_f32_16x16x32_bf16 v[48:51], v[212:215], v[172:175], v[48:51]
	v_mfma_f32_16x16x32_bf16 v[36:39], v[204:207], v[180:183], v[36:39]
	v_mfma_f32_16x16x32_bf16 v[32:35], v[212:215], v[180:183], v[32:35]
	v_mfma_f32_16x16x32_bf16 v[20:23], v[204:207], v[188:191], v[20:23]
	v_mfma_f32_16x16x32_bf16 v[16:19], v[212:215], v[188:191], v[16:19]
	v_mfma_f32_16x16x32_bf16 v[4:7], v[204:207], v[196:199], v[4:7]
	v_mfma_f32_16x16x32_bf16 v[0:3], v[212:215], v[196:199], v[0:3]
	v_mfma_f32_16x16x32_bf16 v[52:55], v[208:211], v[176:179], v[52:55]
	v_mfma_f32_16x16x32_bf16 v[48:51], v[216:219], v[176:179], v[48:51]
	v_mfma_f32_16x16x32_bf16 v[36:39], v[208:211], v[184:187], v[36:39]
	v_mfma_f32_16x16x32_bf16 v[32:35], v[216:219], v[184:187], v[32:35]
	v_mfma_f32_16x16x32_bf16 v[20:23], v[208:211], v[192:195], v[20:23]
	v_mfma_f32_16x16x32_bf16 v[16:19], v[216:219], v[192:195], v[16:19]
	v_mfma_f32_16x16x32_bf16 v[4:7], v[208:211], v[200:203], v[4:7]
	v_mfma_f32_16x16x32_bf16 v[0:3], v[216:219], v[200:203], v[0:3]
	s_setprio 0
	s_add_i32 s49, s49, 2
	s_add_u32 s24, s24, 0x100
	s_addc_u32 s25, s25, 0
	s_add_u32 s47, s47, 0x100
	s_addc_u32 s48, s48, 0
	s_cmp_gt_u32 s49, 29
	s_barrier
	s_cbranch_scc0 .LBB0_952
	v_lshl_add_u32 v146, s22, 8, v148
	v_lshl_or_b32 v144, s20, 8, v150
	v_readlane_b32 s98, v235, 6
	v_readlane_b32 s99, v235, 7
	v_lshlrev_b32_e32 v225, 13, v146
	v_lshl_add_u32 v224, v144, 2, v225
	s_nop 4
	s_add_u32 s100, s98, 0x0
	s_addc_u32 s101, s99, 0
	global_load_dwordx4 v[172:175], v224, s[100:101] nt
	global_load_dwordx4 v[176:179], v224, s[100:101] offset:16 nt
	global_load_dwordx4 v[180:183], v224, s[100:101] offset:512 nt
	global_load_dwordx4 v[184:187], v224, s[100:101] offset:528 nt
	s_add_u32 s100, s98, 0x20000
	s_addc_u32 s101, s99, 0
	global_load_dwordx4 v[188:191], v224, s[100:101] nt
	global_load_dwordx4 v[192:195], v224, s[100:101] offset:16 nt
	global_load_dwordx4 v[196:199], v224, s[100:101] offset:512 nt
	global_load_dwordx4 v[200:203], v224, s[100:101] offset:528 nt
	s_add_u32 s100, s98, 0x40000
	s_addc_u32 s101, s99, 0
	global_load_dwordx4 v[204:207], v224, s[100:101] nt
	global_load_dwordx4 v[208:211], v224, s[100:101] offset:16 nt
	global_load_dwordx4 v[212:215], v224, s[100:101] offset:512 nt
	global_load_dwordx4 v[216:219], v224, s[100:101] offset:528 nt
	s_add_u32 s100, s98, 0x60000
	s_addc_u32 s101, s99, 0
	global_load_dwordx4 v[220:223], v224, s[100:101] nt
	global_load_dwordx4 v[236:239], v224, s[100:101] offset:16 nt
	global_load_dwordx4 v[240:243], v224, s[100:101] offset:512 nt
	global_load_dwordx4 v[244:247], v224, s[100:101] offset:528 nt
	v_ashrrev_i32_e32 v147, 31, v146
	v_ashrrev_i32_e32 v145, 31, v144
	v_lshlrev_b64 v[156:157], 11, v[146:147]
	v_readlane_b32 s48, v235, 6
	v_lshl_add_u64 v[164:165], v[156:157], 0, v[144:145]
	v_readlane_b32 s49, v235, 7
	v_xor_b32_e32 v155, 32, v154
	v_readlane_b32 s50, v235, 8
	v_lshl_add_u64 v[166:167], v[164:165], 2, s[48:49]
	v_lshl_add_u64 v[164:165], v[164:165], 1, s[6:7]
	v_readlane_b32 s51, v235, 9
	v_readlane_b32 s52, v235, 10
	v_readlane_b32 s53, v235, 11
	v_readlane_b32 s54, v235, 12
	v_readlane_b32 s55, v235, 13
	v_readlane_b32 s56, v235, 14
	v_readlane_b32 s57, v235, 15
	v_readlane_b32 s58, v235, 16
	v_readlane_b32 s59, v235, 17
	v_readlane_b32 s60, v235, 18
	v_readlane_b32 s61, v235, 19
	v_readlane_b32 s62, v235, 20
	v_readlane_b32 s63, v235, 21
	s_waitcnt vmcnt(14)
	v_pk_add_f32 v[126:127], v[126:127], v[174:175]
	v_pk_add_f32 v[168:169], v[124:125], v[172:173]
	v_pk_add_f32 v[178:179], v[122:123], v[178:179]
	v_pk_add_f32 v[176:177], v[120:121], v[176:177]
	v_cvt_pk_bf16_f32 v120, v168, v169
	v_cvt_pk_bf16_f32 v121, v126, v127
	v_cvt_pk_bf16_f32 v122, v176, v177
	v_cvt_pk_bf16_f32 v123, v178, v179
	global_store_dwordx4 v[164:165], v[120:123], off
	s_nop 0
	v_mul_f32_e32 v166, v169, v169
	v_mul_f32_e32 v127, v127, v127
	v_and_b32_e32 v121, 64, v154
	v_mul_f32_e32 v177, v177, v177
	v_fmac_f32_e32 v166, v168, v168
	v_fmac_f32_e32 v127, v126, v126
	v_xor_b32_e32 v120, 16, v154
	v_add_u32_e32 v121, 64, v121
	v_mul_f32_e32 v179, v179, v179
	v_fmac_f32_e32 v177, v176, v176
	v_add_f32_e32 v126, v166, v127
	v_cmp_lt_i32_e32 vcc, v120, v121
	v_fmac_f32_e32 v179, v178, v178
	v_add_f32_e32 v126, v126, v177
	v_cndmask_b32_e32 v120, v154, v120, vcc
	v_add_f32_e32 v126, v179, v126
	v_lshlrev_b32_e32 v120, 2, v120
	v_cmp_lt_i32_e32 vcc, v155, v121
	s_waitcnt vmcnt(13)
	v_pk_add_f32 v[118:119], v[118:119], v[182:183]
	v_pk_add_f32 v[116:117], v[116:117], v[180:181]
	v_pk_add_f32 v[182:183], v[112:113], v[184:185]
	v_mul_f32_e32 v112, v117, v117
	v_mul_f32_e32 v113, v119, v119
	v_pk_add_f32 v[180:181], v[114:115], v[186:187]
	v_mul_f32_e32 v114, v183, v183
	v_fmac_f32_e32 v112, v116, v116
	v_fmac_f32_e32 v113, v118, v118
	v_mul_f32_e32 v115, v181, v181
	v_fmac_f32_e32 v114, v182, v182
	v_add_f32_e32 v112, v112, v113
	v_add_f32_e32 v112, v112, v114
	v_fmac_f32_e32 v115, v180, v180
	v_add_f32_e32 v112, v115, v112
	v_add_f32_e32 v112, v126, v112
	ds_bpermute_b32 v113, v120, v112
	v_cndmask_b32_e32 v114, v154, v155, vcc
	v_lshlrev_b32_e32 v114, 2, v114
	v_cvt_pk_bf16_f32 v116, v116, v117
	v_cvt_pk_bf16_f32 v117, v118, v119
	s_waitcnt lgkmcnt(0)
	v_add_f32_e32 v112, v112, v113
	ds_bpermute_b32 v113, v114, v112
	v_cvt_pk_bf16_f32 v118, v182, v183
	v_cvt_pk_bf16_f32 v119, v180, v181
	global_store_dwordx4 v[164:165], v[116:119], off offset:256
	s_and_saveexec_b64 s[20:21], s[2:3]
	s_cbranch_execz .LBB0_955
	v_lshl_add_u64 v[116:117], v[146:147], 2, s[8:9]
	s_waitcnt lgkmcnt(0)
	v_add_f32_e32 v112, v112, v113
	global_atomic_add_f32 v[116:117], v112, off
.LBB0_955:
	s_or_b64 exec, exec, s[20:21]
	s_add_u32 s100, s98, 0x100000
	s_addc_u32 s101, s99, 0
	global_load_dwordx4 v[172:175], v224, s[100:101] nt
	global_load_dwordx4 v[176:179], v224, s[100:101] offset:16 nt
	global_load_dwordx4 v[180:183], v224, s[100:101] offset:512 nt
	global_load_dwordx4 v[184:187], v224, s[100:101] offset:528 nt
	v_or_b32_e32 v112, 16, v146
	s_waitcnt lgkmcnt(0)
	v_ashrrev_i32_e32 v113, 31, v112
	v_lshlrev_b64 v[116:117], 11, v[112:113]
	v_readlane_b32 s48, v235, 6
	v_lshl_add_u64 v[126:127], v[116:117], 0, v[144:145]
	v_readlane_b32 s49, v235, 7
	v_readlane_b32 s50, v235, 8
	v_readlane_b32 s51, v235, 9
	v_lshl_add_u64 v[156:157], v[126:127], 2, s[48:49]
	v_lshl_add_u64 v[126:127], v[126:127], 1, s[6:7]
	v_readlane_b32 s52, v235, 10
	v_readlane_b32 s53, v235, 11
	v_readlane_b32 s54, v235, 12
	v_readlane_b32 s55, v235, 13
	v_readlane_b32 s56, v235, 14
	v_readlane_b32 s57, v235, 15
	v_readlane_b32 s58, v235, 16
	v_readlane_b32 s59, v235, 17
	v_readlane_b32 s60, v235, 18
	v_readlane_b32 s61, v235, 19
	v_readlane_b32 s62, v235, 20
	v_readlane_b32 s63, v235, 21
	s_waitcnt vmcnt(18)
	v_pk_add_f32 v[190:191], v[110:111], v[190:191]
	v_pk_add_f32 v[188:189], v[108:109], v[188:189]
	s_waitcnt vmcnt(17)
	v_pk_add_f32 v[194:195], v[106:107], v[194:195]
	v_pk_add_f32 v[192:193], v[104:105], v[192:193]
	v_cvt_pk_bf16_f32 v104, v188, v189
	v_cvt_pk_bf16_f32 v105, v190, v191
	v_cvt_pk_bf16_f32 v106, v192, v193
	v_cvt_pk_bf16_f32 v107, v194, v195
	global_store_dwordx4 v[126:127], v[104:107], off
	s_nop 0
	v_mul_f32_e32 v115, v189, v189
	v_mul_f32_e32 v189, v191, v191
	v_mul_f32_e32 v191, v193, v193
	v_fmac_f32_e32 v115, v188, v188
	v_fmac_f32_e32 v189, v190, v190
	v_mul_f32_e32 v121, v195, v195
	v_fmac_f32_e32 v191, v192, v192
	v_add_f32_e32 v115, v115, v189
	v_fmac_f32_e32 v121, v194, v194
	v_add_f32_e32 v115, v115, v191
	v_add_f32_e32 v115, v121, v115
	s_waitcnt vmcnt(17)
	v_pk_add_f32 v[102:103], v[102:103], v[198:199]
	v_pk_add_f32 v[100:101], v[100:101], v[196:197]
	s_waitcnt vmcnt(16)
	v_pk_add_f32 v[198:199], v[96:97], v[200:201]
	v_mul_f32_e32 v96, v101, v101
	v_mul_f32_e32 v97, v103, v103
	v_pk_add_f32 v[196:197], v[98:99], v[202:203]
	v_mul_f32_e32 v98, v199, v199
	v_fmac_f32_e32 v96, v100, v100
	v_fmac_f32_e32 v97, v102, v102
	v_mul_f32_e32 v99, v197, v197
	v_fmac_f32_e32 v98, v198, v198
	v_add_f32_e32 v96, v96, v97
	v_add_f32_e32 v96, v96, v98
	v_fmac_f32_e32 v99, v196, v196
	v_add_f32_e32 v96, v99, v96
	v_add_f32_e32 v96, v115, v96
	ds_bpermute_b32 v97, v120, v96
	v_cvt_pk_bf16_f32 v98, v100, v101
	v_cvt_pk_bf16_f32 v99, v102, v103
	v_cvt_pk_bf16_f32 v100, v198, v199
	v_cvt_pk_bf16_f32 v101, v196, v197
	s_waitcnt lgkmcnt(0)
	v_add_f32_e32 v96, v96, v97
	ds_bpermute_b32 v97, v114, v96
	global_store_dwordx4 v[126:127], v[98:101], off offset:256
	s_and_saveexec_b64 s[20:21], s[2:3]
	s_cbranch_execz .LBB0_957
	v_lshl_add_u64 v[98:99], v[112:113], 2, s[8:9]
	s_waitcnt lgkmcnt(0)
	v_add_f32_e32 v96, v96, v97
	global_atomic_add_f32 v[98:99], v96, off
.LBB0_957:
	s_or_b64 exec, exec, s[20:21]
	s_add_u32 s100, s98, 0x120000
	s_addc_u32 s101, s99, 0
	global_load_dwordx4 v[188:191], v224, s[100:101] nt
	global_load_dwordx4 v[192:195], v224, s[100:101] offset:16 nt
	global_load_dwordx4 v[196:199], v224, s[100:101] offset:512 nt
	global_load_dwordx4 v[200:203], v224, s[100:101] offset:528 nt
	v_or_b32_e32 v96, 32, v146
	s_waitcnt lgkmcnt(0)
	v_ashrrev_i32_e32 v97, 31, v96
	v_lshlrev_b64 v[98:99], 11, v[96:97]
	v_readlane_b32 s48, v235, 6
	v_lshl_add_u64 v[106:107], v[98:99], 0, v[144:145]
	v_readlane_b32 s49, v235, 7
	v_readlane_b32 s50, v235, 8
	v_readlane_b32 s51, v235, 9
	v_lshl_add_u64 v[108:109], v[106:107], 2, s[48:49]
	v_lshl_add_u64 v[106:107], v[106:107], 1, s[6:7]
	v_readlane_b32 s52, v235, 10
	v_readlane_b32 s53, v235, 11
	v_readlane_b32 s54, v235, 12
	v_readlane_b32 s55, v235, 13
	v_readlane_b32 s56, v235, 14
	v_readlane_b32 s57, v235, 15
	v_readlane_b32 s58, v235, 16
	v_readlane_b32 s59, v235, 17
	v_readlane_b32 s60, v235, 18
	v_readlane_b32 s61, v235, 19
	v_readlane_b32 s62, v235, 20
	v_readlane_b32 s63, v235, 21
	s_waitcnt vmcnt(21)
	v_pk_add_f32 v[206:207], v[94:95], v[206:207]
	v_pk_add_f32 v[204:205], v[92:93], v[204:205]
	s_waitcnt vmcnt(20)
	v_pk_add_f32 v[210:211], v[90:91], v[210:211]
	v_pk_add_f32 v[208:209], v[88:89], v[208:209]
	v_cvt_pk_bf16_f32 v88, v204, v205
	v_cvt_pk_bf16_f32 v89, v206, v207
	v_cvt_pk_bf16_f32 v90, v208, v209
	v_cvt_pk_bf16_f32 v91, v210, v211
	global_store_dwordx4 v[106:107], v[88:91], off
	s_nop 0
	v_mul_f32_e32 v205, v205, v205
	v_mul_f32_e32 v207, v207, v207
	v_mul_f32_e32 v209, v209, v209
	v_fmac_f32_e32 v205, v204, v204
	v_fmac_f32_e32 v207, v206, v206
	v_mul_f32_e32 v211, v211, v211
	v_fmac_f32_e32 v209, v208, v208
	v_add_f32_e32 v204, v205, v207
	v_fmac_f32_e32 v211, v210, v210
	v_add_f32_e32 v204, v204, v209
	v_add_f32_e32 v204, v211, v204
	s_waitcnt vmcnt(20)
	v_pk_add_f32 v[86:87], v[86:87], v[214:215]
	v_pk_add_f32 v[84:85], v[84:85], v[212:213]
	s_waitcnt vmcnt(19)
	v_pk_add_f32 v[214:215], v[80:81], v[216:217]
	v_mul_f32_e32 v80, v85, v85
	v_mul_f32_e32 v81, v87, v87
	v_pk_add_f32 v[212:213], v[82:83], v[218:219]
	v_mul_f32_e32 v82, v215, v215
	v_fmac_f32_e32 v80, v84, v84
	v_fmac_f32_e32 v81, v86, v86
	v_mul_f32_e32 v83, v213, v213
	v_fmac_f32_e32 v82, v214, v214
	v_add_f32_e32 v80, v80, v81
	v_add_f32_e32 v80, v80, v82
	v_fmac_f32_e32 v83, v212, v212
	v_add_f32_e32 v80, v83, v80
	v_add_f32_e32 v80, v204, v80
	ds_bpermute_b32 v81, v120, v80
	v_cvt_pk_bf16_f32 v82, v84, v85
	v_cvt_pk_bf16_f32 v83, v86, v87
	v_cvt_pk_bf16_f32 v84, v214, v215
	v_cvt_pk_bf16_f32 v85, v212, v213
	s_waitcnt lgkmcnt(0)
	v_add_f32_e32 v80, v80, v81
	ds_bpermute_b32 v81, v114, v80
	global_store_dwordx4 v[106:107], v[82:85], off offset:256
	s_and_saveexec_b64 s[20:21], s[2:3]
	s_cbranch_execz .LBB0_959
	v_lshl_add_u64 v[82:83], v[96:97], 2, s[8:9]
	s_waitcnt lgkmcnt(0)
	v_add_f32_e32 v80, v80, v81
	global_atomic_add_f32 v[82:83], v80, off
.LBB0_959:
	s_or_b64 exec, exec, s[20:21]
	s_add_u32 s100, s98, 0x140000
	s_addc_u32 s101, s99, 0
	global_load_dwordx4 v[204:207], v224, s[100:101] nt
	global_load_dwordx4 v[208:211], v224, s[100:101] offset:16 nt
	global_load_dwordx4 v[212:215], v224, s[100:101] offset:512 nt
	global_load_dwordx4 v[216:219], v224, s[100:101] offset:528 nt
	v_or_b32_e32 v80, 48, v146
	s_waitcnt lgkmcnt(0)
	v_ashrrev_i32_e32 v81, 31, v80
	v_lshlrev_b64 v[82:83], 11, v[80:81]
	v_readlane_b32 s48, v235, 6
	v_lshl_add_u64 v[90:91], v[82:83], 0, v[144:145]
	v_readlane_b32 s49, v235, 7
	v_readlane_b32 s50, v235, 8
	v_readlane_b32 s51, v235, 9
	v_lshl_add_u64 v[92:93], v[90:91], 2, s[48:49]
	v_lshl_add_u64 v[90:91], v[90:91], 1, s[6:7]
	v_readlane_b32 s52, v235, 10
	v_readlane_b32 s53, v235, 11
	v_readlane_b32 s54, v235, 12
	v_readlane_b32 s55, v235, 13
	v_readlane_b32 s56, v235, 14
	v_readlane_b32 s57, v235, 15
	v_readlane_b32 s58, v235, 16
	v_readlane_b32 s59, v235, 17
	v_readlane_b32 s60, v235, 18
	v_readlane_b32 s61, v235, 19
	v_readlane_b32 s62, v235, 20
	v_readlane_b32 s63, v235, 21
	s_waitcnt vmcnt(24)
	v_pk_add_f32 v[222:223], v[78:79], v[222:223]
	v_pk_add_f32 v[220:221], v[76:77], v[220:221]
	s_waitcnt vmcnt(23)
	v_pk_add_f32 v[238:239], v[74:75], v[238:239]
	v_pk_add_f32 v[236:237], v[72:73], v[236:237]
	v_cvt_pk_bf16_f32 v72, v220, v221
	v_cvt_pk_bf16_f32 v73, v222, v223
	v_cvt_pk_bf16_f32 v74, v236, v237
	v_cvt_pk_bf16_f32 v75, v238, v239
	global_store_dwordx4 v[90:91], v[72:75], off
	s_nop 0
	v_mul_f32_e32 v221, v221, v221
	v_mul_f32_e32 v223, v223, v223
	v_mul_f32_e32 v237, v237, v237
	v_fmac_f32_e32 v221, v220, v220
	v_fmac_f32_e32 v223, v222, v222
	v_mul_f32_e32 v239, v239, v239
	v_fmac_f32_e32 v237, v236, v236
	v_add_f32_e32 v220, v221, v223
	v_fmac_f32_e32 v239, v238, v238
	v_add_f32_e32 v220, v220, v237
	v_add_f32_e32 v220, v239, v220
	s_waitcnt vmcnt(23)
	v_pk_add_f32 v[70:71], v[70:71], v[242:243]
	v_pk_add_f32 v[68:69], v[68:69], v[240:241]
	s_waitcnt vmcnt(22)
	v_pk_add_f32 v[242:243], v[64:65], v[244:245]
	v_mul_f32_e32 v64, v69, v69
	v_mul_f32_e32 v65, v71, v71
	v_pk_add_f32 v[240:241], v[66:67], v[246:247]
	v_mul_f32_e32 v66, v243, v243
	v_fmac_f32_e32 v64, v68, v68
	v_fmac_f32_e32 v65, v70, v70
	v_mul_f32_e32 v67, v241, v241
	v_fmac_f32_e32 v66, v242, v242
	v_add_f32_e32 v64, v64, v65
	v_add_f32_e32 v64, v64, v66
	v_fmac_f32_e32 v67, v240, v240
	v_add_f32_e32 v64, v67, v64
	v_add_f32_e32 v64, v220, v64
	ds_bpermute_b32 v65, v120, v64
	v_cvt_pk_bf16_f32 v66, v68, v69
	v_cvt_pk_bf16_f32 v67, v70, v71
	v_cvt_pk_bf16_f32 v68, v242, v243
	v_cvt_pk_bf16_f32 v69, v240, v241
	s_waitcnt lgkmcnt(0)
	v_add_f32_e32 v64, v64, v65
	ds_bpermute_b32 v65, v114, v64
	global_store_dwordx4 v[90:91], v[66:69], off offset:256
	s_and_saveexec_b64 s[20:21], s[2:3]
	s_cbranch_execz .LBB0_961
	v_lshl_add_u64 v[66:67], v[80:81], 2, s[8:9]
	s_waitcnt lgkmcnt(0)
	v_add_f32_e32 v64, v64, v65
	global_atomic_add_f32 v[66:67], v64, off
.LBB0_961:
	s_or_b64 exec, exec, s[20:21]
	s_add_u32 s100, s98, 0x160000
	s_addc_u32 s101, s99, 0
	global_load_dwordx4 v[220:223], v224, s[100:101] nt
	global_load_dwordx4 v[236:239], v224, s[100:101] offset:16 nt
	global_load_dwordx4 v[240:243], v224, s[100:101] offset:512 nt
	global_load_dwordx4 v[244:247], v224, s[100:101] offset:528 nt
	v_add_u32_e32 v64, 0x80, v146
	s_waitcnt lgkmcnt(0)
	v_ashrrev_i32_e32 v65, 31, v64
	v_lshlrev_b64 v[66:67], 11, v[64:65]
	v_readlane_b32 s48, v235, 6
	v_lshl_add_u64 v[74:75], v[66:67], 0, v[144:145]
	v_readlane_b32 s49, v235, 7
	v_readlane_b32 s50, v235, 8
	v_readlane_b32 s51, v235, 9
	v_lshl_add_u64 v[76:77], v[74:75], 2, s[48:49]
	v_lshl_add_u64 v[74:75], v[74:75], 1, s[6:7]
	v_readlane_b32 s52, v235, 10
	v_readlane_b32 s53, v235, 11
	v_readlane_b32 s54, v235, 12
	v_readlane_b32 s55, v235, 13
	v_readlane_b32 s56, v235, 14
	v_readlane_b32 s57, v235, 15
	v_readlane_b32 s58, v235, 16
	v_readlane_b32 s59, v235, 17
	v_readlane_b32 s60, v235, 18
	v_readlane_b32 s61, v235, 19
	v_readlane_b32 s62, v235, 20
	v_readlane_b32 s63, v235, 21
	s_waitcnt vmcnt(24)
	v_pk_add_f32 v[174:175], v[62:63], v[174:175]
	v_pk_add_f32 v[172:173], v[60:61], v[172:173]
	s_waitcnt vmcnt(23)
	v_pk_add_f32 v[178:179], v[58:59], v[178:179]
	v_pk_add_f32 v[176:177], v[56:57], v[176:177]
	v_cvt_pk_bf16_f32 v56, v172, v173
	v_cvt_pk_bf16_f32 v57, v174, v175
	v_cvt_pk_bf16_f32 v58, v176, v177
	v_cvt_pk_bf16_f32 v59, v178, v179
	global_store_dwordx4 v[74:75], v[56:59], off
	s_nop 0
	v_mul_f32_e32 v173, v173, v173
	v_mul_f32_e32 v175, v175, v175
	v_mul_f32_e32 v177, v177, v177
	v_fmac_f32_e32 v173, v172, v172
	v_fmac_f32_e32 v175, v174, v174
	v_mul_f32_e32 v179, v179, v179
	v_fmac_f32_e32 v177, v176, v176
	v_add_f32_e32 v172, v173, v175
	v_fmac_f32_e32 v179, v178, v178
	v_add_f32_e32 v172, v172, v177
	v_add_f32_e32 v172, v179, v172
	s_waitcnt vmcnt(23)
	v_pk_add_f32 v[54:55], v[54:55], v[182:183]
	v_pk_add_f32 v[52:53], v[52:53], v[180:181]
	s_waitcnt vmcnt(22)
	v_pk_add_f32 v[182:183], v[48:49], v[184:185]
	v_mul_f32_e32 v48, v53, v53
	v_mul_f32_e32 v49, v55, v55
	v_pk_add_f32 v[180:181], v[50:51], v[186:187]
	v_mul_f32_e32 v50, v183, v183
	v_fmac_f32_e32 v48, v52, v52
	v_fmac_f32_e32 v49, v54, v54
	v_mul_f32_e32 v51, v181, v181
	v_fmac_f32_e32 v50, v182, v182
	v_add_f32_e32 v48, v48, v49
	v_add_f32_e32 v48, v48, v50
	v_fmac_f32_e32 v51, v180, v180
	v_add_f32_e32 v48, v51, v48
	v_add_f32_e32 v48, v172, v48
	ds_bpermute_b32 v49, v120, v48
	v_cvt_pk_bf16_f32 v50, v52, v53
	v_cvt_pk_bf16_f32 v51, v54, v55
	v_cvt_pk_bf16_f32 v52, v182, v183
	v_cvt_pk_bf16_f32 v53, v180, v181
	s_waitcnt lgkmcnt(0)
	v_add_f32_e32 v48, v48, v49
	ds_bpermute_b32 v49, v114, v48
	global_store_dwordx4 v[74:75], v[50:53], off offset:256
	s_and_saveexec_b64 s[20:21], s[2:3]
	s_cbranch_execz .LBB0_963
	v_lshl_add_u64 v[50:51], v[64:65], 2, s[8:9]
	s_waitcnt lgkmcnt(0)
	v_add_f32_e32 v48, v48, v49
	global_atomic_add_f32 v[50:51], v48, off
.LBB0_963:
	s_or_b64 exec, exec, s[20:21]
	v_add_u32_e32 v48, 0x90, v146
	s_waitcnt lgkmcnt(0)
	v_ashrrev_i32_e32 v49, 31, v48
	v_lshlrev_b64 v[50:51], 11, v[48:49]
	v_readlane_b32 s48, v235, 6
	v_lshl_add_u64 v[58:59], v[50:51], 0, v[144:145]
	v_readlane_b32 s49, v235, 7
	v_readlane_b32 s50, v235, 8
	v_readlane_b32 s51, v235, 9
	v_lshl_add_u64 v[60:61], v[58:59], 2, s[48:49]
	v_lshl_add_u64 v[58:59], v[58:59], 1, s[6:7]
	v_readlane_b32 s52, v235, 10
	v_readlane_b32 s53, v235, 11
	v_readlane_b32 s54, v235, 12
	v_readlane_b32 s55, v235, 13
	v_readlane_b32 s56, v235, 14
	v_readlane_b32 s57, v235, 15
	v_readlane_b32 s58, v235, 16
	v_readlane_b32 s59, v235, 17
	v_readlane_b32 s60, v235, 18
	v_readlane_b32 s61, v235, 19
	v_readlane_b32 s62, v235, 20
	v_readlane_b32 s63, v235, 21
	s_waitcnt vmcnt(20)
	v_pk_add_f32 v[190:191], v[46:47], v[190:191]
	v_pk_add_f32 v[188:189], v[44:45], v[188:189]
	s_waitcnt vmcnt(19)
	v_pk_add_f32 v[194:195], v[42:43], v[194:195]
	v_pk_add_f32 v[192:193], v[40:41], v[192:193]
	v_cvt_pk_bf16_f32 v40, v188, v189
	v_cvt_pk_bf16_f32 v41, v190, v191
	v_cvt_pk_bf16_f32 v42, v192, v193
	v_cvt_pk_bf16_f32 v43, v194, v195
	global_store_dwordx4 v[58:59], v[40:43], off
	s_nop 0
	v_mul_f32_e32 v189, v189, v189
	v_mul_f32_e32 v191, v191, v191
	v_mul_f32_e32 v193, v193, v193
	v_fmac_f32_e32 v189, v188, v188
	v_fmac_f32_e32 v191, v190, v190
	v_mul_f32_e32 v195, v195, v195
	v_fmac_f32_e32 v193, v192, v192
	v_add_f32_e32 v188, v189, v191
	v_fmac_f32_e32 v195, v194, v194
	v_add_f32_e32 v188, v188, v193
	v_add_f32_e32 v188, v195, v188
	s_waitcnt vmcnt(19)
	v_pk_add_f32 v[38:39], v[38:39], v[198:199]
	v_pk_add_f32 v[36:37], v[36:37], v[196:197]
	s_waitcnt vmcnt(18)
	v_pk_add_f32 v[198:199], v[32:33], v[200:201]
	v_mul_f32_e32 v32, v37, v37
	v_mul_f32_e32 v33, v39, v39
	v_pk_add_f32 v[196:197], v[34:35], v[202:203]
	v_mul_f32_e32 v34, v199, v199
	v_fmac_f32_e32 v32, v36, v36
	v_fmac_f32_e32 v33, v38, v38
	v_mul_f32_e32 v35, v197, v197
	v_fmac_f32_e32 v34, v198, v198
	v_add_f32_e32 v32, v32, v33
	v_add_f32_e32 v32, v32, v34
	v_fmac_f32_e32 v35, v196, v196
	v_add_f32_e32 v32, v35, v32
	v_add_f32_e32 v32, v188, v32
	ds_bpermute_b32 v33, v120, v32
	v_cvt_pk_bf16_f32 v34, v36, v37
	v_cvt_pk_bf16_f32 v35, v38, v39
	v_cvt_pk_bf16_f32 v36, v198, v199
	v_cvt_pk_bf16_f32 v37, v196, v197
	s_waitcnt lgkmcnt(0)
	v_add_f32_e32 v32, v32, v33
	ds_bpermute_b32 v33, v114, v32
	global_store_dwordx4 v[58:59], v[34:37], off offset:256
	s_and_saveexec_b64 s[20:21], s[2:3]
	s_cbranch_execz .LBB0_965
	v_lshl_add_u64 v[34:35], v[48:49], 2, s[8:9]
	s_waitcnt lgkmcnt(0)
	v_add_f32_e32 v32, v32, v33
	global_atomic_add_f32 v[34:35], v32, off
.LBB0_965:
	s_or_b64 exec, exec, s[20:21]
	v_add_u32_e32 v32, 0xa0, v146
	s_waitcnt lgkmcnt(0)
	v_ashrrev_i32_e32 v33, 31, v32
	v_lshlrev_b64 v[34:35], 11, v[32:33]
	v_readlane_b32 s48, v235, 6
	v_lshl_add_u64 v[42:43], v[34:35], 0, v[144:145]
	v_readlane_b32 s49, v235, 7
	v_readlane_b32 s50, v235, 8
	v_readlane_b32 s51, v235, 9
	v_lshl_add_u64 v[44:45], v[42:43], 2, s[48:49]
	v_lshl_add_u64 v[42:43], v[42:43], 1, s[6:7]
	v_readlane_b32 s52, v235, 10
	v_readlane_b32 s53, v235, 11
	v_readlane_b32 s54, v235, 12
	v_readlane_b32 s55, v235, 13
	v_readlane_b32 s56, v235, 14
	v_readlane_b32 s57, v235, 15
	v_readlane_b32 s58, v235, 16
	v_readlane_b32 s59, v235, 17
	v_readlane_b32 s60, v235, 18
	v_readlane_b32 s61, v235, 19
	v_readlane_b32 s62, v235, 20
	v_readlane_b32 s63, v235, 21
	s_waitcnt vmcnt(16)
	v_pk_add_f32 v[206:207], v[30:31], v[206:207]
	v_pk_add_f32 v[204:205], v[28:29], v[204:205]
	s_waitcnt vmcnt(15)
	v_pk_add_f32 v[210:211], v[26:27], v[210:211]
	v_pk_add_f32 v[208:209], v[24:25], v[208:209]
	v_cvt_pk_bf16_f32 v24, v204, v205
	v_cvt_pk_bf16_f32 v25, v206, v207
	v_cvt_pk_bf16_f32 v26, v208, v209
	v_cvt_pk_bf16_f32 v27, v210, v211
	global_store_dwordx4 v[42:43], v[24:27], off
	s_nop 0
	v_mul_f32_e32 v205, v205, v205
	v_mul_f32_e32 v207, v207, v207
	v_mul_f32_e32 v209, v209, v209
	v_fmac_f32_e32 v205, v204, v204
	v_fmac_f32_e32 v207, v206, v206
	v_mul_f32_e32 v211, v211, v211
	v_fmac_f32_e32 v209, v208, v208
	v_add_f32_e32 v204, v205, v207
	v_fmac_f32_e32 v211, v210, v210
	v_add_f32_e32 v204, v204, v209
	v_add_f32_e32 v204, v211, v204
	s_waitcnt vmcnt(15)
	v_pk_add_f32 v[22:23], v[22:23], v[214:215]
	v_pk_add_f32 v[20:21], v[20:21], v[212:213]
	s_waitcnt vmcnt(14)
	v_pk_add_f32 v[214:215], v[16:17], v[216:217]
	v_mul_f32_e32 v16, v21, v21
	v_mul_f32_e32 v17, v23, v23
	v_pk_add_f32 v[212:213], v[18:19], v[218:219]
	v_mul_f32_e32 v18, v215, v215
	v_fmac_f32_e32 v16, v20, v20
	v_fmac_f32_e32 v17, v22, v22
	v_mul_f32_e32 v19, v213, v213
	v_fmac_f32_e32 v18, v214, v214
	v_add_f32_e32 v16, v16, v17
	v_add_f32_e32 v16, v16, v18
	v_fmac_f32_e32 v19, v212, v212
	v_add_f32_e32 v16, v19, v16
	v_add_f32_e32 v16, v204, v16
	ds_bpermute_b32 v17, v120, v16
	v_cvt_pk_bf16_f32 v18, v20, v21
	v_cvt_pk_bf16_f32 v19, v22, v23
	v_cvt_pk_bf16_f32 v20, v214, v215
	v_cvt_pk_bf16_f32 v21, v212, v213
	s_waitcnt lgkmcnt(0)
	v_add_f32_e32 v16, v16, v17
	ds_bpermute_b32 v17, v114, v16
	global_store_dwordx4 v[42:43], v[18:21], off offset:256
	s_and_saveexec_b64 s[20:21], s[2:3]
	s_cbranch_execz .LBB0_967
	v_lshl_add_u64 v[18:19], v[32:33], 2, s[8:9]
	s_waitcnt lgkmcnt(0)
	v_add_f32_e32 v16, v16, v17
	global_atomic_add_f32 v[18:19], v16, off
.LBB0_967:
	s_or_b64 exec, exec, s[20:21]
	v_add_u32_e32 v16, 0xb0, v146
	s_waitcnt lgkmcnt(0)
	v_ashrrev_i32_e32 v17, 31, v16
	v_lshlrev_b64 v[18:19], 11, v[16:17]
	v_readlane_b32 s48, v235, 6
	v_lshl_add_u64 v[26:27], v[18:19], 0, v[144:145]
	v_readlane_b32 s49, v235, 7
	v_readlane_b32 s50, v235, 8
	v_readlane_b32 s51, v235, 9
	v_lshl_add_u64 v[28:29], v[26:27], 2, s[48:49]
	v_lshl_add_u64 v[26:27], v[26:27], 1, s[6:7]
	v_readlane_b32 s52, v235, 10
	v_readlane_b32 s53, v235, 11
	v_readlane_b32 s54, v235, 12
	v_readlane_b32 s55, v235, 13
	v_readlane_b32 s56, v235, 14
	v_readlane_b32 s57, v235, 15
	v_readlane_b32 s58, v235, 16
	v_readlane_b32 s59, v235, 17
	v_readlane_b32 s60, v235, 18
	v_readlane_b32 s61, v235, 19
	v_readlane_b32 s62, v235, 20
	v_readlane_b32 s63, v235, 21
	s_waitcnt vmcnt(12)
	v_pk_add_f32 v[222:223], v[14:15], v[222:223]
	v_pk_add_f32 v[220:221], v[12:13], v[220:221]
	s_waitcnt vmcnt(11)
	v_pk_add_f32 v[238:239], v[10:11], v[238:239]
	v_pk_add_f32 v[236:237], v[8:9], v[236:237]
	v_cvt_pk_bf16_f32 v8, v220, v221
	v_cvt_pk_bf16_f32 v9, v222, v223
	v_cvt_pk_bf16_f32 v10, v236, v237
	v_cvt_pk_bf16_f32 v11, v238, v239
	global_store_dwordx4 v[26:27], v[8:11], off
	s_nop 0
	v_mul_f32_e32 v221, v221, v221
	v_mul_f32_e32 v223, v223, v223
	v_mul_f32_e32 v237, v237, v237
	v_fmac_f32_e32 v221, v220, v220
	v_fmac_f32_e32 v223, v222, v222
	v_mul_f32_e32 v239, v239, v239
	v_fmac_f32_e32 v237, v236, v236
	v_add_f32_e32 v220, v221, v223
	v_fmac_f32_e32 v239, v238, v238
	v_add_f32_e32 v220, v220, v237
	v_add_f32_e32 v220, v239, v220
	s_waitcnt vmcnt(11)
	v_pk_add_f32 v[6:7], v[6:7], v[242:243]
	v_pk_add_f32 v[4:5], v[4:5], v[240:241]
	s_waitcnt vmcnt(10)
	v_pk_add_f32 v[242:243], v[0:1], v[244:245]
	v_mul_f32_e32 v0, v5, v5
	v_mul_f32_e32 v1, v7, v7
	v_pk_add_f32 v[240:241], v[2:3], v[246:247]
	v_mul_f32_e32 v2, v243, v243
	v_fmac_f32_e32 v0, v4, v4
	v_fmac_f32_e32 v1, v6, v6
	v_mul_f32_e32 v3, v241, v241
	v_fmac_f32_e32 v2, v242, v242
	v_add_f32_e32 v0, v0, v1
	v_add_f32_e32 v0, v0, v2
	v_fmac_f32_e32 v3, v240, v240
	v_add_f32_e32 v0, v3, v0
	v_add_f32_e32 v0, v220, v0
	ds_bpermute_b32 v1, v120, v0
	v_cvt_pk_bf16_f32 v2, v4, v5
	v_cvt_pk_bf16_f32 v3, v6, v7
	v_cvt_pk_bf16_f32 v4, v242, v243
	v_cvt_pk_bf16_f32 v5, v240, v241
	s_waitcnt lgkmcnt(0)
	v_add_f32_e32 v0, v0, v1
	ds_bpermute_b32 v1, v114, v0
	global_store_dwordx4 v[26:27], v[2:5], off offset:256
	s_and_saveexec_b64 s[20:21], s[2:3]
	s_cbranch_execz .LBB0_944
	v_lshl_add_u64 v[2:3], v[16:17], 2, s[8:9]
	s_waitcnt lgkmcnt(0)
	v_add_f32_e32 v0, v0, v1
	global_atomic_add_f32 v[2:3], v0, off
	s_branch .LBB0_944

.LBB0_1039:
	ds_read_b128 v[144:147], v151
	ds_read_b128 v[156:159], v151 offset:1024
	ds_read_b128 v[160:163], v151 offset:2048
	ds_read_b128 v[164:167], v151 offset:3072
	s_add_u32 s30, s0, 0xfff80080
	s_addc_u32 s31, s1, -1
	s_cmp_eq_u32 s60, 28
	s_cselect_b32 s35, s23, s31
	s_cselect_b32 s34, s56, s30
	s_cselect_b32 s31, s21, s59
	s_cselect_b32 s30, s57, s58
	v_lshl_add_u64 v[168:169], s[0:1], 0, v[136:137]
	s_add_i32 m0, s29, 0xc000
	ds_read_b128 v[172:175], v152
	ds_read_b128 v[176:179], v152 offset:1024
	ds_read_b128 v[180:183], v152 offset:2048
	ds_read_b128 v[184:187], v152 offset:3072
	ds_read_b128 v[188:191], v152 offset:4096
	ds_read_b128 v[192:195], v152 offset:5120
	ds_read_b128 v[196:199], v152 offset:6144
	ds_read_b128 v[200:203], v152 offset:7168
	global_load_lds_dwordx4 v[168:169], off
	v_lshl_add_u64 v[168:169], s[0:1], 0, v[138:139]
	s_add_i32 m0, s29, 0xe000
	s_nop 0
	global_load_lds_dwordx4 v[168:169], off
	s_waitcnt lgkmcnt(8)
	s_barrier
	s_waitcnt lgkmcnt(0)
	s_setprio 1
	s_waitcnt lgkmcnt(0)
	v_mfma_f32_16x16x32_bf16 v[124:127], v[144:147], v[172:175], v[124:127]
	v_mfma_f32_16x16x32_bf16 v[120:123], v[160:163], v[172:175], v[120:123]
	v_mfma_f32_16x16x32_bf16 v[108:111], v[144:147], v[180:183], v[108:111]
	v_mfma_f32_16x16x32_bf16 v[104:107], v[160:163], v[180:183], v[104:107]
	v_mfma_f32_16x16x32_bf16 v[92:95], v[144:147], v[188:191], v[92:95]
	v_mfma_f32_16x16x32_bf16 v[88:91], v[160:163], v[188:191], v[88:91]
	v_mfma_f32_16x16x32_bf16 v[76:79], v[144:147], v[196:199], v[76:79]
	v_mfma_f32_16x16x32_bf16 v[72:75], v[160:163], v[196:199], v[72:75]
	v_mfma_f32_16x16x32_bf16 v[124:127], v[156:159], v[176:179], v[124:127]
	v_mfma_f32_16x16x32_bf16 v[120:123], v[164:167], v[176:179], v[120:123]
	v_mfma_f32_16x16x32_bf16 v[108:111], v[156:159], v[184:187], v[108:111]
	v_mfma_f32_16x16x32_bf16 v[104:107], v[164:167], v[184:187], v[104:107]
	v_mfma_f32_16x16x32_bf16 v[92:95], v[156:159], v[192:195], v[92:95]
	v_mfma_f32_16x16x32_bf16 v[88:91], v[164:167], v[192:195], v[88:91]
	v_mfma_f32_16x16x32_bf16 v[76:79], v[156:159], v[200:203], v[76:79]
	v_mfma_f32_16x16x32_bf16 v[72:75], v[164:167], v[200:203], v[72:75]
	s_setprio 0
	s_barrier
	s_add_i32 s61, s48, s38
	v_lshl_add_u64 v[168:169], s[30:31], 0, v[130:131]
	s_mov_b32 m0, s61
	ds_read_b128 v[204:207], v153
	ds_read_b128 v[208:211], v153 offset:1024
	ds_read_b128 v[212:215], v153 offset:2048
	ds_read_b128 v[216:219], v153 offset:3072
	global_load_lds_dwordx4 v[168:169], off
	v_lshl_add_u64 v[220:221], s[30:31], 0, v[134:135]
	s_add_i32 m0, s61, 0x2000
	s_nop 0
	global_load_lds_dwordx4 v[220:221], off
	s_barrier
	s_waitcnt lgkmcnt(0)
	s_setprio 1
	s_waitcnt lgkmcnt(0)
	v_mfma_f32_16x16x32_bf16 v[116:119], v[204:207], v[172:175], v[116:119]
	v_mfma_f32_16x16x32_bf16 v[112:115], v[212:215], v[172:175], v[112:115]
	v_mfma_f32_16x16x32_bf16 v[100:103], v[204:207], v[180:183], v[100:103]
	v_mfma_f32_16x16x32_bf16 v[96:99], v[212:215], v[180:183], v[96:99]
	v_mfma_f32_16x16x32_bf16 v[84:87], v[204:207], v[188:191], v[84:87]
	v_mfma_f32_16x16x32_bf16 v[80:83], v[212:215], v[188:191], v[80:83]
	v_mfma_f32_16x16x32_bf16 v[68:71], v[204:207], v[196:199], v[68:71]
	v_mfma_f32_16x16x32_bf16 v[64:67], v[212:215], v[196:199], v[64:67]
	v_mfma_f32_16x16x32_bf16 v[116:119], v[208:211], v[176:179], v[116:119]
	v_mfma_f32_16x16x32_bf16 v[112:115], v[216:219], v[176:179], v[112:115]
	v_mfma_f32_16x16x32_bf16 v[100:103], v[208:211], v[184:187], v[100:103]
	v_mfma_f32_16x16x32_bf16 v[96:99], v[216:219], v[184:187], v[96:99]
	v_mfma_f32_16x16x32_bf16 v[84:87], v[208:211], v[192:195], v[84:87]
	v_mfma_f32_16x16x32_bf16 v[80:83], v[216:219], v[192:195], v[80:83]
	v_mfma_f32_16x16x32_bf16 v[68:71], v[208:211], v[200:203], v[68:71]
	v_mfma_f32_16x16x32_bf16 v[64:67], v[216:219], v[200:203], v[64:67]
	s_setprio 0
	s_mov_b32 m0, s29
	v_lshl_add_u64 v[222:223], s[34:35], 0, v[128:129]
	s_barrier
	ds_read_b128 v[172:175], v152 offset:16384
	ds_read_b128 v[176:179], v152 offset:17408
	ds_read_b128 v[180:183], v152 offset:18432
	ds_read_b128 v[184:187], v152 offset:19456
	ds_read_b128 v[188:191], v152 offset:20480
	ds_read_b128 v[192:195], v152 offset:21504
	ds_read_b128 v[196:199], v152 offset:22528
	ds_read_b128 v[200:203], v152 offset:23552
	global_load_lds_dwordx4 v[222:223], off
	v_lshl_add_u64 v[224:225], s[34:35], 0, v[132:133]
	s_mov_b32 m0, s40
	s_nop 0
	global_load_lds_dwordx4 v[224:225], off
	s_barrier
	s_waitcnt lgkmcnt(0)
	s_setprio 1
	s_waitcnt lgkmcnt(0)
	v_mfma_f32_16x16x32_bf16 v[60:63], v[144:147], v[172:175], v[60:63]
	v_mfma_f32_16x16x32_bf16 v[56:59], v[160:163], v[172:175], v[56:59]
	v_mfma_f32_16x16x32_bf16 v[44:47], v[144:147], v[180:183], v[44:47]
	v_mfma_f32_16x16x32_bf16 v[40:43], v[160:163], v[180:183], v[40:43]
	v_mfma_f32_16x16x32_bf16 v[28:31], v[144:147], v[188:191], v[28:31]
	v_mfma_f32_16x16x32_bf16 v[24:27], v[160:163], v[188:191], v[24:27]
	v_mfma_f32_16x16x32_bf16 v[12:15], v[144:147], v[196:199], v[12:15]
	v_mfma_f32_16x16x32_bf16 v[8:11], v[160:163], v[196:199], v[8:11]
	v_mfma_f32_16x16x32_bf16 v[60:63], v[156:159], v[176:179], v[60:63]
	v_mfma_f32_16x16x32_bf16 v[56:59], v[164:167], v[176:179], v[56:59]
	v_mfma_f32_16x16x32_bf16 v[44:47], v[156:159], v[184:187], v[44:47]
	v_mfma_f32_16x16x32_bf16 v[40:43], v[164:167], v[184:187], v[40:43]
	v_mfma_f32_16x16x32_bf16 v[28:31], v[156:159], v[192:195], v[28:31]
	v_mfma_f32_16x16x32_bf16 v[24:27], v[164:167], v[192:195], v[24:27]
	v_mfma_f32_16x16x32_bf16 v[12:15], v[156:159], v[200:203], v[12:15]
	v_mfma_f32_16x16x32_bf16 v[8:11], v[164:167], v[200:203], v[8:11]
	s_setprio 0
	s_barrier
	s_add_u32 s62, s30, 0x80000
	s_addc_u32 s63, s31, 0
	s_add_i32 s61, s49, s38
	v_lshl_add_u64 v[144:145], s[62:63], 0, v[130:131]
	s_mov_b32 m0, s61
	s_nop 0
	global_load_lds_dwordx4 v[144:145], off
	v_lshl_add_u64 v[144:145], s[62:63], 0, v[134:135]
	s_add_i32 m0, s61, 0x2000
	s_nop 0
	global_load_lds_dwordx4 v[144:145], off
	s_waitcnt vmcnt(6)
	s_barrier
	s_setprio 1
	v_mfma_f32_16x16x32_bf16 v[52:55], v[204:207], v[172:175], v[52:55]
	v_mfma_f32_16x16x32_bf16 v[48:51], v[212:215], v[172:175], v[48:51]
	v_mfma_f32_16x16x32_bf16 v[36:39], v[204:207], v[180:183], v[36:39]
	v_mfma_f32_16x16x32_bf16 v[32:35], v[212:215], v[180:183], v[32:35]
	v_mfma_f32_16x16x32_bf16 v[20:23], v[204:207], v[188:191], v[20:23]
	v_mfma_f32_16x16x32_bf16 v[16:19], v[212:215], v[188:191], v[16:19]
	v_mfma_f32_16x16x32_bf16 v[4:7], v[204:207], v[196:199], v[4:7]
	v_mfma_f32_16x16x32_bf16 v[0:3], v[212:215], v[196:199], v[0:3]
	v_mfma_f32_16x16x32_bf16 v[52:55], v[208:211], v[176:179], v[52:55]
	v_mfma_f32_16x16x32_bf16 v[48:51], v[216:219], v[176:179], v[48:51]
	v_mfma_f32_16x16x32_bf16 v[36:39], v[208:211], v[184:187], v[36:39]
	v_mfma_f32_16x16x32_bf16 v[32:35], v[216:219], v[184:187], v[32:35]
	v_mfma_f32_16x16x32_bf16 v[20:23], v[208:211], v[192:195], v[20:23]
	v_mfma_f32_16x16x32_bf16 v[16:19], v[216:219], v[192:195], v[16:19]
	v_mfma_f32_16x16x32_bf16 v[4:7], v[208:211], v[200:203], v[4:7]
	v_mfma_f32_16x16x32_bf16 v[0:3], v[216:219], v[200:203], v[0:3]
	s_setprio 0
	s_add_i32 s61, 0, 0x18000
	v_add_u32_e32 v155, s61, v149
	s_barrier
	ds_read_b128 v[144:147], v155
	ds_read_b128 v[156:159], v155 offset:1024
	ds_read_b128 v[160:163], v155 offset:2048
	ds_read_b128 v[164:167], v155 offset:3072
	s_add_u32 s34, s34, 0x80000
	s_addc_u32 s35, s35, 0
	s_mov_b32 m0, s41
	v_lshl_add_u64 v[204:205], s[34:35], 0, v[128:129]
	ds_read_b128 v[172:175], v152 offset:32768
	ds_read_b128 v[176:179], v152 offset:33792
	ds_read_b128 v[180:183], v152 offset:34816
	ds_read_b128 v[184:187], v152 offset:35840
	ds_read_b128 v[188:191], v152 offset:36864
	ds_read_b128 v[192:195], v152 offset:37888
	ds_read_b128 v[196:199], v152 offset:38912
	ds_read_b128 v[200:203], v152 offset:39936
	global_load_lds_dwordx4 v[204:205], off
	v_lshl_add_u64 v[204:205], s[34:35], 0, v[132:133]
	s_mov_b32 m0, s42
	s_nop 0
	global_load_lds_dwordx4 v[204:205], off
	s_waitcnt lgkmcnt(8)
	s_barrier
	s_waitcnt lgkmcnt(0)
	s_setprio 1
	s_waitcnt lgkmcnt(0)
	v_mfma_f32_16x16x32_bf16 v[124:127], v[144:147], v[172:175], v[124:127]
	v_mfma_f32_16x16x32_bf16 v[120:123], v[160:163], v[172:175], v[120:123]
	v_mfma_f32_16x16x32_bf16 v[108:111], v[144:147], v[180:183], v[108:111]
	v_mfma_f32_16x16x32_bf16 v[104:107], v[160:163], v[180:183], v[104:107]
	v_mfma_f32_16x16x32_bf16 v[92:95], v[144:147], v[188:191], v[92:95]
	v_mfma_f32_16x16x32_bf16 v[88:91], v[160:163], v[188:191], v[88:91]
	v_mfma_f32_16x16x32_bf16 v[76:79], v[144:147], v[196:199], v[76:79]
	v_mfma_f32_16x16x32_bf16 v[72:75], v[160:163], v[196:199], v[72:75]
	v_mfma_f32_16x16x32_bf16 v[124:127], v[156:159], v[176:179], v[124:127]
	v_mfma_f32_16x16x32_bf16 v[120:123], v[164:167], v[176:179], v[120:123]
	v_mfma_f32_16x16x32_bf16 v[108:111], v[156:159], v[184:187], v[108:111]
	v_mfma_f32_16x16x32_bf16 v[104:107], v[164:167], v[184:187], v[104:107]
	v_mfma_f32_16x16x32_bf16 v[92:95], v[156:159], v[192:195], v[92:95]
	v_mfma_f32_16x16x32_bf16 v[88:91], v[164:167], v[192:195], v[88:91]
	v_mfma_f32_16x16x32_bf16 v[76:79], v[156:159], v[200:203], v[76:79]
	v_mfma_f32_16x16x32_bf16 v[72:75], v[164:167], v[200:203], v[72:75]
	s_setprio 0
	s_barrier
	s_add_i32 s34, 0, 0x1c000
	s_add_i32 s35, s61, s38
	v_add_u32_e32 v155, s34, v149
	v_lshl_add_u64 v[168:169], v[168:169], 0, s[12:13]
	s_mov_b32 m0, s35
	ds_read_b128 v[204:207], v155
	ds_read_b128 v[208:211], v155 offset:1024
	ds_read_b128 v[212:215], v155 offset:2048
	ds_read_b128 v[216:219], v155 offset:3072
	global_load_lds_dwordx4 v[168:169], off
	v_lshl_add_u64 v[168:169], v[220:221], 0, s[12:13]
	s_add_i32 m0, s35, 0x2000
	s_nop 0
	global_load_lds_dwordx4 v[168:169], off
	s_barrier
	s_waitcnt lgkmcnt(0)
	s_setprio 1
	s_waitcnt lgkmcnt(0)
	v_mfma_f32_16x16x32_bf16 v[116:119], v[204:207], v[172:175], v[116:119]
	v_mfma_f32_16x16x32_bf16 v[112:115], v[212:215], v[172:175], v[112:115]
	v_mfma_f32_16x16x32_bf16 v[100:103], v[204:207], v[180:183], v[100:103]
	v_mfma_f32_16x16x32_bf16 v[96:99], v[212:215], v[180:183], v[96:99]
	v_mfma_f32_16x16x32_bf16 v[84:87], v[204:207], v[188:191], v[84:87]
	v_mfma_f32_16x16x32_bf16 v[80:83], v[212:215], v[188:191], v[80:83]
	v_mfma_f32_16x16x32_bf16 v[68:71], v[204:207], v[196:199], v[68:71]
	v_mfma_f32_16x16x32_bf16 v[64:67], v[212:215], v[196:199], v[64:67]
	v_mfma_f32_16x16x32_bf16 v[116:119], v[208:211], v[176:179], v[116:119]
	v_mfma_f32_16x16x32_bf16 v[112:115], v[216:219], v[176:179], v[112:115]
	v_mfma_f32_16x16x32_bf16 v[100:103], v[208:211], v[184:187], v[100:103]
	v_mfma_f32_16x16x32_bf16 v[96:99], v[216:219], v[184:187], v[96:99]
	v_mfma_f32_16x16x32_bf16 v[84:87], v[208:211], v[192:195], v[84:87]
	v_mfma_f32_16x16x32_bf16 v[80:83], v[216:219], v[192:195], v[80:83]
	v_mfma_f32_16x16x32_bf16 v[68:71], v[208:211], v[200:203], v[68:71]
	v_mfma_f32_16x16x32_bf16 v[64:67], v[216:219], v[200:203], v[64:67]
	s_setprio 0
	s_mov_b32 m0, s45
	v_lshl_add_u64 v[168:169], v[222:223], 0, s[12:13]
	s_barrier
	ds_read_b128 v[172:175], v152 offset:49152
	ds_read_b128 v[176:179], v152 offset:50176
	ds_read_b128 v[180:183], v152 offset:51200
	ds_read_b128 v[184:187], v152 offset:52224
	ds_read_b128 v[188:191], v152 offset:53248
	ds_read_b128 v[192:195], v152 offset:54272
	ds_read_b128 v[196:199], v152 offset:55296
	ds_read_b128 v[200:203], v152 offset:56320
	global_load_lds_dwordx4 v[168:169], off
	v_lshl_add_u64 v[168:169], v[224:225], 0, s[12:13]
	s_mov_b32 m0, s46
	s_nop 0
	global_load_lds_dwordx4 v[168:169], off
	s_barrier
	s_waitcnt lgkmcnt(0)
	s_setprio 1
	s_waitcnt lgkmcnt(0)
	v_mfma_f32_16x16x32_bf16 v[60:63], v[144:147], v[172:175], v[60:63]
	v_mfma_f32_16x16x32_bf16 v[56:59], v[160:163], v[172:175], v[56:59]
	v_mfma_f32_16x16x32_bf16 v[44:47], v[144:147], v[180:183], v[44:47]
	v_mfma_f32_16x16x32_bf16 v[40:43], v[160:163], v[180:183], v[40:43]
	v_mfma_f32_16x16x32_bf16 v[28:31], v[144:147], v[188:191], v[28:31]
	v_mfma_f32_16x16x32_bf16 v[24:27], v[160:163], v[188:191], v[24:27]
	v_mfma_f32_16x16x32_bf16 v[12:15], v[144:147], v[196:199], v[12:15]
	v_mfma_f32_16x16x32_bf16 v[8:11], v[160:163], v[196:199], v[8:11]
	v_mfma_f32_16x16x32_bf16 v[60:63], v[156:159], v[176:179], v[60:63]
	v_mfma_f32_16x16x32_bf16 v[56:59], v[164:167], v[176:179], v[56:59]
	v_mfma_f32_16x16x32_bf16 v[44:47], v[156:159], v[184:187], v[44:47]
	v_mfma_f32_16x16x32_bf16 v[40:43], v[164:167], v[184:187], v[40:43]
	v_mfma_f32_16x16x32_bf16 v[28:31], v[156:159], v[192:195], v[28:31]
	v_mfma_f32_16x16x32_bf16 v[24:27], v[164:167], v[192:195], v[24:27]
	v_mfma_f32_16x16x32_bf16 v[12:15], v[156:159], v[200:203], v[12:15]
	v_mfma_f32_16x16x32_bf16 v[8:11], v[164:167], v[200:203], v[8:11]
	s_setprio 0
	s_barrier
	s_add_u32 s30, s30, 0x80080
	s_addc_u32 s31, s31, 0
	s_add_i32 s34, s34, s38
	v_lshl_add_u64 v[144:145], s[30:31], 0, v[130:131]
	s_mov_b32 m0, s34
	s_nop 0
	global_load_lds_dwordx4 v[144:145], off
	v_lshl_add_u64 v[144:145], s[30:31], 0, v[134:135]
	s_add_i32 m0, s34, 0x2000
	s_nop 0
	global_load_lds_dwordx4 v[144:145], off
	s_waitcnt vmcnt(6)
	s_barrier
	s_setprio 1
	v_mfma_f32_16x16x32_bf16 v[52:55], v[204:207], v[172:175], v[52:55]
	v_mfma_f32_16x16x32_bf16 v[48:51], v[212:215], v[172:175], v[48:51]
	v_mfma_f32_16x16x32_bf16 v[36:39], v[204:207], v[180:183], v[36:39]
	v_mfma_f32_16x16x32_bf16 v[32:35], v[212:215], v[180:183], v[32:35]
	v_mfma_f32_16x16x32_bf16 v[20:23], v[204:207], v[188:191], v[20:23]
	v_mfma_f32_16x16x32_bf16 v[16:19], v[212:215], v[188:191], v[16:19]
	v_mfma_f32_16x16x32_bf16 v[4:7], v[204:207], v[196:199], v[4:7]
	v_mfma_f32_16x16x32_bf16 v[0:3], v[212:215], v[196:199], v[0:3]
	v_mfma_f32_16x16x32_bf16 v[52:55], v[208:211], v[176:179], v[52:55]
	v_mfma_f32_16x16x32_bf16 v[48:51], v[216:219], v[176:179], v[48:51]
	v_mfma_f32_16x16x32_bf16 v[36:39], v[208:211], v[184:187], v[36:39]
	v_mfma_f32_16x16x32_bf16 v[32:35], v[216:219], v[184:187], v[32:35]
	v_mfma_f32_16x16x32_bf16 v[20:23], v[208:211], v[192:195], v[20:23]
	v_mfma_f32_16x16x32_bf16 v[16:19], v[216:219], v[192:195], v[16:19]
	v_mfma_f32_16x16x32_bf16 v[4:7], v[208:211], v[200:203], v[4:7]
	v_mfma_f32_16x16x32_bf16 v[0:3], v[216:219], v[200:203], v[0:3]
	s_setprio 0
	s_add_i32 s60, s60, 2
	s_add_u32 s0, s0, 0x100
	s_addc_u32 s1, s1, 0
	s_add_u32 s58, s58, 0x100
	s_addc_u32 s59, s59, 0
	s_cmp_gt_u32 s60, 29
	s_barrier
	s_cbranch_scc0 .LBB0_1039
	v_lshl_add_u32 v156, s28, 8, v148
	v_ashrrev_i32_e32 v157, 31, v156
	v_lshl_add_u64 v[144:145], v[156:157], 2, s[8:9]
	global_load_dword v236, v[144:145], off
	global_load_dword v237, v[144:145], off offset:64
	global_load_dword v238, v[144:145], off offset:128
	global_load_dword v239, v[144:145], off offset:192
	global_load_dword v240, v[144:145], off offset:512
	global_load_dword v241, v[144:145], off offset:576
	global_load_dword v242, v[144:145], off offset:640
	global_load_dword v243, v[144:145], off offset:704
	v_lshl_or_b32 v146, s55, 8, v150
	v_ashrrev_i32_e32 v147, 31, v146
	v_lshlrev_b64 v[162:163], 1, v[146:147]
	v_lshlrev_b64 v[160:161], 12, v[156:157]
	v_readlane_b32 s0, v234, 9
	v_readlane_b32 s1, v234, 10
	v_or_b32_e32 v158, 16, v156
	v_ashrrev_i32_e32 v159, 31, v158
	s_mov_b32 s55, s20
	s_mov_b32 s28, s22
	s_mov_b64 s[30:31], s[26:27]
	s_mov_b64 s[34:35], s[24:25]
	s_waitcnt vmcnt(7)
	v_fmamk_f32 v146, v236, 0x3a000000, v154
	v_mul_f32_e32 v147, 0x4b800000, v146
	v_cmp_gt_f32_e32 vcc, s50, v146
	s_nop 1
	v_cndmask_b32_e32 v146, v146, v147, vcc
	v_rsq_f32_e32 v155, v146
	v_lshl_add_u64 v[146:147], s[0:1], 0, v[160:161]
	v_lshl_add_u64 v[146:147], v[146:147], 0, v[162:163]
	v_lshl_add_u64 v[160:161], v[158:159], 2, s[8:9]
	v_mul_f32_e32 v157, 0x45800000, v155
	v_cndmask_b32_e32 v164, v155, v157, vcc
	v_pk_mul_f32 v[126:127], v[126:127], v[164:165] op_sel_hi:[1,0]
	v_pk_mul_f32 v[124:125], v[124:125], v[164:165] op_sel_hi:[1,0]
	v_pk_mul_f32 v[122:123], v[122:123], v[164:165] op_sel_hi:[1,0]
	v_pk_mul_f32 v[120:121], v[120:121], v[164:165] op_sel_hi:[1,0]
	v_pk_mul_f32 v[118:119], v[118:119], v[164:165] op_sel_hi:[1,0]
	v_pk_mul_f32 v[116:117], v[116:117], v[164:165] op_sel_hi:[1,0]
	v_pk_mul_f32 v[166:167], v[114:115], v[164:165] op_sel_hi:[1,0]
	v_pk_mul_f32 v[164:165], v[112:113], v[164:165] op_sel_hi:[1,0]
	v_cvt_pk_bf16_f32 v112, v124, v125
	v_cvt_pk_bf16_f32 v113, v126, v127
	v_cvt_pk_bf16_f32 v114, v120, v121
	v_cvt_pk_bf16_f32 v115, v122, v123
	v_cvt_pk_bf16_f32 v116, v116, v117
	v_cvt_pk_bf16_f32 v117, v118, v119
	v_cvt_pk_bf16_f32 v118, v164, v165
	v_cvt_pk_bf16_f32 v119, v166, v167
	global_store_dwordx4 v[146:147], v[112:115], off
	global_store_dwordx4 v[146:147], v[116:119], off offset:256
	v_lshlrev_b64 v[114:115], 12, v[158:159]
	v_or_b32_e32 v112, 32, v156
	v_lshl_add_u64 v[114:115], s[0:1], 0, v[114:115]
	v_ashrrev_i32_e32 v113, 31, v112
	v_lshl_add_u64 v[114:115], v[114:115], 0, v[162:163]
	s_waitcnt vmcnt(8)
	v_fmamk_f32 v116, v237, 0x3a000000, v154
	v_mul_f32_e32 v117, 0x4b800000, v116
	v_cmp_gt_f32_e32 vcc, s50, v116
	s_nop 1
	v_cndmask_b32_e32 v116, v116, v117, vcc
	v_rsq_f32_e32 v118, v116
	v_lshl_add_u64 v[116:117], v[112:113], 2, s[8:9]
	v_mul_f32_e32 v119, 0x45800000, v118
	v_cndmask_b32_e32 v118, v118, v119, vcc
	v_pk_mul_f32 v[110:111], v[110:111], v[118:119] op_sel_hi:[1,0]
	v_pk_mul_f32 v[108:109], v[108:109], v[118:119] op_sel_hi:[1,0]
	v_pk_mul_f32 v[106:107], v[106:107], v[118:119] op_sel_hi:[1,0]
	v_pk_mul_f32 v[104:105], v[104:105], v[118:119] op_sel_hi:[1,0]
	v_pk_mul_f32 v[102:103], v[102:103], v[118:119] op_sel_hi:[1,0]
	v_pk_mul_f32 v[100:101], v[100:101], v[118:119] op_sel_hi:[1,0]
	v_pk_mul_f32 v[120:121], v[98:99], v[118:119] op_sel_hi:[1,0]
	v_pk_mul_f32 v[118:119], v[96:97], v[118:119] op_sel_hi:[1,0]
	v_cvt_pk_bf16_f32 v96, v108, v109
	v_cvt_pk_bf16_f32 v97, v110, v111
	v_cvt_pk_bf16_f32 v98, v104, v105
	v_cvt_pk_bf16_f32 v99, v106, v107
	v_cvt_pk_bf16_f32 v100, v100, v101
	v_cvt_pk_bf16_f32 v101, v102, v103
	v_cvt_pk_bf16_f32 v102, v118, v119
	v_cvt_pk_bf16_f32 v103, v120, v121
	global_store_dwordx4 v[114:115], v[96:99], off
	global_store_dwordx4 v[114:115], v[100:103], off offset:256
	v_lshlrev_b64 v[98:99], 12, v[112:113]
	v_or_b32_e32 v96, 48, v156
	v_lshl_add_u64 v[98:99], s[0:1], 0, v[98:99]
	v_ashrrev_i32_e32 v97, 31, v96
	v_lshl_add_u64 v[98:99], v[98:99], 0, v[162:163]
	s_waitcnt vmcnt(9)
	v_fmamk_f32 v100, v238, 0x3a000000, v154
	v_mul_f32_e32 v101, 0x4b800000, v100
	v_cmp_gt_f32_e32 vcc, s50, v100
	s_nop 1
	v_cndmask_b32_e32 v100, v100, v101, vcc
	v_rsq_f32_e32 v102, v100
	v_lshl_add_u64 v[100:101], v[96:97], 2, s[8:9]
	v_mul_f32_e32 v103, 0x45800000, v102
	v_cndmask_b32_e32 v102, v102, v103, vcc
	v_pk_mul_f32 v[94:95], v[94:95], v[102:103] op_sel_hi:[1,0]
	v_pk_mul_f32 v[92:93], v[92:93], v[102:103] op_sel_hi:[1,0]
	v_pk_mul_f32 v[90:91], v[90:91], v[102:103] op_sel_hi:[1,0]
	v_pk_mul_f32 v[88:89], v[88:89], v[102:103] op_sel_hi:[1,0]
	v_pk_mul_f32 v[86:87], v[86:87], v[102:103] op_sel_hi:[1,0]
	v_pk_mul_f32 v[84:85], v[84:85], v[102:103] op_sel_hi:[1,0]
	v_pk_mul_f32 v[104:105], v[82:83], v[102:103] op_sel_hi:[1,0]
	v_pk_mul_f32 v[102:103], v[80:81], v[102:103] op_sel_hi:[1,0]
	v_cvt_pk_bf16_f32 v80, v92, v93
	v_cvt_pk_bf16_f32 v81, v94, v95
	v_cvt_pk_bf16_f32 v82, v88, v89
	v_cvt_pk_bf16_f32 v83, v90, v91
	v_cvt_pk_bf16_f32 v84, v84, v85
	v_cvt_pk_bf16_f32 v85, v86, v87
	v_cvt_pk_bf16_f32 v86, v102, v103
	v_cvt_pk_bf16_f32 v87, v104, v105
	global_store_dwordx4 v[98:99], v[80:83], off
	global_store_dwordx4 v[98:99], v[84:87], off offset:256
	s_waitcnt vmcnt(10)
	v_fmamk_f32 v80, v239, 0x3a000000, v154
	v_mul_f32_e32 v81, 0x4b800000, v80
	v_cmp_gt_f32_e32 vcc, s50, v80
	s_nop 1
	v_cndmask_b32_e32 v80, v80, v81, vcc
	v_rsq_f32_e32 v82, v80
	v_lshlrev_b64 v[80:81], 12, v[96:97]
	v_lshl_add_u64 v[80:81], s[0:1], 0, v[80:81]
	v_lshl_add_u64 v[80:81], v[80:81], 0, v[162:163]
	v_mul_f32_e32 v83, 0x45800000, v82
	v_cndmask_b32_e32 v82, v82, v83, vcc
	v_pk_mul_f32 v[78:79], v[78:79], v[82:83] op_sel_hi:[1,0]
	v_pk_mul_f32 v[76:77], v[76:77], v[82:83] op_sel_hi:[1,0]
	v_pk_mul_f32 v[74:75], v[74:75], v[82:83] op_sel_hi:[1,0]
	v_pk_mul_f32 v[72:73], v[72:73], v[82:83] op_sel_hi:[1,0]
	v_pk_mul_f32 v[70:71], v[70:71], v[82:83] op_sel_hi:[1,0]
	v_pk_mul_f32 v[68:69], v[68:69], v[82:83] op_sel_hi:[1,0]
	v_pk_mul_f32 v[84:85], v[66:67], v[82:83] op_sel_hi:[1,0]
	v_pk_mul_f32 v[82:83], v[64:65], v[82:83] op_sel_hi:[1,0]
	v_cvt_pk_bf16_f32 v64, v76, v77
	v_cvt_pk_bf16_f32 v65, v78, v79
	v_cvt_pk_bf16_f32 v66, v72, v73
	v_cvt_pk_bf16_f32 v67, v74, v75
	v_cvt_pk_bf16_f32 v68, v68, v69
	v_cvt_pk_bf16_f32 v69, v70, v71
	v_cvt_pk_bf16_f32 v70, v82, v83
	v_cvt_pk_bf16_f32 v71, v84, v85
	global_store_dwordx4 v[80:81], v[64:67], off
	global_store_dwordx4 v[80:81], v[68:71], off offset:256
	v_lshl_add_u64 v[64:65], v[146:147], 0, s[10:11]
	s_waitcnt vmcnt(11)
	v_fmamk_f32 v66, v240, 0x3a000000, v154
	v_mul_f32_e32 v67, 0x4b800000, v66
	v_cmp_gt_f32_e32 vcc, s50, v66
	s_nop 1
	v_cndmask_b32_e32 v66, v66, v67, vcc
	v_rsq_f32_e32 v68, v66
	v_add_co_u32_e64 v66, s[0:1], s51, v146
	v_mul_f32_e32 v69, 0x45800000, v68
	v_cndmask_b32_e32 v68, v68, v69, vcc
	v_pk_mul_f32 v[62:63], v[62:63], v[68:69] op_sel_hi:[1,0]
	v_pk_mul_f32 v[60:61], v[60:61], v[68:69] op_sel_hi:[1,0]
	v_pk_mul_f32 v[58:59], v[58:59], v[68:69] op_sel_hi:[1,0]
	v_pk_mul_f32 v[56:57], v[56:57], v[68:69] op_sel_hi:[1,0]
	v_addc_co_u32_e64 v67, s[0:1], 0, v147, s[0:1]
	v_pk_mul_f32 v[54:55], v[54:55], v[68:69] op_sel_hi:[1,0]
	v_pk_mul_f32 v[52:53], v[52:53], v[68:69] op_sel_hi:[1,0]
	v_pk_mul_f32 v[70:71], v[50:51], v[68:69] op_sel_hi:[1,0]
	v_pk_mul_f32 v[68:69], v[48:49], v[68:69] op_sel_hi:[1,0]
	v_cvt_pk_bf16_f32 v48, v60, v61
	v_cvt_pk_bf16_f32 v49, v62, v63
	v_cvt_pk_bf16_f32 v50, v56, v57
	v_cvt_pk_bf16_f32 v51, v58, v59
	v_cvt_pk_bf16_f32 v52, v52, v53
	v_cvt_pk_bf16_f32 v53, v54, v55
	v_cvt_pk_bf16_f32 v54, v68, v69
	v_cvt_pk_bf16_f32 v55, v70, v71
	global_store_dwordx4 v[66:67], v[48:51], off
	global_store_dwordx4 v[64:65], v[52:55], off offset:256
	v_lshl_add_u64 v[48:49], v[146:147], 0, s[14:15]
	s_waitcnt vmcnt(12)
	v_fmamk_f32 v50, v241, 0x3a000000, v154
	v_mul_f32_e32 v51, 0x4b800000, v50
	v_cmp_gt_f32_e32 vcc, s50, v50
	s_nop 1
	v_cndmask_b32_e32 v50, v50, v51, vcc
	v_rsq_f32_e32 v52, v50
	v_add_co_u32_e64 v50, s[0:1], s52, v146
	v_mul_f32_e32 v53, 0x45800000, v52
	v_cndmask_b32_e32 v52, v52, v53, vcc
	v_pk_mul_f32 v[46:47], v[46:47], v[52:53] op_sel_hi:[1,0]
	v_pk_mul_f32 v[44:45], v[44:45], v[52:53] op_sel_hi:[1,0]
	v_pk_mul_f32 v[42:43], v[42:43], v[52:53] op_sel_hi:[1,0]
	v_pk_mul_f32 v[40:41], v[40:41], v[52:53] op_sel_hi:[1,0]
	v_addc_co_u32_e64 v51, s[0:1], 0, v147, s[0:1]
	v_pk_mul_f32 v[38:39], v[38:39], v[52:53] op_sel_hi:[1,0]
	v_pk_mul_f32 v[36:37], v[36:37], v[52:53] op_sel_hi:[1,0]
	v_pk_mul_f32 v[54:55], v[34:35], v[52:53] op_sel_hi:[1,0]
	v_pk_mul_f32 v[52:53], v[32:33], v[52:53] op_sel_hi:[1,0]
	v_cvt_pk_bf16_f32 v32, v44, v45
	v_cvt_pk_bf16_f32 v33, v46, v47
	v_cvt_pk_bf16_f32 v34, v40, v41
	v_cvt_pk_bf16_f32 v35, v42, v43
	v_cvt_pk_bf16_f32 v36, v36, v37
	v_cvt_pk_bf16_f32 v37, v38, v39
	v_cvt_pk_bf16_f32 v38, v52, v53
	v_cvt_pk_bf16_f32 v39, v54, v55
	global_store_dwordx4 v[50:51], v[32:35], off
	global_store_dwordx4 v[48:49], v[36:39], off offset:256
	v_lshl_add_u64 v[32:33], v[146:147], 0, s[16:17]
	s_waitcnt vmcnt(13)
	v_fmamk_f32 v34, v242, 0x3a000000, v154
	v_mul_f32_e32 v35, 0x4b800000, v34
	v_cmp_gt_f32_e32 vcc, s50, v34
	s_nop 1
	v_cndmask_b32_e32 v34, v34, v35, vcc
	v_rsq_f32_e32 v36, v34
	v_add_co_u32_e64 v34, s[0:1], s53, v146
	v_mul_f32_e32 v37, 0x45800000, v36
	v_cndmask_b32_e32 v36, v36, v37, vcc
	v_pk_mul_f32 v[30:31], v[30:31], v[36:37] op_sel_hi:[1,0]
	v_pk_mul_f32 v[28:29], v[28:29], v[36:37] op_sel_hi:[1,0]
	v_pk_mul_f32 v[26:27], v[26:27], v[36:37] op_sel_hi:[1,0]
	v_pk_mul_f32 v[24:25], v[24:25], v[36:37] op_sel_hi:[1,0]
	v_addc_co_u32_e64 v35, s[0:1], 0, v147, s[0:1]
	v_pk_mul_f32 v[22:23], v[22:23], v[36:37] op_sel_hi:[1,0]
	v_pk_mul_f32 v[20:21], v[20:21], v[36:37] op_sel_hi:[1,0]
	v_pk_mul_f32 v[38:39], v[18:19], v[36:37] op_sel_hi:[1,0]
	v_pk_mul_f32 v[36:37], v[16:17], v[36:37] op_sel_hi:[1,0]
	v_cvt_pk_bf16_f32 v16, v28, v29
	v_cvt_pk_bf16_f32 v17, v30, v31
	v_cvt_pk_bf16_f32 v18, v24, v25
	v_cvt_pk_bf16_f32 v19, v26, v27
	v_cvt_pk_bf16_f32 v20, v20, v21
	v_cvt_pk_bf16_f32 v21, v22, v23
	v_cvt_pk_bf16_f32 v22, v36, v37
	v_cvt_pk_bf16_f32 v23, v38, v39
	global_store_dwordx4 v[34:35], v[16:19], off
	global_store_dwordx4 v[32:33], v[20:23], off offset:256
	s_and_b64 vcc, exec, s[2:3]
	v_lshl_add_u64 v[16:17], v[146:147], 0, s[18:19]
	s_waitcnt vmcnt(14)
	v_fmamk_f32 v18, v243, 0x3a000000, v154
	v_mul_f32_e32 v19, 0x4b800000, v18
	v_cmp_gt_f32_e64 s[0:1], s50, v18
	s_nop 1
	v_cndmask_b32_e64 v18, v18, v19, s[0:1]
	v_rsq_f32_e32 v20, v18
	v_add_co_u32_e64 v18, s[2:3], s54, v146
	v_mul_f32_e32 v21, 0x45800000, v20
	v_cndmask_b32_e64 v20, v20, v21, s[0:1]
	v_pk_mul_f32 v[14:15], v[14:15], v[20:21] op_sel_hi:[1,0]
	v_pk_mul_f32 v[12:13], v[12:13], v[20:21] op_sel_hi:[1,0]
	v_pk_mul_f32 v[10:11], v[10:11], v[20:21] op_sel_hi:[1,0]
	v_pk_mul_f32 v[8:9], v[8:9], v[20:21] op_sel_hi:[1,0]
	v_addc_co_u32_e64 v19, s[2:3], 0, v147, s[2:3]
	v_pk_mul_f32 v[6:7], v[6:7], v[20:21] op_sel_hi:[1,0]
	v_pk_mul_f32 v[4:5], v[4:5], v[20:21] op_sel_hi:[1,0]
	v_pk_mul_f32 v[22:23], v[2:3], v[20:21] op_sel_hi:[1,0]
	v_pk_mul_f32 v[20:21], v[0:1], v[20:21] op_sel_hi:[1,0]
	v_cvt_pk_bf16_f32 v0, v12, v13
	v_cvt_pk_bf16_f32 v1, v14, v15
	v_cvt_pk_bf16_f32 v2, v8, v9
	v_cvt_pk_bf16_f32 v3, v10, v11
	v_cvt_pk_bf16_f32 v4, v4, v5
	v_cvt_pk_bf16_f32 v5, v6, v7
	v_cvt_pk_bf16_f32 v6, v20, v21
	v_cvt_pk_bf16_f32 v7, v22, v23
	global_store_dwordx4 v[18:19], v[0:3], off
	global_store_dwordx4 v[16:17], v[4:7], off offset:256
	s_cbranch_vccz .LBB0_1032
	s_waitcnt vmcnt(0)
	s_cmpk_gt_u32 s33, 0xff
	s_cbranch_scc1 .LBB0_1043
	s_barrier

.LBB0_1184:
	ds_read_b128 v[144:147], v151
	ds_read_b128 v[156:159], v151 offset:1024
	ds_read_b128 v[160:163], v151 offset:2048
	ds_read_b128 v[164:167], v151 offset:3072
	s_add_u32 s26, s24, 0xfff80080
	s_addc_u32 s27, s25, -1
	s_cmp_eq_u32 s49, 28
	s_cselect_b32 s29, s15, s27
	s_cselect_b32 s28, s21, s26
	s_cselect_b32 s27, s13, s48
	s_cselect_b32 s26, s46, s47
	v_lshl_add_u64 v[168:169], s[24:25], 0, v[136:137]
	s_add_i32 m0, s23, 0xc000
	ds_read_b128 v[172:175], v152
	ds_read_b128 v[176:179], v152 offset:1024
	ds_read_b128 v[180:183], v152 offset:2048
	ds_read_b128 v[184:187], v152 offset:3072
	ds_read_b128 v[188:191], v152 offset:4096
	ds_read_b128 v[192:195], v152 offset:5120
	ds_read_b128 v[196:199], v152 offset:6144
	ds_read_b128 v[200:203], v152 offset:7168
	global_load_lds_dwordx4 v[168:169], off
	v_lshl_add_u64 v[168:169], s[24:25], 0, v[138:139]
	s_add_i32 m0, s23, 0xe000
	s_nop 0
	global_load_lds_dwordx4 v[168:169], off
	s_waitcnt lgkmcnt(8)
	s_barrier
	s_waitcnt lgkmcnt(0)
	s_setprio 1
	s_waitcnt lgkmcnt(0)
	v_mfma_f32_16x16x32_bf16 v[124:127], v[144:147], v[172:175], v[124:127]
	v_mfma_f32_16x16x32_bf16 v[120:123], v[160:163], v[172:175], v[120:123]
	v_mfma_f32_16x16x32_bf16 v[108:111], v[144:147], v[180:183], v[108:111]
	v_mfma_f32_16x16x32_bf16 v[104:107], v[160:163], v[180:183], v[104:107]
	v_mfma_f32_16x16x32_bf16 v[92:95], v[144:147], v[188:191], v[92:95]
	v_mfma_f32_16x16x32_bf16 v[88:91], v[160:163], v[188:191], v[88:91]
	v_mfma_f32_16x16x32_bf16 v[76:79], v[144:147], v[196:199], v[76:79]
	v_mfma_f32_16x16x32_bf16 v[72:75], v[160:163], v[196:199], v[72:75]
	v_mfma_f32_16x16x32_bf16 v[124:127], v[156:159], v[176:179], v[124:127]
	v_mfma_f32_16x16x32_bf16 v[120:123], v[164:167], v[176:179], v[120:123]
	v_mfma_f32_16x16x32_bf16 v[108:111], v[156:159], v[184:187], v[108:111]
	v_mfma_f32_16x16x32_bf16 v[104:107], v[164:167], v[184:187], v[104:107]
	v_mfma_f32_16x16x32_bf16 v[92:95], v[156:159], v[192:195], v[92:95]
	v_mfma_f32_16x16x32_bf16 v[88:91], v[164:167], v[192:195], v[88:91]
	v_mfma_f32_16x16x32_bf16 v[76:79], v[156:159], v[200:203], v[76:79]
	v_mfma_f32_16x16x32_bf16 v[72:75], v[164:167], v[200:203], v[72:75]
	s_setprio 0
	s_barrier
	s_add_i32 s50, s44, s34
	v_lshl_add_u64 v[168:169], s[26:27], 0, v[130:131]
	s_mov_b32 m0, s50
	ds_read_b128 v[204:207], v153
	ds_read_b128 v[208:211], v153 offset:1024
	ds_read_b128 v[212:215], v153 offset:2048
	ds_read_b128 v[216:219], v153 offset:3072
	global_load_lds_dwordx4 v[168:169], off
	v_lshl_add_u64 v[220:221], s[26:27], 0, v[134:135]
	s_add_i32 m0, s50, 0x2000
	s_nop 0
	global_load_lds_dwordx4 v[220:221], off
	s_barrier
	s_waitcnt lgkmcnt(0)
	s_setprio 1
	s_waitcnt lgkmcnt(0)
	v_mfma_f32_16x16x32_bf16 v[116:119], v[204:207], v[172:175], v[116:119]
	v_mfma_f32_16x16x32_bf16 v[112:115], v[212:215], v[172:175], v[112:115]
	v_mfma_f32_16x16x32_bf16 v[100:103], v[204:207], v[180:183], v[100:103]
	v_mfma_f32_16x16x32_bf16 v[96:99], v[212:215], v[180:183], v[96:99]
	v_mfma_f32_16x16x32_bf16 v[84:87], v[204:207], v[188:191], v[84:87]
	v_mfma_f32_16x16x32_bf16 v[80:83], v[212:215], v[188:191], v[80:83]
	v_mfma_f32_16x16x32_bf16 v[68:71], v[204:207], v[196:199], v[68:71]
	v_mfma_f32_16x16x32_bf16 v[64:67], v[212:215], v[196:199], v[64:67]
	v_mfma_f32_16x16x32_bf16 v[116:119], v[208:211], v[176:179], v[116:119]
	v_mfma_f32_16x16x32_bf16 v[112:115], v[216:219], v[176:179], v[112:115]
	v_mfma_f32_16x16x32_bf16 v[100:103], v[208:211], v[184:187], v[100:103]
	v_mfma_f32_16x16x32_bf16 v[96:99], v[216:219], v[184:187], v[96:99]
	v_mfma_f32_16x16x32_bf16 v[84:87], v[208:211], v[192:195], v[84:87]
	v_mfma_f32_16x16x32_bf16 v[80:83], v[216:219], v[192:195], v[80:83]
	v_mfma_f32_16x16x32_bf16 v[68:71], v[208:211], v[200:203], v[68:71]
	v_mfma_f32_16x16x32_bf16 v[64:67], v[216:219], v[200:203], v[64:67]
	s_setprio 0
	s_mov_b32 m0, s23
	v_lshl_add_u64 v[222:223], s[28:29], 0, v[128:129]
	s_barrier
	ds_read_b128 v[172:175], v152 offset:16384
	ds_read_b128 v[176:179], v152 offset:17408
	ds_read_b128 v[180:183], v152 offset:18432
	ds_read_b128 v[184:187], v152 offset:19456
	ds_read_b128 v[188:191], v152 offset:20480
	ds_read_b128 v[192:195], v152 offset:21504
	ds_read_b128 v[196:199], v152 offset:22528
	ds_read_b128 v[200:203], v152 offset:23552
	global_load_lds_dwordx4 v[222:223], off
	v_lshl_add_u64 v[224:225], s[28:29], 0, v[132:133]
	s_mov_b32 m0, s35
	s_nop 0
	global_load_lds_dwordx4 v[224:225], off
	s_barrier
	s_waitcnt lgkmcnt(0)
	s_setprio 1
	s_waitcnt lgkmcnt(0)
	v_mfma_f32_16x16x32_bf16 v[60:63], v[144:147], v[172:175], v[60:63]
	v_mfma_f32_16x16x32_bf16 v[56:59], v[160:163], v[172:175], v[56:59]
	v_mfma_f32_16x16x32_bf16 v[44:47], v[144:147], v[180:183], v[44:47]
	v_mfma_f32_16x16x32_bf16 v[40:43], v[160:163], v[180:183], v[40:43]
	v_mfma_f32_16x16x32_bf16 v[28:31], v[144:147], v[188:191], v[28:31]
	v_mfma_f32_16x16x32_bf16 v[24:27], v[160:163], v[188:191], v[24:27]
	v_mfma_f32_16x16x32_bf16 v[12:15], v[144:147], v[196:199], v[12:15]
	v_mfma_f32_16x16x32_bf16 v[8:11], v[160:163], v[196:199], v[8:11]
	v_mfma_f32_16x16x32_bf16 v[60:63], v[156:159], v[176:179], v[60:63]
	v_mfma_f32_16x16x32_bf16 v[56:59], v[164:167], v[176:179], v[56:59]
	v_mfma_f32_16x16x32_bf16 v[44:47], v[156:159], v[184:187], v[44:47]
	v_mfma_f32_16x16x32_bf16 v[40:43], v[164:167], v[184:187], v[40:43]
	v_mfma_f32_16x16x32_bf16 v[28:31], v[156:159], v[192:195], v[28:31]
	v_mfma_f32_16x16x32_bf16 v[24:27], v[164:167], v[192:195], v[24:27]
	v_mfma_f32_16x16x32_bf16 v[12:15], v[156:159], v[200:203], v[12:15]
	v_mfma_f32_16x16x32_bf16 v[8:11], v[164:167], v[200:203], v[8:11]
	s_setprio 0
	s_barrier
	s_add_u32 s50, s26, 0x80000
	s_addc_u32 s51, s27, 0
	s_add_i32 s52, s45, s34
	v_lshl_add_u64 v[144:145], s[50:51], 0, v[130:131]
	s_mov_b32 m0, s52
	s_nop 0
	global_load_lds_dwordx4 v[144:145], off
	v_lshl_add_u64 v[144:145], s[50:51], 0, v[134:135]
	s_add_i32 m0, s52, 0x2000
	s_nop 0
	global_load_lds_dwordx4 v[144:145], off
	s_waitcnt vmcnt(6)
	s_barrier
	s_setprio 1
	v_mfma_f32_16x16x32_bf16 v[52:55], v[204:207], v[172:175], v[52:55]
	v_mfma_f32_16x16x32_bf16 v[48:51], v[212:215], v[172:175], v[48:51]
	v_mfma_f32_16x16x32_bf16 v[36:39], v[204:207], v[180:183], v[36:39]
	v_mfma_f32_16x16x32_bf16 v[32:35], v[212:215], v[180:183], v[32:35]
	v_mfma_f32_16x16x32_bf16 v[20:23], v[204:207], v[188:191], v[20:23]
	v_mfma_f32_16x16x32_bf16 v[16:19], v[212:215], v[188:191], v[16:19]
	v_mfma_f32_16x16x32_bf16 v[4:7], v[204:207], v[196:199], v[4:7]
	v_mfma_f32_16x16x32_bf16 v[0:3], v[212:215], v[196:199], v[0:3]
	v_mfma_f32_16x16x32_bf16 v[52:55], v[208:211], v[176:179], v[52:55]
	v_mfma_f32_16x16x32_bf16 v[48:51], v[216:219], v[176:179], v[48:51]
	v_mfma_f32_16x16x32_bf16 v[36:39], v[208:211], v[184:187], v[36:39]
	v_mfma_f32_16x16x32_bf16 v[32:35], v[216:219], v[184:187], v[32:35]
	v_mfma_f32_16x16x32_bf16 v[20:23], v[208:211], v[192:195], v[20:23]
	v_mfma_f32_16x16x32_bf16 v[16:19], v[216:219], v[192:195], v[16:19]
	v_mfma_f32_16x16x32_bf16 v[4:7], v[208:211], v[200:203], v[4:7]
	v_mfma_f32_16x16x32_bf16 v[0:3], v[216:219], v[200:203], v[0:3]
	s_setprio 0
	s_add_i32 s50, 0, 0x18000
	v_add_u32_e32 v155, s50, v149
	s_barrier
	ds_read_b128 v[144:147], v155
	ds_read_b128 v[156:159], v155 offset:1024
	ds_read_b128 v[160:163], v155 offset:2048
	ds_read_b128 v[164:167], v155 offset:3072
	s_add_u32 s28, s28, 0x80000
	s_addc_u32 s29, s29, 0
	s_mov_b32 m0, s36
	v_lshl_add_u64 v[204:205], s[28:29], 0, v[128:129]
	ds_read_b128 v[172:175], v152 offset:32768
	ds_read_b128 v[176:179], v152 offset:33792
	ds_read_b128 v[180:183], v152 offset:34816
	ds_read_b128 v[184:187], v152 offset:35840
	ds_read_b128 v[188:191], v152 offset:36864
	ds_read_b128 v[192:195], v152 offset:37888
	ds_read_b128 v[196:199], v152 offset:38912
	ds_read_b128 v[200:203], v152 offset:39936
	global_load_lds_dwordx4 v[204:205], off
	v_lshl_add_u64 v[204:205], s[28:29], 0, v[132:133]
	s_mov_b32 m0, s37
	s_nop 0
	global_load_lds_dwordx4 v[204:205], off
	s_waitcnt lgkmcnt(8)
	s_barrier
	s_waitcnt lgkmcnt(0)
	s_setprio 1
	s_waitcnt lgkmcnt(0)
	v_mfma_f32_16x16x32_bf16 v[124:127], v[144:147], v[172:175], v[124:127]
	v_mfma_f32_16x16x32_bf16 v[120:123], v[160:163], v[172:175], v[120:123]
	v_mfma_f32_16x16x32_bf16 v[108:111], v[144:147], v[180:183], v[108:111]
	v_mfma_f32_16x16x32_bf16 v[104:107], v[160:163], v[180:183], v[104:107]
	v_mfma_f32_16x16x32_bf16 v[92:95], v[144:147], v[188:191], v[92:95]
	v_mfma_f32_16x16x32_bf16 v[88:91], v[160:163], v[188:191], v[88:91]
	v_mfma_f32_16x16x32_bf16 v[76:79], v[144:147], v[196:199], v[76:79]
	v_mfma_f32_16x16x32_bf16 v[72:75], v[160:163], v[196:199], v[72:75]
	v_mfma_f32_16x16x32_bf16 v[124:127], v[156:159], v[176:179], v[124:127]
	v_mfma_f32_16x16x32_bf16 v[120:123], v[164:167], v[176:179], v[120:123]
	v_mfma_f32_16x16x32_bf16 v[108:111], v[156:159], v[184:187], v[108:111]
	v_mfma_f32_16x16x32_bf16 v[104:107], v[164:167], v[184:187], v[104:107]
	v_mfma_f32_16x16x32_bf16 v[92:95], v[156:159], v[192:195], v[92:95]
	v_mfma_f32_16x16x32_bf16 v[88:91], v[164:167], v[192:195], v[88:91]
	v_mfma_f32_16x16x32_bf16 v[76:79], v[156:159], v[200:203], v[76:79]
	v_mfma_f32_16x16x32_bf16 v[72:75], v[164:167], v[200:203], v[72:75]
	s_setprio 0
	s_barrier
	s_add_i32 s28, 0, 0x1c000
	s_add_i32 s29, s50, s34
	v_add_u32_e32 v155, s28, v149
	v_lshl_add_u64 v[168:169], v[168:169], 0, s[10:11]
	s_mov_b32 m0, s29
	ds_read_b128 v[204:207], v155
	ds_read_b128 v[208:211], v155 offset:1024
	ds_read_b128 v[212:215], v155 offset:2048
	ds_read_b128 v[216:219], v155 offset:3072
	global_load_lds_dwordx4 v[168:169], off
	v_lshl_add_u64 v[168:169], v[220:221], 0, s[10:11]
	s_add_i32 m0, s29, 0x2000
	s_nop 0
	global_load_lds_dwordx4 v[168:169], off
	s_barrier
	s_waitcnt lgkmcnt(0)
	s_setprio 1
	s_waitcnt lgkmcnt(0)
	v_mfma_f32_16x16x32_bf16 v[116:119], v[204:207], v[172:175], v[116:119]
	v_mfma_f32_16x16x32_bf16 v[112:115], v[212:215], v[172:175], v[112:115]
	v_mfma_f32_16x16x32_bf16 v[100:103], v[204:207], v[180:183], v[100:103]
	v_mfma_f32_16x16x32_bf16 v[96:99], v[212:215], v[180:183], v[96:99]
	v_mfma_f32_16x16x32_bf16 v[84:87], v[204:207], v[188:191], v[84:87]
	v_mfma_f32_16x16x32_bf16 v[80:83], v[212:215], v[188:191], v[80:83]
	v_mfma_f32_16x16x32_bf16 v[68:71], v[204:207], v[196:199], v[68:71]
	v_mfma_f32_16x16x32_bf16 v[64:67], v[212:215], v[196:199], v[64:67]
	v_mfma_f32_16x16x32_bf16 v[116:119], v[208:211], v[176:179], v[116:119]
	v_mfma_f32_16x16x32_bf16 v[112:115], v[216:219], v[176:179], v[112:115]
	v_mfma_f32_16x16x32_bf16 v[100:103], v[208:211], v[184:187], v[100:103]
	v_mfma_f32_16x16x32_bf16 v[96:99], v[216:219], v[184:187], v[96:99]
	v_mfma_f32_16x16x32_bf16 v[84:87], v[208:211], v[192:195], v[84:87]
	v_mfma_f32_16x16x32_bf16 v[80:83], v[216:219], v[192:195], v[80:83]
	v_mfma_f32_16x16x32_bf16 v[68:71], v[208:211], v[200:203], v[68:71]
	v_mfma_f32_16x16x32_bf16 v[64:67], v[216:219], v[200:203], v[64:67]
	s_setprio 0
	s_mov_b32 m0, s39
	v_lshl_add_u64 v[168:169], v[222:223], 0, s[10:11]
	s_barrier
	ds_read_b128 v[172:175], v152 offset:49152
	ds_read_b128 v[176:179], v152 offset:50176
	ds_read_b128 v[180:183], v152 offset:51200
	ds_read_b128 v[184:187], v152 offset:52224
	ds_read_b128 v[188:191], v152 offset:53248
	ds_read_b128 v[192:195], v152 offset:54272
	ds_read_b128 v[196:199], v152 offset:55296
	ds_read_b128 v[200:203], v152 offset:56320
	global_load_lds_dwordx4 v[168:169], off
	v_lshl_add_u64 v[168:169], v[224:225], 0, s[10:11]
	s_mov_b32 m0, s40
	s_nop 0
	global_load_lds_dwordx4 v[168:169], off
	s_barrier
	s_waitcnt lgkmcnt(0)
	s_setprio 1
	s_waitcnt lgkmcnt(0)
	v_mfma_f32_16x16x32_bf16 v[60:63], v[144:147], v[172:175], v[60:63]
	v_mfma_f32_16x16x32_bf16 v[56:59], v[160:163], v[172:175], v[56:59]
	v_mfma_f32_16x16x32_bf16 v[44:47], v[144:147], v[180:183], v[44:47]
	v_mfma_f32_16x16x32_bf16 v[40:43], v[160:163], v[180:183], v[40:43]
	v_mfma_f32_16x16x32_bf16 v[28:31], v[144:147], v[188:191], v[28:31]
	v_mfma_f32_16x16x32_bf16 v[24:27], v[160:163], v[188:191], v[24:27]
	v_mfma_f32_16x16x32_bf16 v[12:15], v[144:147], v[196:199], v[12:15]
	v_mfma_f32_16x16x32_bf16 v[8:11], v[160:163], v[196:199], v[8:11]
	v_mfma_f32_16x16x32_bf16 v[60:63], v[156:159], v[176:179], v[60:63]
	v_mfma_f32_16x16x32_bf16 v[56:59], v[164:167], v[176:179], v[56:59]
	v_mfma_f32_16x16x32_bf16 v[44:47], v[156:159], v[184:187], v[44:47]
	v_mfma_f32_16x16x32_bf16 v[40:43], v[164:167], v[184:187], v[40:43]
	v_mfma_f32_16x16x32_bf16 v[28:31], v[156:159], v[192:195], v[28:31]
	v_mfma_f32_16x16x32_bf16 v[24:27], v[164:167], v[192:195], v[24:27]
	v_mfma_f32_16x16x32_bf16 v[12:15], v[156:159], v[200:203], v[12:15]
	v_mfma_f32_16x16x32_bf16 v[8:11], v[164:167], v[200:203], v[8:11]
	s_setprio 0
	s_barrier
	s_add_u32 s26, s26, 0x80080
	s_addc_u32 s27, s27, 0
	s_add_i32 s28, s28, s34
	v_lshl_add_u64 v[144:145], s[26:27], 0, v[130:131]
	s_mov_b32 m0, s28
	s_nop 0
	global_load_lds_dwordx4 v[144:145], off
	v_lshl_add_u64 v[144:145], s[26:27], 0, v[134:135]
	s_add_i32 m0, s28, 0x2000
	s_nop 0
	global_load_lds_dwordx4 v[144:145], off
	s_waitcnt vmcnt(6)
	s_barrier
	s_setprio 1
	v_mfma_f32_16x16x32_bf16 v[52:55], v[204:207], v[172:175], v[52:55]
	v_mfma_f32_16x16x32_bf16 v[48:51], v[212:215], v[172:175], v[48:51]
	v_mfma_f32_16x16x32_bf16 v[36:39], v[204:207], v[180:183], v[36:39]
	v_mfma_f32_16x16x32_bf16 v[32:35], v[212:215], v[180:183], v[32:35]
	v_mfma_f32_16x16x32_bf16 v[20:23], v[204:207], v[188:191], v[20:23]
	v_mfma_f32_16x16x32_bf16 v[16:19], v[212:215], v[188:191], v[16:19]
	v_mfma_f32_16x16x32_bf16 v[4:7], v[204:207], v[196:199], v[4:7]
	v_mfma_f32_16x16x32_bf16 v[0:3], v[212:215], v[196:199], v[0:3]
	v_mfma_f32_16x16x32_bf16 v[52:55], v[208:211], v[176:179], v[52:55]
	v_mfma_f32_16x16x32_bf16 v[48:51], v[216:219], v[176:179], v[48:51]
	v_mfma_f32_16x16x32_bf16 v[36:39], v[208:211], v[184:187], v[36:39]
	v_mfma_f32_16x16x32_bf16 v[32:35], v[216:219], v[184:187], v[32:35]
	v_mfma_f32_16x16x32_bf16 v[20:23], v[208:211], v[192:195], v[20:23]
	v_mfma_f32_16x16x32_bf16 v[16:19], v[216:219], v[192:195], v[16:19]
	v_mfma_f32_16x16x32_bf16 v[4:7], v[208:211], v[200:203], v[4:7]
	v_mfma_f32_16x16x32_bf16 v[0:3], v[216:219], v[200:203], v[0:3]
	s_setprio 0
	s_add_i32 s49, s49, 2
	s_add_u32 s24, s24, 0x100
	s_addc_u32 s25, s25, 0
	s_add_u32 s47, s47, 0x100
	s_addc_u32 s48, s48, 0
	s_cmp_gt_u32 s49, 29
	s_barrier
	s_cbranch_scc0 .LBB0_1184
	v_lshl_add_u32 v146, s20, 8, v148
	v_ashrrev_i32_e32 v147, 31, v146
	v_lshl_or_b32 v144, s22, 8, v150
	v_lshlrev_b32_e32 v179, 12, v146
	v_lshl_add_u32 v178, v144, 1, v179
	global_load_dwordx4 v[180:183], v178, s[6:7]
	global_load_dwordx4 v[184:187], v178, s[6:7] offset:256
	s_add_u32 s98, s6, 0x10000
	s_addc_u32 s99, s7, 0
	global_load_dwordx4 v[188:191], v178, s[98:99]
	global_load_dwordx4 v[192:195], v178, s[98:99] offset:256
	s_add_u32 s98, s6, 0x20000
	s_addc_u32 s99, s7, 0
	global_load_dwordx4 v[196:199], v178, s[98:99]
	global_load_dwordx4 v[200:203], v178, s[98:99] offset:256
	s_add_u32 s98, s6, 0x30000
	s_addc_u32 s99, s7, 0
	global_load_dwordx4 v[204:207], v178, s[98:99]
	global_load_dwordx4 v[208:211], v178, s[98:99] offset:256
	s_add_u32 s98, s6, 0x80000
	s_addc_u32 s99, s7, 0
	global_load_dwordx4 v[212:215], v178, s[98:99]
	global_load_dwordx4 v[216:219], v178, s[98:99] offset:256
	s_add_u32 s98, s6, 0x90000
	s_addc_u32 s99, s7, 0
	global_load_dwordx4 v[236:239], v178, s[98:99]
	global_load_dwordx4 v[240:243], v178, s[98:99] offset:256
	s_add_u32 s98, s6, 0xa0000
	s_addc_u32 s99, s7, 0
	global_load_dwordx4 v[244:247], v178, s[98:99]
	global_load_dwordx4 v[248:251], v178, s[98:99] offset:256
	s_add_u32 s98, s6, 0xb0000
	s_addc_u32 s99, s7, 0
	global_load_dwordx4 v[220:223], v178, s[98:99]
	global_load_dwordx4 v[252:255], v178, s[98:99] offset:256
	v_lshlrev_b64 v[156:157], 12, v[146:147]
	v_ashrrev_i32_e32 v145, 31, v144
	v_lshl_add_u64 v[156:157], s[6:7], 0, v[156:157]
	v_lshl_add_u64 v[166:167], v[144:145], 1, v[156:157]
	v_and_b32_e32 v156, 64, v154
	v_xor_b32_e32 v155, 16, v154
	v_add_u32_e32 v156, 64, v156
	v_xor_b32_e32 v157, 32, v154
	v_cmp_lt_i32_e32 vcc, v155, v156
	s_waitcnt vmcnt(14)
	v_lshlrev_b32_e32 v168, 16, v180
	v_and_b32_e32 v169, 0xffff0000, v180
	v_lshlrev_b32_e32 v180, 16, v181
	v_and_b32_e32 v181, 0xffff0000, v181
	v_lshlrev_b32_e32 v174, 16, v184
	v_and_b32_e32 v175, 0xffff0000, v184
	v_lshlrev_b32_e32 v184, 16, v185
	v_and_b32_e32 v185, 0xffff0000, v185
	v_cndmask_b32_e32 v155, v154, v155, vcc
	v_cmp_lt_i32_e32 vcc, v157, v156
	v_lshlrev_b32_e32 v172, 16, v182
	v_and_b32_e32 v173, 0xffff0000, v182
	v_lshlrev_b32_e32 v182, 16, v183
	v_and_b32_e32 v183, 0xffff0000, v183
	v_lshlrev_b32_e32 v176, 16, v186
	v_and_b32_e32 v177, 0xffff0000, v186
	v_lshlrev_b32_e32 v186, 16, v187
	v_and_b32_e32 v187, 0xffff0000, v187
	v_pk_add_f32 v[126:127], v[126:127], v[180:181]
	v_pk_add_f32 v[124:125], v[124:125], v[168:169]
	v_pk_add_f32 v[118:119], v[118:119], v[184:185]
	v_pk_add_f32 v[116:117], v[116:117], v[174:175]
	v_cndmask_b32_e32 v157, v154, v157, vcc
	v_pk_add_f32 v[122:123], v[122:123], v[182:183]
	v_pk_add_f32 v[120:121], v[120:121], v[172:173]
	v_pk_add_f32 v[180:181], v[114:115], v[186:187]
	v_pk_add_f32 v[182:183], v[112:113], v[176:177]
	v_mul_f32_e32 v114, v125, v125
	v_mul_f32_e32 v115, v127, v127
	v_cvt_pk_bf16_f32 v112, v124, v125
	v_cvt_pk_bf16_f32 v113, v126, v127
	v_mul_f32_e32 v125, v117, v117
	v_mul_f32_e32 v127, v119, v119
	v_lshlrev_b32_e32 v156, 2, v155
	v_lshlrev_b32_e32 v155, 2, v157
	v_mul_f32_e32 v157, v121, v121
	v_mul_f32_e32 v185, v183, v183
	v_fmac_f32_e32 v114, v124, v124
	v_fmac_f32_e32 v115, v126, v126
	v_fmac_f32_e32 v125, v116, v116
	v_fmac_f32_e32 v127, v118, v118
	v_mul_f32_e32 v184, v123, v123
	v_mul_f32_e32 v186, v181, v181
	v_fmac_f32_e32 v157, v120, v120
	v_fmac_f32_e32 v185, v182, v182
	v_add_f32_e32 v114, v114, v115
	v_add_f32_e32 v115, v125, v127
	v_fmac_f32_e32 v184, v122, v122
	v_fmac_f32_e32 v186, v180, v180
	v_add_f32_e32 v114, v157, v114
	v_add_f32_e32 v115, v185, v115
	v_add_f32_e32 v114, v184, v114
	v_add_f32_e32 v115, v186, v115
	v_add_f32_e32 v124, v114, v115
	ds_bpermute_b32 v125, v156, v124
	v_cvt_pk_bf16_f32 v114, v120, v121
	v_cvt_pk_bf16_f32 v115, v122, v123
	global_store_dwordx4 v[166:167], v[112:115], off
	s_waitcnt lgkmcnt(0)
	s_nop 0
	v_add_f32_e32 v112, v124, v125
	ds_bpermute_b32 v113, v155, v112
	v_cvt_pk_bf16_f32 v114, v116, v117
	v_cvt_pk_bf16_f32 v115, v118, v119
	v_cvt_pk_bf16_f32 v116, v182, v183
	v_cvt_pk_bf16_f32 v117, v180, v181
	global_store_dwordx4 v[166:167], v[114:117], off offset:256
	s_and_saveexec_b64 s[20:21], s[2:3]
	s_cbranch_execz .LBB0_1187
	v_lshl_add_u64 v[114:115], v[146:147], 2, s[8:9]
	s_waitcnt lgkmcnt(0)
	v_add_f32_e32 v112, v112, v113
	global_atomic_add_f32 v[114:115], v112, off
.LBB0_1187:
	s_or_b64 exec, exec, s[20:21]
	v_or_b32_e32 v112, 16, v146
	s_waitcnt lgkmcnt(0)
	v_ashrrev_i32_e32 v113, 31, v112
	v_lshlrev_b64 v[114:115], 12, v[112:113]
	v_lshl_add_u64 v[114:115], s[6:7], 0, v[114:115]
	v_lshl_add_u64 v[122:123], v[144:145], 1, v[114:115]
	s_waitcnt vmcnt(16)
	v_lshlrev_b32_e32 v124, 16, v188
	v_and_b32_e32 v125, 0xffff0000, v188
	v_lshlrev_b32_e32 v188, 16, v189
	v_and_b32_e32 v189, 0xffff0000, v189
	s_waitcnt vmcnt(15)
	v_lshlrev_b32_e32 v158, 16, v192
	v_and_b32_e32 v159, 0xffff0000, v192
	v_lshlrev_b32_e32 v192, 16, v193
	v_and_b32_e32 v193, 0xffff0000, v193
	v_lshlrev_b32_e32 v126, 16, v190
	v_and_b32_e32 v127, 0xffff0000, v190
	v_lshlrev_b32_e32 v190, 16, v191
	v_and_b32_e32 v191, 0xffff0000, v191
	v_lshlrev_b32_e32 v160, 16, v194
	v_and_b32_e32 v161, 0xffff0000, v194
	v_lshlrev_b32_e32 v194, 16, v195
	v_and_b32_e32 v195, 0xffff0000, v195
	v_pk_add_f32 v[110:111], v[110:111], v[188:189]
	v_pk_add_f32 v[108:109], v[108:109], v[124:125]
	v_pk_add_f32 v[102:103], v[102:103], v[192:193]
	v_pk_add_f32 v[100:101], v[100:101], v[158:159]
	v_pk_add_f32 v[106:107], v[106:107], v[190:191]
	v_pk_add_f32 v[104:105], v[104:105], v[126:127]
	v_pk_add_f32 v[188:189], v[98:99], v[194:195]
	v_pk_add_f32 v[190:191], v[96:97], v[160:161]
	v_mul_f32_e32 v98, v109, v109
	v_mul_f32_e32 v99, v111, v111
	v_cvt_pk_bf16_f32 v96, v108, v109
	v_cvt_pk_bf16_f32 v97, v110, v111
	v_mul_f32_e32 v109, v101, v101
	v_mul_f32_e32 v111, v103, v103
	v_mul_f32_e32 v192, v105, v105
	v_mul_f32_e32 v194, v191, v191
	v_fmac_f32_e32 v98, v108, v108
	v_fmac_f32_e32 v99, v110, v110
	v_fmac_f32_e32 v109, v100, v100
	v_fmac_f32_e32 v111, v102, v102
	v_mul_f32_e32 v193, v107, v107
	v_mul_f32_e32 v195, v189, v189
	v_fmac_f32_e32 v192, v104, v104
	v_fmac_f32_e32 v194, v190, v190
	v_add_f32_e32 v98, v98, v99
	v_add_f32_e32 v99, v109, v111
	v_fmac_f32_e32 v193, v106, v106
	v_fmac_f32_e32 v195, v188, v188
	v_add_f32_e32 v98, v192, v98
	v_add_f32_e32 v99, v194, v99
	v_add_f32_e32 v98, v193, v98
	v_add_f32_e32 v99, v195, v99
	v_add_f32_e32 v108, v98, v99
	ds_bpermute_b32 v109, v156, v108
	v_cvt_pk_bf16_f32 v98, v104, v105
	v_cvt_pk_bf16_f32 v99, v106, v107
	global_store_dwordx4 v[122:123], v[96:99], off
	s_waitcnt lgkmcnt(0)
	s_nop 0
	v_add_f32_e32 v96, v108, v109
	ds_bpermute_b32 v97, v155, v96
	v_cvt_pk_bf16_f32 v98, v100, v101
	v_cvt_pk_bf16_f32 v99, v102, v103
	v_cvt_pk_bf16_f32 v100, v190, v191
	v_cvt_pk_bf16_f32 v101, v188, v189
	global_store_dwordx4 v[122:123], v[98:101], off offset:256
	s_and_saveexec_b64 s[20:21], s[2:3]
	s_cbranch_execz .LBB0_1189
	v_lshl_add_u64 v[98:99], v[112:113], 2, s[8:9]
	s_waitcnt lgkmcnt(0)
	v_add_f32_e32 v96, v96, v97
	global_atomic_add_f32 v[98:99], v96, off
.LBB0_1189:
	s_or_b64 exec, exec, s[20:21]
	v_or_b32_e32 v96, 32, v146
	s_waitcnt lgkmcnt(0)
	v_ashrrev_i32_e32 v97, 31, v96
	v_lshlrev_b64 v[98:99], 12, v[96:97]
	v_lshl_add_u64 v[98:99], s[6:7], 0, v[98:99]
	v_lshl_add_u64 v[106:107], v[144:145], 1, v[98:99]
	s_waitcnt vmcnt(17)
	v_lshlrev_b32_e32 v108, 16, v196
	v_and_b32_e32 v109, 0xffff0000, v196
	v_lshlrev_b32_e32 v196, 16, v197
	v_and_b32_e32 v197, 0xffff0000, v197
	s_waitcnt vmcnt(16)
	v_lshlrev_b32_e32 v112, 16, v200
	v_and_b32_e32 v113, 0xffff0000, v200
	v_lshlrev_b32_e32 v200, 16, v201
	v_and_b32_e32 v201, 0xffff0000, v201
	v_lshlrev_b32_e32 v110, 16, v198
	v_and_b32_e32 v111, 0xffff0000, v198
	v_lshlrev_b32_e32 v198, 16, v199
	v_and_b32_e32 v199, 0xffff0000, v199
	v_lshlrev_b32_e32 v114, 16, v202
	v_and_b32_e32 v115, 0xffff0000, v202
	v_lshlrev_b32_e32 v202, 16, v203
	v_and_b32_e32 v203, 0xffff0000, v203
	v_pk_add_f32 v[94:95], v[94:95], v[196:197]
	v_pk_add_f32 v[92:93], v[92:93], v[108:109]
	v_pk_add_f32 v[86:87], v[86:87], v[200:201]
	v_pk_add_f32 v[84:85], v[84:85], v[112:113]
	v_pk_add_f32 v[90:91], v[90:91], v[198:199]
	v_pk_add_f32 v[88:89], v[88:89], v[110:111]
	v_pk_add_f32 v[196:197], v[82:83], v[202:203]
	v_pk_add_f32 v[198:199], v[80:81], v[114:115]
	v_mul_f32_e32 v82, v93, v93
	v_mul_f32_e32 v83, v95, v95
	v_cvt_pk_bf16_f32 v80, v92, v93
	v_cvt_pk_bf16_f32 v81, v94, v95
	v_mul_f32_e32 v93, v85, v85
	v_mul_f32_e32 v95, v87, v87
	v_mul_f32_e32 v200, v89, v89
	v_mul_f32_e32 v202, v199, v199
	v_fmac_f32_e32 v82, v92, v92
	v_fmac_f32_e32 v83, v94, v94
	v_fmac_f32_e32 v93, v84, v84
	v_fmac_f32_e32 v95, v86, v86
	v_mul_f32_e32 v201, v91, v91
	v_mul_f32_e32 v203, v197, v197
	v_fmac_f32_e32 v200, v88, v88
	v_fmac_f32_e32 v202, v198, v198
	v_add_f32_e32 v82, v82, v83
	v_add_f32_e32 v83, v93, v95
	v_fmac_f32_e32 v201, v90, v90
	v_fmac_f32_e32 v203, v196, v196
	v_add_f32_e32 v82, v200, v82
	v_add_f32_e32 v83, v202, v83
	v_add_f32_e32 v82, v201, v82
	v_add_f32_e32 v83, v203, v83
	v_add_f32_e32 v92, v82, v83
	ds_bpermute_b32 v93, v156, v92
	v_cvt_pk_bf16_f32 v82, v88, v89
	v_cvt_pk_bf16_f32 v83, v90, v91
	global_store_dwordx4 v[106:107], v[80:83], off
	s_waitcnt lgkmcnt(0)
	s_nop 0
	v_add_f32_e32 v80, v92, v93
	ds_bpermute_b32 v81, v155, v80
	v_cvt_pk_bf16_f32 v82, v84, v85
	v_cvt_pk_bf16_f32 v83, v86, v87
	v_cvt_pk_bf16_f32 v84, v198, v199
	v_cvt_pk_bf16_f32 v85, v196, v197
	global_store_dwordx4 v[106:107], v[82:85], off offset:256
	s_and_saveexec_b64 s[20:21], s[2:3]
	s_cbranch_execz .LBB0_1191
	v_lshl_add_u64 v[82:83], v[96:97], 2, s[8:9]
	s_waitcnt lgkmcnt(0)
	v_add_f32_e32 v80, v80, v81
	global_atomic_add_f32 v[82:83], v80, off
.LBB0_1191:
	s_or_b64 exec, exec, s[20:21]
	v_or_b32_e32 v80, 48, v146
	s_waitcnt lgkmcnt(0)
	v_ashrrev_i32_e32 v81, 31, v80
	v_lshlrev_b64 v[82:83], 12, v[80:81]
	v_lshl_add_u64 v[82:83], s[6:7], 0, v[82:83]
	v_lshl_add_u64 v[90:91], v[144:145], 1, v[82:83]
	s_waitcnt vmcnt(18)
	v_lshlrev_b32_e32 v92, 16, v204
	v_and_b32_e32 v93, 0xffff0000, v204
	v_lshlrev_b32_e32 v204, 16, v205
	v_and_b32_e32 v205, 0xffff0000, v205
	s_waitcnt vmcnt(17)
	v_lshlrev_b32_e32 v96, 16, v208
	v_and_b32_e32 v97, 0xffff0000, v208
	v_lshlrev_b32_e32 v208, 16, v209
	v_and_b32_e32 v209, 0xffff0000, v209
	v_lshlrev_b32_e32 v94, 16, v206
	v_and_b32_e32 v95, 0xffff0000, v206
	v_lshlrev_b32_e32 v206, 16, v207
	v_and_b32_e32 v207, 0xffff0000, v207
	v_lshlrev_b32_e32 v98, 16, v210
	v_and_b32_e32 v99, 0xffff0000, v210
	v_lshlrev_b32_e32 v210, 16, v211
	v_and_b32_e32 v211, 0xffff0000, v211
	v_pk_add_f32 v[78:79], v[78:79], v[204:205]
	v_pk_add_f32 v[76:77], v[76:77], v[92:93]
	v_pk_add_f32 v[70:71], v[70:71], v[208:209]
	v_pk_add_f32 v[68:69], v[68:69], v[96:97]
	v_pk_add_f32 v[74:75], v[74:75], v[206:207]
	v_pk_add_f32 v[72:73], v[72:73], v[94:95]
	v_pk_add_f32 v[204:205], v[66:67], v[210:211]
	v_pk_add_f32 v[206:207], v[64:65], v[98:99]
	v_mul_f32_e32 v66, v77, v77
	v_mul_f32_e32 v67, v79, v79
	v_cvt_pk_bf16_f32 v64, v76, v77
	v_cvt_pk_bf16_f32 v65, v78, v79
	v_mul_f32_e32 v77, v69, v69
	v_mul_f32_e32 v79, v71, v71
	v_mul_f32_e32 v208, v73, v73
	v_mul_f32_e32 v210, v207, v207
	v_fmac_f32_e32 v66, v76, v76
	v_fmac_f32_e32 v67, v78, v78
	v_fmac_f32_e32 v77, v68, v68
	v_fmac_f32_e32 v79, v70, v70
	v_mul_f32_e32 v209, v75, v75
	v_mul_f32_e32 v211, v205, v205
	v_fmac_f32_e32 v208, v72, v72
	v_fmac_f32_e32 v210, v206, v206
	v_add_f32_e32 v66, v66, v67
	v_add_f32_e32 v67, v77, v79
	v_fmac_f32_e32 v209, v74, v74
	v_fmac_f32_e32 v211, v204, v204
	v_add_f32_e32 v66, v208, v66
	v_add_f32_e32 v67, v210, v67
	v_add_f32_e32 v66, v209, v66
	v_add_f32_e32 v67, v211, v67
	v_add_f32_e32 v76, v66, v67
	ds_bpermute_b32 v77, v156, v76
	v_cvt_pk_bf16_f32 v66, v72, v73
	v_cvt_pk_bf16_f32 v67, v74, v75
	global_store_dwordx4 v[90:91], v[64:67], off
	s_waitcnt lgkmcnt(0)
	s_nop 0
	v_add_f32_e32 v64, v76, v77
	ds_bpermute_b32 v65, v155, v64
	v_cvt_pk_bf16_f32 v66, v68, v69
	v_cvt_pk_bf16_f32 v67, v70, v71
	v_cvt_pk_bf16_f32 v68, v206, v207
	v_cvt_pk_bf16_f32 v69, v204, v205
	global_store_dwordx4 v[90:91], v[66:69], off offset:256
	s_and_saveexec_b64 s[20:21], s[2:3]
	s_cbranch_execz .LBB0_1193
	v_lshl_add_u64 v[66:67], v[80:81], 2, s[8:9]
	s_waitcnt lgkmcnt(0)
	v_add_f32_e32 v64, v64, v65
	global_atomic_add_f32 v[66:67], v64, off
.LBB0_1193:
	s_or_b64 exec, exec, s[20:21]
	v_add_u32_e32 v64, 0x80, v146
	s_waitcnt lgkmcnt(0)
	v_ashrrev_i32_e32 v65, 31, v64
	v_lshlrev_b64 v[66:67], 12, v[64:65]
	v_lshl_add_u64 v[66:67], s[6:7], 0, v[66:67]
	v_lshl_add_u64 v[74:75], v[144:145], 1, v[66:67]
	s_waitcnt vmcnt(19)
	v_lshlrev_b32_e32 v76, 16, v212
	v_and_b32_e32 v77, 0xffff0000, v212
	v_lshlrev_b32_e32 v212, 16, v213
	v_and_b32_e32 v213, 0xffff0000, v213
	s_waitcnt vmcnt(18)
	v_lshlrev_b32_e32 v80, 16, v216
	v_and_b32_e32 v81, 0xffff0000, v216
	v_lshlrev_b32_e32 v216, 16, v217
	v_and_b32_e32 v217, 0xffff0000, v217
	v_lshlrev_b32_e32 v78, 16, v214
	v_and_b32_e32 v79, 0xffff0000, v214
	v_lshlrev_b32_e32 v214, 16, v215
	v_and_b32_e32 v215, 0xffff0000, v215
	v_lshlrev_b32_e32 v82, 16, v218
	v_and_b32_e32 v83, 0xffff0000, v218
	v_lshlrev_b32_e32 v218, 16, v219
	v_and_b32_e32 v219, 0xffff0000, v219
	v_pk_add_f32 v[62:63], v[62:63], v[212:213]
	v_pk_add_f32 v[60:61], v[60:61], v[76:77]
	v_pk_add_f32 v[54:55], v[54:55], v[216:217]
	v_pk_add_f32 v[52:53], v[52:53], v[80:81]
	v_pk_add_f32 v[58:59], v[58:59], v[214:215]
	v_pk_add_f32 v[56:57], v[56:57], v[78:79]
	v_pk_add_f32 v[212:213], v[50:51], v[218:219]
	v_pk_add_f32 v[214:215], v[48:49], v[82:83]
	v_mul_f32_e32 v50, v61, v61
	v_mul_f32_e32 v51, v63, v63
	v_cvt_pk_bf16_f32 v48, v60, v61
	v_cvt_pk_bf16_f32 v49, v62, v63
	v_mul_f32_e32 v61, v53, v53
	v_mul_f32_e32 v63, v55, v55
	v_mul_f32_e32 v216, v57, v57
	v_mul_f32_e32 v218, v215, v215
	v_fmac_f32_e32 v50, v60, v60
	v_fmac_f32_e32 v51, v62, v62
	v_fmac_f32_e32 v61, v52, v52
	v_fmac_f32_e32 v63, v54, v54
	v_mul_f32_e32 v217, v59, v59
	v_mul_f32_e32 v219, v213, v213
	v_fmac_f32_e32 v216, v56, v56
	v_fmac_f32_e32 v218, v214, v214
	v_add_f32_e32 v50, v50, v51
	v_add_f32_e32 v51, v61, v63
	v_fmac_f32_e32 v217, v58, v58
	v_fmac_f32_e32 v219, v212, v212
	v_add_f32_e32 v50, v216, v50
	v_add_f32_e32 v51, v218, v51
	v_add_f32_e32 v50, v217, v50
	v_add_f32_e32 v51, v219, v51
	v_add_f32_e32 v60, v50, v51
	ds_bpermute_b32 v61, v156, v60
	v_cvt_pk_bf16_f32 v50, v56, v57
	v_cvt_pk_bf16_f32 v51, v58, v59
	global_store_dwordx4 v[74:75], v[48:51], off
	s_waitcnt lgkmcnt(0)
	s_nop 0
	v_add_f32_e32 v48, v60, v61
	ds_bpermute_b32 v49, v155, v48
	v_cvt_pk_bf16_f32 v50, v52, v53
	v_cvt_pk_bf16_f32 v51, v54, v55
	v_cvt_pk_bf16_f32 v52, v214, v215
	v_cvt_pk_bf16_f32 v53, v212, v213
	global_store_dwordx4 v[74:75], v[50:53], off offset:256
	s_and_saveexec_b64 s[20:21], s[2:3]
	s_cbranch_execz .LBB0_1195
	v_lshl_add_u64 v[50:51], v[64:65], 2, s[8:9]
	s_waitcnt lgkmcnt(0)
	v_add_f32_e32 v48, v48, v49
	global_atomic_add_f32 v[50:51], v48, off
.LBB0_1195:
	s_or_b64 exec, exec, s[20:21]
	v_add_u32_e32 v48, 0x90, v146
	s_waitcnt lgkmcnt(0)
	v_ashrrev_i32_e32 v49, 31, v48
	v_lshlrev_b64 v[50:51], 12, v[48:49]
	v_lshl_add_u64 v[50:51], s[6:7], 0, v[50:51]
	v_lshl_add_u64 v[58:59], v[144:145], 1, v[50:51]
	s_waitcnt vmcnt(20)
	v_lshlrev_b32_e32 v60, 16, v236
	v_and_b32_e32 v61, 0xffff0000, v236
	v_lshlrev_b32_e32 v236, 16, v237
	v_and_b32_e32 v237, 0xffff0000, v237
	s_waitcnt vmcnt(19)
	v_lshlrev_b32_e32 v64, 16, v240
	v_and_b32_e32 v65, 0xffff0000, v240
	v_lshlrev_b32_e32 v240, 16, v241
	v_and_b32_e32 v241, 0xffff0000, v241
	v_lshlrev_b32_e32 v62, 16, v238
	v_and_b32_e32 v63, 0xffff0000, v238
	v_lshlrev_b32_e32 v238, 16, v239
	v_and_b32_e32 v239, 0xffff0000, v239
	v_lshlrev_b32_e32 v66, 16, v242
	v_and_b32_e32 v67, 0xffff0000, v242
	v_lshlrev_b32_e32 v242, 16, v243
	v_and_b32_e32 v243, 0xffff0000, v243
	v_pk_add_f32 v[46:47], v[46:47], v[236:237]
	v_pk_add_f32 v[44:45], v[44:45], v[60:61]
	v_pk_add_f32 v[38:39], v[38:39], v[240:241]
	v_pk_add_f32 v[36:37], v[36:37], v[64:65]
	v_pk_add_f32 v[42:43], v[42:43], v[238:239]
	v_pk_add_f32 v[40:41], v[40:41], v[62:63]
	v_pk_add_f32 v[236:237], v[34:35], v[242:243]
	v_pk_add_f32 v[238:239], v[32:33], v[66:67]
	v_mul_f32_e32 v34, v45, v45
	v_mul_f32_e32 v35, v47, v47
	v_cvt_pk_bf16_f32 v32, v44, v45
	v_cvt_pk_bf16_f32 v33, v46, v47
	v_mul_f32_e32 v45, v37, v37
	v_mul_f32_e32 v47, v39, v39
	v_mul_f32_e32 v240, v41, v41
	v_mul_f32_e32 v242, v239, v239
	v_fmac_f32_e32 v34, v44, v44
	v_fmac_f32_e32 v35, v46, v46
	v_fmac_f32_e32 v45, v36, v36
	v_fmac_f32_e32 v47, v38, v38
	v_mul_f32_e32 v241, v43, v43
	v_mul_f32_e32 v243, v237, v237
	v_fmac_f32_e32 v240, v40, v40
	v_fmac_f32_e32 v242, v238, v238
	v_add_f32_e32 v34, v34, v35
	v_add_f32_e32 v35, v45, v47
	v_fmac_f32_e32 v241, v42, v42
	v_fmac_f32_e32 v243, v236, v236
	v_add_f32_e32 v34, v240, v34
	v_add_f32_e32 v35, v242, v35
	v_add_f32_e32 v34, v241, v34
	v_add_f32_e32 v35, v243, v35
	v_add_f32_e32 v44, v34, v35
	ds_bpermute_b32 v45, v156, v44
	v_cvt_pk_bf16_f32 v34, v40, v41
	v_cvt_pk_bf16_f32 v35, v42, v43
	global_store_dwordx4 v[58:59], v[32:35], off
	s_waitcnt lgkmcnt(0)
	s_nop 0
	v_add_f32_e32 v32, v44, v45
	ds_bpermute_b32 v33, v155, v32
	v_cvt_pk_bf16_f32 v34, v36, v37
	v_cvt_pk_bf16_f32 v35, v38, v39
	v_cvt_pk_bf16_f32 v36, v238, v239
	v_cvt_pk_bf16_f32 v37, v236, v237
	global_store_dwordx4 v[58:59], v[34:37], off offset:256
	s_and_saveexec_b64 s[20:21], s[2:3]
	s_cbranch_execz .LBB0_1197
	v_lshl_add_u64 v[34:35], v[48:49], 2, s[8:9]
	s_waitcnt lgkmcnt(0)
	v_add_f32_e32 v32, v32, v33
	global_atomic_add_f32 v[34:35], v32, off
.LBB0_1197:
	s_or_b64 exec, exec, s[20:21]
	v_add_u32_e32 v32, 0xa0, v146
	s_waitcnt lgkmcnt(0)
	v_ashrrev_i32_e32 v33, 31, v32
	v_lshlrev_b64 v[34:35], 12, v[32:33]
	v_lshl_add_u64 v[34:35], s[6:7], 0, v[34:35]
	v_lshl_add_u64 v[42:43], v[144:145], 1, v[34:35]
	s_waitcnt vmcnt(21)
	v_lshlrev_b32_e32 v44, 16, v244
	v_and_b32_e32 v45, 0xffff0000, v244
	v_lshlrev_b32_e32 v244, 16, v245
	v_and_b32_e32 v245, 0xffff0000, v245
	s_waitcnt vmcnt(20)
	v_lshlrev_b32_e32 v48, 16, v248
	v_and_b32_e32 v49, 0xffff0000, v248
	v_lshlrev_b32_e32 v248, 16, v249
	v_and_b32_e32 v249, 0xffff0000, v249
	v_lshlrev_b32_e32 v46, 16, v246
	v_and_b32_e32 v47, 0xffff0000, v246
	v_lshlrev_b32_e32 v246, 16, v247
	v_and_b32_e32 v247, 0xffff0000, v247
	v_lshlrev_b32_e32 v50, 16, v250
	v_and_b32_e32 v51, 0xffff0000, v250
	v_lshlrev_b32_e32 v250, 16, v251
	v_and_b32_e32 v251, 0xffff0000, v251
	v_pk_add_f32 v[30:31], v[30:31], v[244:245]
	v_pk_add_f32 v[28:29], v[28:29], v[44:45]
	v_pk_add_f32 v[22:23], v[22:23], v[248:249]
	v_pk_add_f32 v[20:21], v[20:21], v[48:49]
	v_pk_add_f32 v[26:27], v[26:27], v[246:247]
	v_pk_add_f32 v[24:25], v[24:25], v[46:47]
	v_pk_add_f32 v[244:245], v[18:19], v[250:251]
	v_pk_add_f32 v[246:247], v[16:17], v[50:51]
	v_mul_f32_e32 v18, v29, v29
	v_mul_f32_e32 v19, v31, v31
	v_cvt_pk_bf16_f32 v16, v28, v29
	v_cvt_pk_bf16_f32 v17, v30, v31
	v_mul_f32_e32 v29, v21, v21
	v_mul_f32_e32 v31, v23, v23
	v_mul_f32_e32 v248, v25, v25
	v_mul_f32_e32 v250, v247, v247
	v_fmac_f32_e32 v18, v28, v28
	v_fmac_f32_e32 v19, v30, v30
	v_fmac_f32_e32 v29, v20, v20
	v_fmac_f32_e32 v31, v22, v22
	v_mul_f32_e32 v249, v27, v27
	v_mul_f32_e32 v251, v245, v245
	v_fmac_f32_e32 v248, v24, v24
	v_fmac_f32_e32 v250, v246, v246
	v_add_f32_e32 v18, v18, v19
	v_add_f32_e32 v19, v29, v31
	v_fmac_f32_e32 v249, v26, v26
	v_fmac_f32_e32 v251, v244, v244
	v_add_f32_e32 v18, v248, v18
	v_add_f32_e32 v19, v250, v19
	v_add_f32_e32 v18, v249, v18
	v_add_f32_e32 v19, v251, v19
	v_add_f32_e32 v28, v18, v19
	ds_bpermute_b32 v29, v156, v28
	v_cvt_pk_bf16_f32 v18, v24, v25
	v_cvt_pk_bf16_f32 v19, v26, v27
	global_store_dwordx4 v[42:43], v[16:19], off
	s_waitcnt lgkmcnt(0)
	s_nop 0
	v_add_f32_e32 v16, v28, v29
	ds_bpermute_b32 v17, v155, v16
	v_cvt_pk_bf16_f32 v18, v20, v21
	v_cvt_pk_bf16_f32 v19, v22, v23
	v_cvt_pk_bf16_f32 v20, v246, v247
	v_cvt_pk_bf16_f32 v21, v244, v245
	global_store_dwordx4 v[42:43], v[18:21], off offset:256
	s_and_saveexec_b64 s[20:21], s[2:3]
	s_cbranch_execz .LBB0_1199
	v_lshl_add_u64 v[18:19], v[32:33], 2, s[8:9]
	s_waitcnt lgkmcnt(0)
	v_add_f32_e32 v16, v16, v17
	global_atomic_add_f32 v[18:19], v16, off
.LBB0_1199:
	s_or_b64 exec, exec, s[20:21]
	v_add_u32_e32 v16, 0xb0, v146
	s_waitcnt lgkmcnt(0)
	v_ashrrev_i32_e32 v17, 31, v16
	v_lshlrev_b64 v[18:19], 12, v[16:17]
	v_lshl_add_u64 v[18:19], s[6:7], 0, v[18:19]
	v_lshl_add_u64 v[26:27], v[144:145], 1, v[18:19]
	s_waitcnt vmcnt(22)
	v_lshlrev_b32_e32 v28, 16, v220
	v_and_b32_e32 v29, 0xffff0000, v220
	v_lshlrev_b32_e32 v220, 16, v221
	v_and_b32_e32 v221, 0xffff0000, v221
	s_waitcnt vmcnt(21)
	v_lshlrev_b32_e32 v32, 16, v252
	v_and_b32_e32 v33, 0xffff0000, v252
	v_lshlrev_b32_e32 v252, 16, v253
	v_and_b32_e32 v253, 0xffff0000, v253
	v_lshlrev_b32_e32 v30, 16, v222
	v_and_b32_e32 v31, 0xffff0000, v222
	v_lshlrev_b32_e32 v222, 16, v223
	v_and_b32_e32 v223, 0xffff0000, v223
	v_lshlrev_b32_e32 v34, 16, v254
	v_and_b32_e32 v35, 0xffff0000, v254
	v_lshlrev_b32_e32 v254, 16, v255
	v_and_b32_e32 v255, 0xffff0000, v255
	v_pk_add_f32 v[14:15], v[14:15], v[220:221]
	v_pk_add_f32 v[12:13], v[12:13], v[28:29]
	v_pk_add_f32 v[6:7], v[6:7], v[252:253]
	v_pk_add_f32 v[4:5], v[4:5], v[32:33]
	v_pk_add_f32 v[10:11], v[10:11], v[222:223]
	v_pk_add_f32 v[8:9], v[8:9], v[30:31]
	v_pk_add_f32 v[220:221], v[2:3], v[254:255]
	v_pk_add_f32 v[222:223], v[0:1], v[34:35]
	v_mul_f32_e32 v2, v13, v13
	v_mul_f32_e32 v3, v15, v15
	v_cvt_pk_bf16_f32 v0, v12, v13
	v_cvt_pk_bf16_f32 v1, v14, v15
	v_mul_f32_e32 v13, v5, v5
	v_mul_f32_e32 v15, v7, v7
	v_mul_f32_e32 v252, v9, v9
	v_mul_f32_e32 v254, v223, v223
	v_fmac_f32_e32 v2, v12, v12
	v_fmac_f32_e32 v3, v14, v14
	v_fmac_f32_e32 v13, v4, v4
	v_fmac_f32_e32 v15, v6, v6
	v_mul_f32_e32 v253, v11, v11
	v_mul_f32_e32 v255, v221, v221
	v_fmac_f32_e32 v252, v8, v8
	v_fmac_f32_e32 v254, v222, v222
	v_add_f32_e32 v2, v2, v3
	v_add_f32_e32 v3, v13, v15
	v_fmac_f32_e32 v253, v10, v10
	v_fmac_f32_e32 v255, v220, v220
	v_add_f32_e32 v2, v252, v2
	v_add_f32_e32 v3, v254, v3
	v_add_f32_e32 v2, v253, v2
	v_add_f32_e32 v3, v255, v3
	v_add_f32_e32 v12, v2, v3
	ds_bpermute_b32 v13, v156, v12
	v_cvt_pk_bf16_f32 v2, v8, v9
	v_cvt_pk_bf16_f32 v3, v10, v11
	global_store_dwordx4 v[26:27], v[0:3], off
	s_waitcnt lgkmcnt(0)
	s_nop 0
	v_add_f32_e32 v0, v12, v13
	ds_bpermute_b32 v1, v155, v0
	v_cvt_pk_bf16_f32 v2, v4, v5
	v_cvt_pk_bf16_f32 v3, v6, v7
	v_cvt_pk_bf16_f32 v4, v222, v223
	v_cvt_pk_bf16_f32 v5, v220, v221
	global_store_dwordx4 v[26:27], v[2:5], off offset:256
	s_and_saveexec_b64 s[20:21], s[2:3]
	s_cbranch_execz .LBB0_1176
	v_lshl_add_u64 v[2:3], v[16:17], 2, s[8:9]
	s_waitcnt lgkmcnt(0)
	v_add_f32_e32 v0, v0, v1
	global_atomic_add_f32 v[2:3], v0, off
	s_branch .LBB0_1176

.LBB0_1271:
	ds_read_b128 v[144:147], v155
	ds_read_b128 v[148:151], v155 offset:1024
	ds_read_b128 v[160:163], v155 offset:2048
	ds_read_b128 v[164:167], v155 offset:3072
	s_add_u32 s30, s0, 0xfff80080
	s_addc_u32 s31, s1, -1
	s_cmp_eq_u32 s60, 28
	s_cselect_b32 s35, s23, s31
	s_cselect_b32 s34, s56, s30
	s_cselect_b32 s31, s21, s59
	s_cselect_b32 s30, s57, s58
	v_lshl_add_u64 v[168:169], s[0:1], 0, v[136:137]
	s_add_i32 m0, s29, 0xc000
	ds_read_b128 v[172:175], v156
	ds_read_b128 v[176:179], v156 offset:1024
	ds_read_b128 v[180:183], v156 offset:2048
	ds_read_b128 v[184:187], v156 offset:3072
	ds_read_b128 v[188:191], v156 offset:4096
	ds_read_b128 v[192:195], v156 offset:5120
	ds_read_b128 v[196:199], v156 offset:6144
	ds_read_b128 v[200:203], v156 offset:7168
	global_load_lds_dwordx4 v[168:169], off
	v_lshl_add_u64 v[168:169], s[0:1], 0, v[138:139]
	s_add_i32 m0, s29, 0xe000
	s_nop 0
	global_load_lds_dwordx4 v[168:169], off
	s_waitcnt lgkmcnt(8)
	s_barrier
	s_waitcnt lgkmcnt(0)
	s_setprio 1
	s_waitcnt lgkmcnt(0)
	v_mfma_f32_16x16x32_bf16 v[124:127], v[144:147], v[172:175], v[124:127]
	v_mfma_f32_16x16x32_bf16 v[120:123], v[160:163], v[172:175], v[120:123]
	v_mfma_f32_16x16x32_bf16 v[108:111], v[144:147], v[180:183], v[108:111]
	v_mfma_f32_16x16x32_bf16 v[104:107], v[160:163], v[180:183], v[104:107]
	v_mfma_f32_16x16x32_bf16 v[92:95], v[144:147], v[188:191], v[92:95]
	v_mfma_f32_16x16x32_bf16 v[88:91], v[160:163], v[188:191], v[88:91]
	v_mfma_f32_16x16x32_bf16 v[76:79], v[144:147], v[196:199], v[76:79]
	v_mfma_f32_16x16x32_bf16 v[72:75], v[160:163], v[196:199], v[72:75]
	v_mfma_f32_16x16x32_bf16 v[124:127], v[148:151], v[176:179], v[124:127]
	v_mfma_f32_16x16x32_bf16 v[120:123], v[164:167], v[176:179], v[120:123]
	v_mfma_f32_16x16x32_bf16 v[108:111], v[148:151], v[184:187], v[108:111]
	v_mfma_f32_16x16x32_bf16 v[104:107], v[164:167], v[184:187], v[104:107]
	v_mfma_f32_16x16x32_bf16 v[92:95], v[148:151], v[192:195], v[92:95]
	v_mfma_f32_16x16x32_bf16 v[88:91], v[164:167], v[192:195], v[88:91]
	v_mfma_f32_16x16x32_bf16 v[76:79], v[148:151], v[200:203], v[76:79]
	v_mfma_f32_16x16x32_bf16 v[72:75], v[164:167], v[200:203], v[72:75]
	s_setprio 0
	s_barrier
	s_add_i32 s61, s48, s38
	v_lshl_add_u64 v[168:169], s[30:31], 0, v[130:131]
	s_mov_b32 m0, s61
	ds_read_b128 v[204:207], v157
	ds_read_b128 v[208:211], v157 offset:1024
	ds_read_b128 v[212:215], v157 offset:2048
	ds_read_b128 v[216:219], v157 offset:3072
	global_load_lds_dwordx4 v[168:169], off
	v_lshl_add_u64 v[220:221], s[30:31], 0, v[134:135]
	s_add_i32 m0, s61, 0x2000
	s_nop 0
	global_load_lds_dwordx4 v[220:221], off
	s_barrier
	s_waitcnt lgkmcnt(0)
	s_setprio 1
	s_waitcnt lgkmcnt(0)
	v_mfma_f32_16x16x32_bf16 v[116:119], v[204:207], v[172:175], v[116:119]
	v_mfma_f32_16x16x32_bf16 v[112:115], v[212:215], v[172:175], v[112:115]
	v_mfma_f32_16x16x32_bf16 v[100:103], v[204:207], v[180:183], v[100:103]
	v_mfma_f32_16x16x32_bf16 v[96:99], v[212:215], v[180:183], v[96:99]
	v_mfma_f32_16x16x32_bf16 v[84:87], v[204:207], v[188:191], v[84:87]
	v_mfma_f32_16x16x32_bf16 v[80:83], v[212:215], v[188:191], v[80:83]
	v_mfma_f32_16x16x32_bf16 v[68:71], v[204:207], v[196:199], v[68:71]
	v_mfma_f32_16x16x32_bf16 v[64:67], v[212:215], v[196:199], v[64:67]
	v_mfma_f32_16x16x32_bf16 v[116:119], v[208:211], v[176:179], v[116:119]
	v_mfma_f32_16x16x32_bf16 v[112:115], v[216:219], v[176:179], v[112:115]
	v_mfma_f32_16x16x32_bf16 v[100:103], v[208:211], v[184:187], v[100:103]
	v_mfma_f32_16x16x32_bf16 v[96:99], v[216:219], v[184:187], v[96:99]
	v_mfma_f32_16x16x32_bf16 v[84:87], v[208:211], v[192:195], v[84:87]
	v_mfma_f32_16x16x32_bf16 v[80:83], v[216:219], v[192:195], v[80:83]
	v_mfma_f32_16x16x32_bf16 v[68:71], v[208:211], v[200:203], v[68:71]
	v_mfma_f32_16x16x32_bf16 v[64:67], v[216:219], v[200:203], v[64:67]
	s_setprio 0
	s_mov_b32 m0, s29
	v_lshl_add_u64 v[222:223], s[34:35], 0, v[128:129]
	s_barrier
	ds_read_b128 v[172:175], v156 offset:16384
	ds_read_b128 v[176:179], v156 offset:17408
	ds_read_b128 v[180:183], v156 offset:18432
	ds_read_b128 v[184:187], v156 offset:19456
	ds_read_b128 v[188:191], v156 offset:20480
	ds_read_b128 v[192:195], v156 offset:21504
	ds_read_b128 v[196:199], v156 offset:22528
	ds_read_b128 v[200:203], v156 offset:23552
	global_load_lds_dwordx4 v[222:223], off
	v_lshl_add_u64 v[224:225], s[34:35], 0, v[132:133]
	s_mov_b32 m0, s40
	s_nop 0
	global_load_lds_dwordx4 v[224:225], off
	s_barrier
	s_waitcnt lgkmcnt(0)
	s_setprio 1
	s_waitcnt lgkmcnt(0)
	v_mfma_f32_16x16x32_bf16 v[60:63], v[144:147], v[172:175], v[60:63]
	v_mfma_f32_16x16x32_bf16 v[56:59], v[160:163], v[172:175], v[56:59]
	v_mfma_f32_16x16x32_bf16 v[44:47], v[144:147], v[180:183], v[44:47]
	v_mfma_f32_16x16x32_bf16 v[40:43], v[160:163], v[180:183], v[40:43]
	v_mfma_f32_16x16x32_bf16 v[28:31], v[144:147], v[188:191], v[28:31]
	v_mfma_f32_16x16x32_bf16 v[24:27], v[160:163], v[188:191], v[24:27]
	v_mfma_f32_16x16x32_bf16 v[12:15], v[144:147], v[196:199], v[12:15]
	v_mfma_f32_16x16x32_bf16 v[8:11], v[160:163], v[196:199], v[8:11]
	v_mfma_f32_16x16x32_bf16 v[60:63], v[148:151], v[176:179], v[60:63]
	v_mfma_f32_16x16x32_bf16 v[56:59], v[164:167], v[176:179], v[56:59]
	v_mfma_f32_16x16x32_bf16 v[44:47], v[148:151], v[184:187], v[44:47]
	v_mfma_f32_16x16x32_bf16 v[40:43], v[164:167], v[184:187], v[40:43]
	v_mfma_f32_16x16x32_bf16 v[28:31], v[148:151], v[192:195], v[28:31]
	v_mfma_f32_16x16x32_bf16 v[24:27], v[164:167], v[192:195], v[24:27]
	v_mfma_f32_16x16x32_bf16 v[12:15], v[148:151], v[200:203], v[12:15]
	v_mfma_f32_16x16x32_bf16 v[8:11], v[164:167], v[200:203], v[8:11]
	s_setprio 0
	s_barrier
	s_add_u32 s62, s30, 0x80000
	s_addc_u32 s63, s31, 0
	s_add_i32 s61, s49, s38
	v_lshl_add_u64 v[144:145], s[62:63], 0, v[130:131]
	s_mov_b32 m0, s61
	s_nop 0
	global_load_lds_dwordx4 v[144:145], off
	v_lshl_add_u64 v[144:145], s[62:63], 0, v[134:135]
	s_add_i32 m0, s61, 0x2000
	s_nop 0
	global_load_lds_dwordx4 v[144:145], off
	s_waitcnt vmcnt(6)
	s_barrier
	s_setprio 1
	v_mfma_f32_16x16x32_bf16 v[52:55], v[204:207], v[172:175], v[52:55]
	v_mfma_f32_16x16x32_bf16 v[48:51], v[212:215], v[172:175], v[48:51]
	v_mfma_f32_16x16x32_bf16 v[36:39], v[204:207], v[180:183], v[36:39]
	v_mfma_f32_16x16x32_bf16 v[32:35], v[212:215], v[180:183], v[32:35]
	v_mfma_f32_16x16x32_bf16 v[20:23], v[204:207], v[188:191], v[20:23]
	v_mfma_f32_16x16x32_bf16 v[16:19], v[212:215], v[188:191], v[16:19]
	v_mfma_f32_16x16x32_bf16 v[4:7], v[204:207], v[196:199], v[4:7]
	v_mfma_f32_16x16x32_bf16 v[0:3], v[212:215], v[196:199], v[0:3]
	v_mfma_f32_16x16x32_bf16 v[52:55], v[208:211], v[176:179], v[52:55]
	v_mfma_f32_16x16x32_bf16 v[48:51], v[216:219], v[176:179], v[48:51]
	v_mfma_f32_16x16x32_bf16 v[36:39], v[208:211], v[184:187], v[36:39]
	v_mfma_f32_16x16x32_bf16 v[32:35], v[216:219], v[184:187], v[32:35]
	v_mfma_f32_16x16x32_bf16 v[20:23], v[208:211], v[192:195], v[20:23]
	v_mfma_f32_16x16x32_bf16 v[16:19], v[216:219], v[192:195], v[16:19]
	v_mfma_f32_16x16x32_bf16 v[4:7], v[208:211], v[200:203], v[4:7]
	v_mfma_f32_16x16x32_bf16 v[0:3], v[216:219], v[200:203], v[0:3]
	s_setprio 0
	s_add_i32 s61, 0, 0x18000
	v_add_u32_e32 v159, s61, v153
	s_barrier
	ds_read_b128 v[144:147], v159
	ds_read_b128 v[148:151], v159 offset:1024
	ds_read_b128 v[160:163], v159 offset:2048
	ds_read_b128 v[164:167], v159 offset:3072
	s_add_u32 s34, s34, 0x80000
	s_addc_u32 s35, s35, 0
	s_mov_b32 m0, s41
	v_lshl_add_u64 v[204:205], s[34:35], 0, v[128:129]
	ds_read_b128 v[172:175], v156 offset:32768
	ds_read_b128 v[176:179], v156 offset:33792
	ds_read_b128 v[180:183], v156 offset:34816
	ds_read_b128 v[184:187], v156 offset:35840
	ds_read_b128 v[188:191], v156 offset:36864
	ds_read_b128 v[192:195], v156 offset:37888
	ds_read_b128 v[196:199], v156 offset:38912
	ds_read_b128 v[200:203], v156 offset:39936
	global_load_lds_dwordx4 v[204:205], off
	v_lshl_add_u64 v[204:205], s[34:35], 0, v[132:133]
	s_mov_b32 m0, s42
	s_nop 0
	global_load_lds_dwordx4 v[204:205], off
	s_waitcnt lgkmcnt(8)
	s_barrier
	s_waitcnt lgkmcnt(0)
	s_setprio 1
	s_waitcnt lgkmcnt(0)
	v_mfma_f32_16x16x32_bf16 v[124:127], v[144:147], v[172:175], v[124:127]
	v_mfma_f32_16x16x32_bf16 v[120:123], v[160:163], v[172:175], v[120:123]
	v_mfma_f32_16x16x32_bf16 v[108:111], v[144:147], v[180:183], v[108:111]
	v_mfma_f32_16x16x32_bf16 v[104:107], v[160:163], v[180:183], v[104:107]
	v_mfma_f32_16x16x32_bf16 v[92:95], v[144:147], v[188:191], v[92:95]
	v_mfma_f32_16x16x32_bf16 v[88:91], v[160:163], v[188:191], v[88:91]
	v_mfma_f32_16x16x32_bf16 v[76:79], v[144:147], v[196:199], v[76:79]
	v_mfma_f32_16x16x32_bf16 v[72:75], v[160:163], v[196:199], v[72:75]
	v_mfma_f32_16x16x32_bf16 v[124:127], v[148:151], v[176:179], v[124:127]
	v_mfma_f32_16x16x32_bf16 v[120:123], v[164:167], v[176:179], v[120:123]
	v_mfma_f32_16x16x32_bf16 v[108:111], v[148:151], v[184:187], v[108:111]
	v_mfma_f32_16x16x32_bf16 v[104:107], v[164:167], v[184:187], v[104:107]
	v_mfma_f32_16x16x32_bf16 v[92:95], v[148:151], v[192:195], v[92:95]
	v_mfma_f32_16x16x32_bf16 v[88:91], v[164:167], v[192:195], v[88:91]
	v_mfma_f32_16x16x32_bf16 v[76:79], v[148:151], v[200:203], v[76:79]
	v_mfma_f32_16x16x32_bf16 v[72:75], v[164:167], v[200:203], v[72:75]
	s_setprio 0
	s_barrier
	s_add_i32 s34, 0, 0x1c000
	s_add_i32 s35, s61, s38
	v_add_u32_e32 v159, s34, v153
	v_lshl_add_u64 v[168:169], v[168:169], 0, s[10:11]
	s_mov_b32 m0, s35
	ds_read_b128 v[204:207], v159
	ds_read_b128 v[208:211], v159 offset:1024
	ds_read_b128 v[212:215], v159 offset:2048
	ds_read_b128 v[216:219], v159 offset:3072
	global_load_lds_dwordx4 v[168:169], off
	v_lshl_add_u64 v[168:169], v[220:221], 0, s[10:11]
	s_add_i32 m0, s35, 0x2000
	s_nop 0
	global_load_lds_dwordx4 v[168:169], off
	s_barrier
	s_waitcnt lgkmcnt(0)
	s_setprio 1
	s_waitcnt lgkmcnt(0)
	v_mfma_f32_16x16x32_bf16 v[116:119], v[204:207], v[172:175], v[116:119]
	v_mfma_f32_16x16x32_bf16 v[112:115], v[212:215], v[172:175], v[112:115]
	v_mfma_f32_16x16x32_bf16 v[100:103], v[204:207], v[180:183], v[100:103]
	v_mfma_f32_16x16x32_bf16 v[96:99], v[212:215], v[180:183], v[96:99]
	v_mfma_f32_16x16x32_bf16 v[84:87], v[204:207], v[188:191], v[84:87]
	v_mfma_f32_16x16x32_bf16 v[80:83], v[212:215], v[188:191], v[80:83]
	v_mfma_f32_16x16x32_bf16 v[68:71], v[204:207], v[196:199], v[68:71]
	v_mfma_f32_16x16x32_bf16 v[64:67], v[212:215], v[196:199], v[64:67]
	v_mfma_f32_16x16x32_bf16 v[116:119], v[208:211], v[176:179], v[116:119]
	v_mfma_f32_16x16x32_bf16 v[112:115], v[216:219], v[176:179], v[112:115]
	v_mfma_f32_16x16x32_bf16 v[100:103], v[208:211], v[184:187], v[100:103]
	v_mfma_f32_16x16x32_bf16 v[96:99], v[216:219], v[184:187], v[96:99]
	v_mfma_f32_16x16x32_bf16 v[84:87], v[208:211], v[192:195], v[84:87]
	v_mfma_f32_16x16x32_bf16 v[80:83], v[216:219], v[192:195], v[80:83]
	v_mfma_f32_16x16x32_bf16 v[68:71], v[208:211], v[200:203], v[68:71]
	v_mfma_f32_16x16x32_bf16 v[64:67], v[216:219], v[200:203], v[64:67]
	s_setprio 0
	s_mov_b32 m0, s45
	v_lshl_add_u64 v[168:169], v[222:223], 0, s[10:11]
	s_barrier
	ds_read_b128 v[172:175], v156 offset:49152
	ds_read_b128 v[176:179], v156 offset:50176
	ds_read_b128 v[180:183], v156 offset:51200
	ds_read_b128 v[184:187], v156 offset:52224
	ds_read_b128 v[188:191], v156 offset:53248
	ds_read_b128 v[192:195], v156 offset:54272
	ds_read_b128 v[196:199], v156 offset:55296
	ds_read_b128 v[200:203], v156 offset:56320
	global_load_lds_dwordx4 v[168:169], off
	v_lshl_add_u64 v[168:169], v[224:225], 0, s[10:11]
	s_mov_b32 m0, s46
	s_nop 0
	global_load_lds_dwordx4 v[168:169], off
	s_barrier
	s_waitcnt lgkmcnt(0)
	s_setprio 1
	s_waitcnt lgkmcnt(0)
	v_mfma_f32_16x16x32_bf16 v[60:63], v[144:147], v[172:175], v[60:63]
	v_mfma_f32_16x16x32_bf16 v[56:59], v[160:163], v[172:175], v[56:59]
	v_mfma_f32_16x16x32_bf16 v[44:47], v[144:147], v[180:183], v[44:47]
	v_mfma_f32_16x16x32_bf16 v[40:43], v[160:163], v[180:183], v[40:43]
	v_mfma_f32_16x16x32_bf16 v[28:31], v[144:147], v[188:191], v[28:31]
	v_mfma_f32_16x16x32_bf16 v[24:27], v[160:163], v[188:191], v[24:27]
	v_mfma_f32_16x16x32_bf16 v[12:15], v[144:147], v[196:199], v[12:15]
	v_mfma_f32_16x16x32_bf16 v[8:11], v[160:163], v[196:199], v[8:11]
	v_mfma_f32_16x16x32_bf16 v[60:63], v[148:151], v[176:179], v[60:63]
	v_mfma_f32_16x16x32_bf16 v[56:59], v[164:167], v[176:179], v[56:59]
	v_mfma_f32_16x16x32_bf16 v[44:47], v[148:151], v[184:187], v[44:47]
	v_mfma_f32_16x16x32_bf16 v[40:43], v[164:167], v[184:187], v[40:43]
	v_mfma_f32_16x16x32_bf16 v[28:31], v[148:151], v[192:195], v[28:31]
	v_mfma_f32_16x16x32_bf16 v[24:27], v[164:167], v[192:195], v[24:27]
	v_mfma_f32_16x16x32_bf16 v[12:15], v[148:151], v[200:203], v[12:15]
	v_mfma_f32_16x16x32_bf16 v[8:11], v[164:167], v[200:203], v[8:11]
	s_setprio 0
	s_barrier
	s_add_u32 s30, s30, 0x80080
	s_addc_u32 s31, s31, 0
	s_add_i32 s34, s34, s38
	v_lshl_add_u64 v[144:145], s[30:31], 0, v[130:131]
	s_mov_b32 m0, s34
	s_nop 0
	global_load_lds_dwordx4 v[144:145], off
	v_lshl_add_u64 v[144:145], s[30:31], 0, v[134:135]
	s_add_i32 m0, s34, 0x2000
	s_nop 0
	global_load_lds_dwordx4 v[144:145], off
	s_waitcnt vmcnt(6)
	s_barrier
	s_setprio 1
	v_mfma_f32_16x16x32_bf16 v[52:55], v[204:207], v[172:175], v[52:55]
	v_mfma_f32_16x16x32_bf16 v[48:51], v[212:215], v[172:175], v[48:51]
	v_mfma_f32_16x16x32_bf16 v[36:39], v[204:207], v[180:183], v[36:39]
	v_mfma_f32_16x16x32_bf16 v[32:35], v[212:215], v[180:183], v[32:35]
	v_mfma_f32_16x16x32_bf16 v[20:23], v[204:207], v[188:191], v[20:23]
	v_mfma_f32_16x16x32_bf16 v[16:19], v[212:215], v[188:191], v[16:19]
	v_mfma_f32_16x16x32_bf16 v[4:7], v[204:207], v[196:199], v[4:7]
	v_mfma_f32_16x16x32_bf16 v[0:3], v[212:215], v[196:199], v[0:3]
	v_mfma_f32_16x16x32_bf16 v[52:55], v[208:211], v[176:179], v[52:55]
	v_mfma_f32_16x16x32_bf16 v[48:51], v[216:219], v[176:179], v[48:51]
	v_mfma_f32_16x16x32_bf16 v[36:39], v[208:211], v[184:187], v[36:39]
	v_mfma_f32_16x16x32_bf16 v[32:35], v[216:219], v[184:187], v[32:35]
	v_mfma_f32_16x16x32_bf16 v[20:23], v[208:211], v[192:195], v[20:23]
	v_mfma_f32_16x16x32_bf16 v[16:19], v[216:219], v[192:195], v[16:19]
	v_mfma_f32_16x16x32_bf16 v[4:7], v[208:211], v[200:203], v[4:7]
	v_mfma_f32_16x16x32_bf16 v[0:3], v[216:219], v[200:203], v[0:3]
	s_setprio 0
	s_add_i32 s60, s60, 2
	s_add_u32 s0, s0, 0x100
	s_addc_u32 s1, s1, 0
	s_add_u32 s58, s58, 0x100
	s_addc_u32 s59, s59, 0
	s_cmp_gt_u32 s60, 29
	s_barrier
	s_cbranch_scc0 .LBB0_1271
	v_lshl_add_u32 v148, s28, 8, v152
	v_ashrrev_i32_e32 v149, 31, v148
	v_lshl_add_u64 v[146:147], v[148:149], 2, s[8:9]
	global_load_dword v236, v[146:147], off
	global_load_dword v237, v[146:147], off offset:64
	global_load_dword v238, v[146:147], off offset:128
	global_load_dword v239, v[146:147], off offset:192
	global_load_dword v240, v[146:147], off offset:512
	global_load_dword v241, v[146:147], off offset:576
	global_load_dword v242, v[146:147], off offset:640
	global_load_dword v243, v[146:147], off offset:704
	v_lshl_or_b32 v144, s55, 8, v154
	v_ashrrev_i32_e32 v145, 31, v144
	v_lshlrev_b64 v[150:151], 1, v[144:145]
	v_lshlrev_b64 v[162:163], 14, v[148:149]
	v_or_b32_e32 v160, 16, v148
	v_ashrrev_i32_e32 v161, 31, v160
	s_mov_b32 s55, s20
	s_mov_b32 s28, s22
	s_mov_b64 s[30:31], s[26:27]
	s_mov_b64 s[34:35], s[24:25]
	s_waitcnt vmcnt(7)
	v_fmamk_f32 v144, v236, 0x3a000000, v158
	v_mul_f32_e32 v145, 0x4b800000, v144
	v_cmp_gt_f32_e32 vcc, s50, v144
	s_nop 1
	v_cndmask_b32_e32 v144, v144, v145, vcc
	v_rsq_f32_e32 v149, v144
	v_lshl_add_u64 v[144:145], s[68:69], 0, v[162:163]
	v_lshl_add_u64 v[144:145], v[144:145], 0, v[150:151]
	v_lshl_add_u64 v[162:163], v[160:161], 2, s[8:9]
	v_mul_f32_e32 v159, 0x45800000, v149
	v_cndmask_b32_e32 v164, v149, v159, vcc
	v_pk_mul_f32 v[126:127], v[126:127], v[164:165] op_sel_hi:[1,0]
	v_pk_mul_f32 v[124:125], v[124:125], v[164:165] op_sel_hi:[1,0]
	v_pk_mul_f32 v[122:123], v[122:123], v[164:165] op_sel_hi:[1,0]
	v_pk_mul_f32 v[120:121], v[120:121], v[164:165] op_sel_hi:[1,0]
	v_pk_mul_f32 v[118:119], v[118:119], v[164:165] op_sel_hi:[1,0]
	v_pk_mul_f32 v[116:117], v[116:117], v[164:165] op_sel_hi:[1,0]
	v_pk_mul_f32 v[114:115], v[114:115], v[164:165] op_sel_hi:[1,0]
	v_pk_mul_f32 v[112:113], v[112:113], v[164:165] op_sel_hi:[1,0]
	v_max_f32_e32 v124, 0, v124
	v_max_f32_e32 v120, 0, v120
	v_max_f32_e32 v125, 0, v125
	v_max_f32_e32 v121, 0, v121
	v_max_f32_e32 v126, 0, v126
	v_max_f32_e32 v122, 0, v122
	v_max_f32_e32 v127, 0, v127
	v_max_f32_e32 v123, 0, v123
	v_max_f32_e32 v116, 0, v116
	v_max_f32_e32 v112, 0, v112
	v_max_f32_e32 v117, 0, v117
	v_max_f32_e32 v113, 0, v113
	v_max_f32_e32 v118, 0, v118
	v_max_f32_e32 v114, 0, v114
	v_max_f32_e32 v119, 0, v119
	v_max_f32_e32 v115, 0, v115
	v_mul_f32_e32 v124, v124, v124
	v_mul_f32_e32 v120, v120, v120
	v_mul_f32_e32 v125, v125, v125
	v_mul_f32_e32 v121, v121, v121
	v_mul_f32_e32 v126, v126, v126
	v_mul_f32_e32 v122, v122, v122
	v_mul_f32_e32 v127, v127, v127
	v_mul_f32_e32 v123, v123, v123
	v_mul_f32_e32 v116, v116, v116
	v_mul_f32_e32 v149, v112, v112
	v_mul_f32_e32 v117, v117, v117
	v_mul_f32_e32 v159, v113, v113
	v_mul_f32_e32 v118, v118, v118
	v_mul_f32_e32 v164, v114, v114
	v_mul_f32_e32 v119, v119, v119
	v_mul_f32_e32 v165, v115, v115
	v_cvt_pk_bf16_f32 v112, v124, v125
	v_cvt_pk_bf16_f32 v113, v126, v127
	v_cvt_pk_bf16_f32 v114, v120, v121
	v_cvt_pk_bf16_f32 v115, v122, v123
	v_cvt_pk_bf16_f32 v116, v116, v117
	v_cvt_pk_bf16_f32 v117, v118, v119
	v_cvt_pk_bf16_f32 v118, v149, v159
	v_cvt_pk_bf16_f32 v119, v164, v165
	global_store_dwordx4 v[144:145], v[112:115], off
	global_store_dwordx4 v[144:145], v[116:119], off offset:256
	v_lshlrev_b64 v[114:115], 14, v[160:161]
	v_or_b32_e32 v112, 32, v148
	v_lshl_add_u64 v[114:115], s[68:69], 0, v[114:115]
	v_ashrrev_i32_e32 v113, 31, v112
	v_lshl_add_u64 v[114:115], v[114:115], 0, v[150:151]
	s_waitcnt vmcnt(8)
	v_fmamk_f32 v116, v237, 0x3a000000, v158
	v_mul_f32_e32 v117, 0x4b800000, v116
	v_cmp_gt_f32_e32 vcc, s50, v116
	s_nop 1
	v_cndmask_b32_e32 v116, v116, v117, vcc
	v_rsq_f32_e32 v118, v116
	v_lshl_add_u64 v[116:117], v[112:113], 2, s[8:9]
	v_mul_f32_e32 v119, 0x45800000, v118
	v_cndmask_b32_e32 v118, v118, v119, vcc
	v_pk_mul_f32 v[110:111], v[110:111], v[118:119] op_sel_hi:[1,0]
	v_pk_mul_f32 v[108:109], v[108:109], v[118:119] op_sel_hi:[1,0]
	v_pk_mul_f32 v[106:107], v[106:107], v[118:119] op_sel_hi:[1,0]
	v_pk_mul_f32 v[104:105], v[104:105], v[118:119] op_sel_hi:[1,0]
	v_pk_mul_f32 v[102:103], v[102:103], v[118:119] op_sel_hi:[1,0]
	v_pk_mul_f32 v[100:101], v[100:101], v[118:119] op_sel_hi:[1,0]
	v_pk_mul_f32 v[98:99], v[98:99], v[118:119] op_sel_hi:[1,0]
	v_pk_mul_f32 v[96:97], v[96:97], v[118:119] op_sel_hi:[1,0]
	v_max_f32_e32 v108, 0, v108
	v_max_f32_e32 v104, 0, v104
	v_max_f32_e32 v109, 0, v109
	v_max_f32_e32 v105, 0, v105
	v_max_f32_e32 v110, 0, v110
	v_max_f32_e32 v106, 0, v106
	v_max_f32_e32 v111, 0, v111
	v_max_f32_e32 v107, 0, v107
	v_max_f32_e32 v100, 0, v100
	v_max_f32_e32 v96, 0, v96
	v_max_f32_e32 v101, 0, v101
	v_max_f32_e32 v97, 0, v97
	v_max_f32_e32 v102, 0, v102
	v_max_f32_e32 v98, 0, v98
	v_max_f32_e32 v103, 0, v103
	v_max_f32_e32 v99, 0, v99
	v_mul_f32_e32 v108, v108, v108
	v_mul_f32_e32 v104, v104, v104
	v_mul_f32_e32 v109, v109, v109
	v_mul_f32_e32 v105, v105, v105
	v_mul_f32_e32 v110, v110, v110
	v_mul_f32_e32 v106, v106, v106
	v_mul_f32_e32 v111, v111, v111
	v_mul_f32_e32 v107, v107, v107
	v_mul_f32_e32 v100, v100, v100
	v_mul_f32_e32 v118, v96, v96
	v_mul_f32_e32 v101, v101, v101
	v_mul_f32_e32 v119, v97, v97
	v_mul_f32_e32 v102, v102, v102
	v_mul_f32_e32 v120, v98, v98
	v_mul_f32_e32 v103, v103, v103
	v_mul_f32_e32 v121, v99, v99
	v_cvt_pk_bf16_f32 v96, v108, v109
	v_cvt_pk_bf16_f32 v97, v110, v111
	v_cvt_pk_bf16_f32 v98, v104, v105
	v_cvt_pk_bf16_f32 v99, v106, v107
	v_cvt_pk_bf16_f32 v100, v100, v101
	v_cvt_pk_bf16_f32 v101, v102, v103
	v_cvt_pk_bf16_f32 v102, v118, v119
	v_cvt_pk_bf16_f32 v103, v120, v121
	global_store_dwordx4 v[114:115], v[96:99], off
	global_store_dwordx4 v[114:115], v[100:103], off offset:256
	v_lshlrev_b64 v[98:99], 14, v[112:113]
	v_or_b32_e32 v96, 48, v148
	v_lshl_add_u64 v[98:99], s[68:69], 0, v[98:99]
	v_ashrrev_i32_e32 v97, 31, v96
	v_lshl_add_u64 v[98:99], v[98:99], 0, v[150:151]
	s_waitcnt vmcnt(9)
	v_fmamk_f32 v100, v238, 0x3a000000, v158
	v_mul_f32_e32 v101, 0x4b800000, v100
	v_cmp_gt_f32_e32 vcc, s50, v100
	s_nop 1
	v_cndmask_b32_e32 v100, v100, v101, vcc
	v_rsq_f32_e32 v102, v100
	v_lshl_add_u64 v[100:101], v[96:97], 2, s[8:9]
	v_mul_f32_e32 v103, 0x45800000, v102
	v_cndmask_b32_e32 v102, v102, v103, vcc
	v_pk_mul_f32 v[94:95], v[94:95], v[102:103] op_sel_hi:[1,0]
	v_pk_mul_f32 v[92:93], v[92:93], v[102:103] op_sel_hi:[1,0]
	v_pk_mul_f32 v[90:91], v[90:91], v[102:103] op_sel_hi:[1,0]
	v_pk_mul_f32 v[88:89], v[88:89], v[102:103] op_sel_hi:[1,0]
	v_pk_mul_f32 v[86:87], v[86:87], v[102:103] op_sel_hi:[1,0]
	v_pk_mul_f32 v[84:85], v[84:85], v[102:103] op_sel_hi:[1,0]
	v_pk_mul_f32 v[82:83], v[82:83], v[102:103] op_sel_hi:[1,0]
	v_pk_mul_f32 v[80:81], v[80:81], v[102:103] op_sel_hi:[1,0]
	v_max_f32_e32 v92, 0, v92
	v_max_f32_e32 v88, 0, v88
	v_max_f32_e32 v93, 0, v93
	v_max_f32_e32 v89, 0, v89
	v_max_f32_e32 v94, 0, v94
	v_max_f32_e32 v90, 0, v90
	v_max_f32_e32 v95, 0, v95
	v_max_f32_e32 v91, 0, v91
	v_max_f32_e32 v84, 0, v84
	v_max_f32_e32 v80, 0, v80
	v_max_f32_e32 v85, 0, v85
	v_max_f32_e32 v81, 0, v81
	v_max_f32_e32 v86, 0, v86
	v_max_f32_e32 v82, 0, v82
	v_max_f32_e32 v87, 0, v87
	v_max_f32_e32 v83, 0, v83
	v_mul_f32_e32 v92, v92, v92
	v_mul_f32_e32 v88, v88, v88
	v_mul_f32_e32 v93, v93, v93
	v_mul_f32_e32 v89, v89, v89
	v_mul_f32_e32 v94, v94, v94
	v_mul_f32_e32 v90, v90, v90
	v_mul_f32_e32 v95, v95, v95
	v_mul_f32_e32 v91, v91, v91
	v_mul_f32_e32 v84, v84, v84
	v_mul_f32_e32 v102, v80, v80
	v_mul_f32_e32 v85, v85, v85
	v_mul_f32_e32 v103, v81, v81
	v_mul_f32_e32 v86, v86, v86
	v_mul_f32_e32 v104, v82, v82
	v_mul_f32_e32 v87, v87, v87
	v_mul_f32_e32 v105, v83, v83
	v_cvt_pk_bf16_f32 v80, v92, v93
	v_cvt_pk_bf16_f32 v81, v94, v95
	v_cvt_pk_bf16_f32 v82, v88, v89
	v_cvt_pk_bf16_f32 v83, v90, v91
	v_cvt_pk_bf16_f32 v84, v84, v85
	v_cvt_pk_bf16_f32 v85, v86, v87
	v_cvt_pk_bf16_f32 v86, v102, v103
	v_cvt_pk_bf16_f32 v87, v104, v105
	global_store_dwordx4 v[98:99], v[80:83], off
	global_store_dwordx4 v[98:99], v[84:87], off offset:256
	s_waitcnt vmcnt(10)
	v_fmamk_f32 v80, v239, 0x3a000000, v158
	v_mul_f32_e32 v81, 0x4b800000, v80
	v_cmp_gt_f32_e32 vcc, s50, v80
	s_nop 1
	v_cndmask_b32_e32 v80, v80, v81, vcc
	v_rsq_f32_e32 v82, v80
	v_lshlrev_b64 v[80:81], 14, v[96:97]
	v_lshl_add_u64 v[80:81], s[68:69], 0, v[80:81]
	v_lshl_add_u64 v[80:81], v[80:81], 0, v[150:151]
	v_mul_f32_e32 v83, 0x45800000, v82
	v_cndmask_b32_e32 v82, v82, v83, vcc
	v_pk_mul_f32 v[78:79], v[78:79], v[82:83] op_sel_hi:[1,0]
	v_pk_mul_f32 v[76:77], v[76:77], v[82:83] op_sel_hi:[1,0]
	v_pk_mul_f32 v[74:75], v[74:75], v[82:83] op_sel_hi:[1,0]
	v_pk_mul_f32 v[72:73], v[72:73], v[82:83] op_sel_hi:[1,0]
	v_pk_mul_f32 v[70:71], v[70:71], v[82:83] op_sel_hi:[1,0]
	v_pk_mul_f32 v[68:69], v[68:69], v[82:83] op_sel_hi:[1,0]
	v_pk_mul_f32 v[66:67], v[66:67], v[82:83] op_sel_hi:[1,0]
	v_pk_mul_f32 v[64:65], v[64:65], v[82:83] op_sel_hi:[1,0]
	v_max_f32_e32 v76, 0, v76
	v_max_f32_e32 v72, 0, v72
	v_max_f32_e32 v77, 0, v77
	v_max_f32_e32 v73, 0, v73
	v_max_f32_e32 v78, 0, v78
	v_max_f32_e32 v74, 0, v74
	v_max_f32_e32 v79, 0, v79
	v_max_f32_e32 v75, 0, v75
	v_max_f32_e32 v68, 0, v68
	v_max_f32_e32 v64, 0, v64
	v_max_f32_e32 v69, 0, v69
	v_max_f32_e32 v65, 0, v65
	v_max_f32_e32 v70, 0, v70
	v_max_f32_e32 v66, 0, v66
	v_max_f32_e32 v71, 0, v71
	v_max_f32_e32 v67, 0, v67
	v_mul_f32_e32 v76, v76, v76
	v_mul_f32_e32 v72, v72, v72
	v_mul_f32_e32 v77, v77, v77
	v_mul_f32_e32 v73, v73, v73
	v_mul_f32_e32 v78, v78, v78
	v_mul_f32_e32 v74, v74, v74
	v_mul_f32_e32 v79, v79, v79
	v_mul_f32_e32 v75, v75, v75
	v_mul_f32_e32 v68, v68, v68
	v_mul_f32_e32 v82, v64, v64
	v_mul_f32_e32 v69, v69, v69
	v_mul_f32_e32 v83, v65, v65
	v_mul_f32_e32 v70, v70, v70
	v_mul_f32_e32 v84, v66, v66
	v_mul_f32_e32 v71, v71, v71
	v_mul_f32_e32 v85, v67, v67
	v_cvt_pk_bf16_f32 v64, v76, v77
	v_cvt_pk_bf16_f32 v65, v78, v79
	v_cvt_pk_bf16_f32 v66, v72, v73
	v_cvt_pk_bf16_f32 v67, v74, v75
	v_cvt_pk_bf16_f32 v68, v68, v69
	v_cvt_pk_bf16_f32 v69, v70, v71
	v_cvt_pk_bf16_f32 v70, v82, v83
	v_cvt_pk_bf16_f32 v71, v84, v85
	global_store_dwordx4 v[80:81], v[64:67], off
	global_store_dwordx4 v[80:81], v[68:71], off offset:256
	v_lshl_add_u64 v[64:65], v[144:145], 0, s[12:13]
	s_waitcnt vmcnt(11)
	v_fmamk_f32 v66, v240, 0x3a000000, v158
	v_mul_f32_e32 v67, 0x4b800000, v66
	v_cmp_gt_f32_e32 vcc, s50, v66
	s_nop 1
	v_cndmask_b32_e32 v66, v66, v67, vcc
	v_rsq_f32_e32 v68, v66
	v_add_co_u32_e64 v66, s[0:1], s51, v144
	v_mul_f32_e32 v69, 0x45800000, v68
	v_cndmask_b32_e32 v68, v68, v69, vcc
	v_pk_mul_f32 v[62:63], v[62:63], v[68:69] op_sel_hi:[1,0]
	v_pk_mul_f32 v[60:61], v[60:61], v[68:69] op_sel_hi:[1,0]
	v_pk_mul_f32 v[58:59], v[58:59], v[68:69] op_sel_hi:[1,0]
	v_pk_mul_f32 v[56:57], v[56:57], v[68:69] op_sel_hi:[1,0]
	v_pk_mul_f32 v[54:55], v[54:55], v[68:69] op_sel_hi:[1,0]
	v_pk_mul_f32 v[52:53], v[52:53], v[68:69] op_sel_hi:[1,0]
	v_pk_mul_f32 v[50:51], v[50:51], v[68:69] op_sel_hi:[1,0]
	v_pk_mul_f32 v[48:49], v[48:49], v[68:69] op_sel_hi:[1,0]
	v_max_f32_e32 v60, 0, v60
	v_max_f32_e32 v56, 0, v56
	v_max_f32_e32 v61, 0, v61
	v_max_f32_e32 v57, 0, v57
	v_max_f32_e32 v62, 0, v62
	v_max_f32_e32 v58, 0, v58
	v_max_f32_e32 v63, 0, v63
	v_max_f32_e32 v59, 0, v59
	v_max_f32_e32 v52, 0, v52
	v_max_f32_e32 v48, 0, v48
	v_max_f32_e32 v53, 0, v53
	v_max_f32_e32 v49, 0, v49
	v_max_f32_e32 v54, 0, v54
	v_max_f32_e32 v50, 0, v50
	v_max_f32_e32 v55, 0, v55
	v_max_f32_e32 v51, 0, v51
	v_mul_f32_e32 v60, v60, v60
	v_mul_f32_e32 v56, v56, v56
	v_mul_f32_e32 v61, v61, v61
	v_mul_f32_e32 v57, v57, v57
	v_mul_f32_e32 v62, v62, v62
	v_mul_f32_e32 v58, v58, v58
	v_mul_f32_e32 v63, v63, v63
	v_mul_f32_e32 v59, v59, v59
	v_addc_co_u32_e64 v67, s[0:1], 0, v145, s[0:1]
	v_mul_f32_e32 v52, v52, v52
	v_mul_f32_e32 v68, v48, v48
	v_mul_f32_e32 v53, v53, v53
	v_mul_f32_e32 v69, v49, v49
	v_mul_f32_e32 v54, v54, v54
	v_mul_f32_e32 v70, v50, v50
	v_mul_f32_e32 v55, v55, v55
	v_mul_f32_e32 v71, v51, v51
	v_cvt_pk_bf16_f32 v48, v60, v61
	v_cvt_pk_bf16_f32 v49, v62, v63
	v_cvt_pk_bf16_f32 v50, v56, v57
	v_cvt_pk_bf16_f32 v51, v58, v59
	v_cvt_pk_bf16_f32 v52, v52, v53
	v_cvt_pk_bf16_f32 v53, v54, v55
	v_cvt_pk_bf16_f32 v54, v68, v69
	v_cvt_pk_bf16_f32 v55, v70, v71
	global_store_dwordx4 v[66:67], v[48:51], off
	global_store_dwordx4 v[64:65], v[52:55], off offset:256
	v_lshl_add_u64 v[48:49], v[144:145], 0, s[14:15]
	s_waitcnt vmcnt(12)
	v_fmamk_f32 v50, v241, 0x3a000000, v158
	v_mul_f32_e32 v51, 0x4b800000, v50
	v_cmp_gt_f32_e32 vcc, s50, v50
	s_nop 1
	v_cndmask_b32_e32 v50, v50, v51, vcc
	v_rsq_f32_e32 v52, v50
	v_add_co_u32_e64 v50, s[0:1], s52, v144
	v_mul_f32_e32 v53, 0x45800000, v52
	v_cndmask_b32_e32 v52, v52, v53, vcc
	v_pk_mul_f32 v[46:47], v[46:47], v[52:53] op_sel_hi:[1,0]
	v_pk_mul_f32 v[44:45], v[44:45], v[52:53] op_sel_hi:[1,0]
	v_pk_mul_f32 v[42:43], v[42:43], v[52:53] op_sel_hi:[1,0]
	v_pk_mul_f32 v[40:41], v[40:41], v[52:53] op_sel_hi:[1,0]
	v_pk_mul_f32 v[38:39], v[38:39], v[52:53] op_sel_hi:[1,0]
	v_pk_mul_f32 v[36:37], v[36:37], v[52:53] op_sel_hi:[1,0]
	v_pk_mul_f32 v[34:35], v[34:35], v[52:53] op_sel_hi:[1,0]
	v_pk_mul_f32 v[32:33], v[32:33], v[52:53] op_sel_hi:[1,0]
	v_max_f32_e32 v44, 0, v44
	v_max_f32_e32 v40, 0, v40
	v_max_f32_e32 v45, 0, v45
	v_max_f32_e32 v41, 0, v41
	v_max_f32_e32 v46, 0, v46
	v_max_f32_e32 v42, 0, v42
	v_max_f32_e32 v47, 0, v47
	v_max_f32_e32 v43, 0, v43
	v_max_f32_e32 v36, 0, v36
	v_max_f32_e32 v32, 0, v32
	v_max_f32_e32 v37, 0, v37
	v_max_f32_e32 v33, 0, v33
	v_max_f32_e32 v38, 0, v38
	v_max_f32_e32 v34, 0, v34
	v_max_f32_e32 v39, 0, v39
	v_max_f32_e32 v35, 0, v35
	v_mul_f32_e32 v44, v44, v44
	v_mul_f32_e32 v40, v40, v40
	v_mul_f32_e32 v45, v45, v45
	v_mul_f32_e32 v41, v41, v41
	v_mul_f32_e32 v46, v46, v46
	v_mul_f32_e32 v42, v42, v42
	v_mul_f32_e32 v47, v47, v47
	v_mul_f32_e32 v43, v43, v43
	v_addc_co_u32_e64 v51, s[0:1], 0, v145, s[0:1]
	v_mul_f32_e32 v36, v36, v36
	v_mul_f32_e32 v52, v32, v32
	v_mul_f32_e32 v37, v37, v37
	v_mul_f32_e32 v53, v33, v33
	v_mul_f32_e32 v38, v38, v38
	v_mul_f32_e32 v54, v34, v34
	v_mul_f32_e32 v39, v39, v39
	v_mul_f32_e32 v55, v35, v35
	v_cvt_pk_bf16_f32 v32, v44, v45
	v_cvt_pk_bf16_f32 v33, v46, v47
	v_cvt_pk_bf16_f32 v34, v40, v41
	v_cvt_pk_bf16_f32 v35, v42, v43
	v_cvt_pk_bf16_f32 v36, v36, v37
	v_cvt_pk_bf16_f32 v37, v38, v39
	v_cvt_pk_bf16_f32 v38, v52, v53
	v_cvt_pk_bf16_f32 v39, v54, v55
	global_store_dwordx4 v[50:51], v[32:35], off
	global_store_dwordx4 v[48:49], v[36:39], off offset:256
	v_lshl_add_u64 v[32:33], v[144:145], 0, s[16:17]
	s_waitcnt vmcnt(13)
	v_fmamk_f32 v34, v242, 0x3a000000, v158
	v_mul_f32_e32 v35, 0x4b800000, v34
	v_cmp_gt_f32_e32 vcc, s50, v34
	s_nop 1
	v_cndmask_b32_e32 v34, v34, v35, vcc
	v_rsq_f32_e32 v36, v34
	v_add_co_u32_e64 v34, s[0:1], s53, v144
	v_mul_f32_e32 v37, 0x45800000, v36
	v_cndmask_b32_e32 v36, v36, v37, vcc
	v_pk_mul_f32 v[30:31], v[30:31], v[36:37] op_sel_hi:[1,0]
	v_pk_mul_f32 v[28:29], v[28:29], v[36:37] op_sel_hi:[1,0]
	v_pk_mul_f32 v[26:27], v[26:27], v[36:37] op_sel_hi:[1,0]
	v_pk_mul_f32 v[24:25], v[24:25], v[36:37] op_sel_hi:[1,0]
	v_pk_mul_f32 v[22:23], v[22:23], v[36:37] op_sel_hi:[1,0]
	v_pk_mul_f32 v[20:21], v[20:21], v[36:37] op_sel_hi:[1,0]
	v_pk_mul_f32 v[18:19], v[18:19], v[36:37] op_sel_hi:[1,0]
	v_pk_mul_f32 v[16:17], v[16:17], v[36:37] op_sel_hi:[1,0]
	v_max_f32_e32 v28, 0, v28
	v_max_f32_e32 v24, 0, v24
	v_max_f32_e32 v29, 0, v29
	v_max_f32_e32 v25, 0, v25
	v_max_f32_e32 v30, 0, v30
	v_max_f32_e32 v26, 0, v26
	v_max_f32_e32 v31, 0, v31
	v_max_f32_e32 v27, 0, v27
	v_max_f32_e32 v20, 0, v20
	v_max_f32_e32 v16, 0, v16
	v_max_f32_e32 v21, 0, v21
	v_max_f32_e32 v17, 0, v17
	v_max_f32_e32 v22, 0, v22
	v_max_f32_e32 v18, 0, v18
	v_max_f32_e32 v23, 0, v23
	v_max_f32_e32 v19, 0, v19
	v_mul_f32_e32 v28, v28, v28
	v_mul_f32_e32 v24, v24, v24
	v_mul_f32_e32 v29, v29, v29
	v_mul_f32_e32 v25, v25, v25
	v_mul_f32_e32 v30, v30, v30
	v_mul_f32_e32 v26, v26, v26
	v_mul_f32_e32 v31, v31, v31
	v_mul_f32_e32 v27, v27, v27
	v_addc_co_u32_e64 v35, s[0:1], 0, v145, s[0:1]
	v_mul_f32_e32 v20, v20, v20
	v_mul_f32_e32 v36, v16, v16
	v_mul_f32_e32 v21, v21, v21
	v_mul_f32_e32 v37, v17, v17
	v_mul_f32_e32 v22, v22, v22
	v_mul_f32_e32 v38, v18, v18
	v_mul_f32_e32 v23, v23, v23
	v_mul_f32_e32 v39, v19, v19
	v_cvt_pk_bf16_f32 v16, v28, v29
	v_cvt_pk_bf16_f32 v17, v30, v31
	v_cvt_pk_bf16_f32 v18, v24, v25
	v_cvt_pk_bf16_f32 v19, v26, v27
	v_cvt_pk_bf16_f32 v20, v20, v21
	v_cvt_pk_bf16_f32 v21, v22, v23
	v_cvt_pk_bf16_f32 v22, v36, v37
	v_cvt_pk_bf16_f32 v23, v38, v39
	global_store_dwordx4 v[34:35], v[16:19], off
	global_store_dwordx4 v[32:33], v[20:23], off offset:256
	s_and_b64 vcc, exec, s[2:3]
	v_lshl_add_u64 v[16:17], v[144:145], 0, s[18:19]
	s_waitcnt vmcnt(14)
	v_fmamk_f32 v18, v243, 0x3a000000, v158
	v_mul_f32_e32 v19, 0x4b800000, v18
	v_cmp_gt_f32_e64 s[0:1], s50, v18
	s_nop 1
	v_cndmask_b32_e64 v18, v18, v19, s[0:1]
	v_rsq_f32_e32 v20, v18
	v_add_co_u32_e64 v18, s[2:3], s54, v144
	v_mul_f32_e32 v21, 0x45800000, v20
	v_cndmask_b32_e64 v20, v20, v21, s[0:1]
	v_pk_mul_f32 v[14:15], v[14:15], v[20:21] op_sel_hi:[1,0]
	v_pk_mul_f32 v[12:13], v[12:13], v[20:21] op_sel_hi:[1,0]
	v_pk_mul_f32 v[10:11], v[10:11], v[20:21] op_sel_hi:[1,0]
	v_pk_mul_f32 v[8:9], v[8:9], v[20:21] op_sel_hi:[1,0]
	v_pk_mul_f32 v[6:7], v[6:7], v[20:21] op_sel_hi:[1,0]
	v_pk_mul_f32 v[4:5], v[4:5], v[20:21] op_sel_hi:[1,0]
	v_pk_mul_f32 v[2:3], v[2:3], v[20:21] op_sel_hi:[1,0]
	v_pk_mul_f32 v[0:1], v[0:1], v[20:21] op_sel_hi:[1,0]
	v_max_f32_e32 v12, 0, v12
	v_max_f32_e32 v8, 0, v8
	v_max_f32_e32 v13, 0, v13
	v_max_f32_e32 v9, 0, v9
	v_max_f32_e32 v14, 0, v14
	v_max_f32_e32 v10, 0, v10
	v_max_f32_e32 v15, 0, v15
	v_max_f32_e32 v11, 0, v11
	v_max_f32_e32 v4, 0, v4
	v_max_f32_e32 v0, 0, v0
	v_max_f32_e32 v5, 0, v5
	v_max_f32_e32 v1, 0, v1
	v_max_f32_e32 v6, 0, v6
	v_max_f32_e32 v2, 0, v2
	v_max_f32_e32 v7, 0, v7
	v_max_f32_e32 v3, 0, v3
	v_mul_f32_e32 v12, v12, v12
	v_mul_f32_e32 v8, v8, v8
	v_mul_f32_e32 v13, v13, v13
	v_mul_f32_e32 v9, v9, v9
	v_mul_f32_e32 v14, v14, v14
	v_mul_f32_e32 v10, v10, v10
	v_mul_f32_e32 v15, v15, v15
	v_mul_f32_e32 v11, v11, v11
	v_addc_co_u32_e64 v19, s[2:3], 0, v145, s[2:3]
	v_mul_f32_e32 v4, v4, v4
	v_mul_f32_e32 v20, v0, v0
	v_mul_f32_e32 v5, v5, v5
	v_mul_f32_e32 v21, v1, v1
	v_mul_f32_e32 v6, v6, v6
	v_mul_f32_e32 v22, v2, v2
	v_mul_f32_e32 v7, v7, v7
	v_mul_f32_e32 v23, v3, v3
	v_cvt_pk_bf16_f32 v0, v12, v13
	v_cvt_pk_bf16_f32 v1, v14, v15
	v_cvt_pk_bf16_f32 v2, v8, v9
	v_cvt_pk_bf16_f32 v3, v10, v11
	v_cvt_pk_bf16_f32 v4, v4, v5
	v_cvt_pk_bf16_f32 v5, v6, v7
	v_cvt_pk_bf16_f32 v6, v20, v21
	v_cvt_pk_bf16_f32 v7, v22, v23
	global_store_dwordx4 v[18:19], v[0:3], off
	global_store_dwordx4 v[16:17], v[4:7], off offset:256
	s_cbranch_vccz .LBB0_1264
	s_waitcnt vmcnt(0)
	s_cmpk_gt_u32 s33, 0xff
	s_cbranch_scc1 .LBB0_1275
	s_barrier

.LBB0_1350:
	ds_read_b128 v[144:147], v151
	ds_read_b128 v[156:159], v151 offset:1024
	ds_read_b128 v[160:163], v151 offset:2048
	ds_read_b128 v[164:167], v151 offset:3072
	s_add_u32 s26, s24, 0xffe00080
	s_addc_u32 s27, s25, -1
	s_cmpk_eq_i32 s49, 0x7c
	s_cselect_b32 s29, s15, s27
	s_cselect_b32 s28, s21, s26
	s_cselect_b32 s27, s13, s48
	s_cselect_b32 s26, s46, s47
	v_lshl_add_u64 v[168:169], s[24:25], 0, v[136:137]
	s_add_i32 m0, s23, 0xc000
	ds_read_b128 v[172:175], v152
	ds_read_b128 v[176:179], v152 offset:1024
	ds_read_b128 v[180:183], v152 offset:2048
	ds_read_b128 v[184:187], v152 offset:3072
	ds_read_b128 v[188:191], v152 offset:4096
	ds_read_b128 v[192:195], v152 offset:5120
	ds_read_b128 v[196:199], v152 offset:6144
	ds_read_b128 v[200:203], v152 offset:7168
	global_load_lds_dwordx4 v[168:169], off
	v_lshl_add_u64 v[168:169], s[24:25], 0, v[138:139]
	s_add_i32 m0, s23, 0xe000
	s_nop 0
	global_load_lds_dwordx4 v[168:169], off
	s_waitcnt lgkmcnt(8)
	s_barrier
	s_waitcnt lgkmcnt(0)
	s_setprio 1
	s_waitcnt lgkmcnt(0)
	v_mfma_f32_16x16x32_bf16 v[124:127], v[144:147], v[172:175], v[124:127]
	v_mfma_f32_16x16x32_bf16 v[120:123], v[160:163], v[172:175], v[120:123]
	v_mfma_f32_16x16x32_bf16 v[108:111], v[144:147], v[180:183], v[108:111]
	v_mfma_f32_16x16x32_bf16 v[104:107], v[160:163], v[180:183], v[104:107]
	v_mfma_f32_16x16x32_bf16 v[92:95], v[144:147], v[188:191], v[92:95]
	v_mfma_f32_16x16x32_bf16 v[88:91], v[160:163], v[188:191], v[88:91]
	v_mfma_f32_16x16x32_bf16 v[76:79], v[144:147], v[196:199], v[76:79]
	v_mfma_f32_16x16x32_bf16 v[72:75], v[160:163], v[196:199], v[72:75]
	v_mfma_f32_16x16x32_bf16 v[124:127], v[156:159], v[176:179], v[124:127]
	v_mfma_f32_16x16x32_bf16 v[120:123], v[164:167], v[176:179], v[120:123]
	v_mfma_f32_16x16x32_bf16 v[108:111], v[156:159], v[184:187], v[108:111]
	v_mfma_f32_16x16x32_bf16 v[104:107], v[164:167], v[184:187], v[104:107]
	v_mfma_f32_16x16x32_bf16 v[92:95], v[156:159], v[192:195], v[92:95]
	v_mfma_f32_16x16x32_bf16 v[88:91], v[164:167], v[192:195], v[88:91]
	v_mfma_f32_16x16x32_bf16 v[76:79], v[156:159], v[200:203], v[76:79]
	v_mfma_f32_16x16x32_bf16 v[72:75], v[164:167], v[200:203], v[72:75]
	s_setprio 0
	s_barrier
	s_add_i32 s50, s44, s34
	v_lshl_add_u64 v[168:169], s[26:27], 0, v[130:131]
	s_mov_b32 m0, s50
	ds_read_b128 v[204:207], v153
	ds_read_b128 v[208:211], v153 offset:1024
	ds_read_b128 v[212:215], v153 offset:2048
	ds_read_b128 v[216:219], v153 offset:3072
	global_load_lds_dwordx4 v[168:169], off
	v_lshl_add_u64 v[220:221], s[26:27], 0, v[134:135]
	s_add_i32 m0, s50, 0x2000
	s_nop 0
	global_load_lds_dwordx4 v[220:221], off
	s_barrier
	s_waitcnt lgkmcnt(0)
	s_setprio 1
	s_waitcnt lgkmcnt(0)
	v_mfma_f32_16x16x32_bf16 v[116:119], v[204:207], v[172:175], v[116:119]
	v_mfma_f32_16x16x32_bf16 v[112:115], v[212:215], v[172:175], v[112:115]
	v_mfma_f32_16x16x32_bf16 v[100:103], v[204:207], v[180:183], v[100:103]
	v_mfma_f32_16x16x32_bf16 v[96:99], v[212:215], v[180:183], v[96:99]
	v_mfma_f32_16x16x32_bf16 v[84:87], v[204:207], v[188:191], v[84:87]
	v_mfma_f32_16x16x32_bf16 v[80:83], v[212:215], v[188:191], v[80:83]
	v_mfma_f32_16x16x32_bf16 v[68:71], v[204:207], v[196:199], v[68:71]
	v_mfma_f32_16x16x32_bf16 v[64:67], v[212:215], v[196:199], v[64:67]
	v_mfma_f32_16x16x32_bf16 v[116:119], v[208:211], v[176:179], v[116:119]
	v_mfma_f32_16x16x32_bf16 v[112:115], v[216:219], v[176:179], v[112:115]
	v_mfma_f32_16x16x32_bf16 v[100:103], v[208:211], v[184:187], v[100:103]
	v_mfma_f32_16x16x32_bf16 v[96:99], v[216:219], v[184:187], v[96:99]
	v_mfma_f32_16x16x32_bf16 v[84:87], v[208:211], v[192:195], v[84:87]
	v_mfma_f32_16x16x32_bf16 v[80:83], v[216:219], v[192:195], v[80:83]
	v_mfma_f32_16x16x32_bf16 v[68:71], v[208:211], v[200:203], v[68:71]
	v_mfma_f32_16x16x32_bf16 v[64:67], v[216:219], v[200:203], v[64:67]
	s_setprio 0
	s_mov_b32 m0, s23
	v_lshl_add_u64 v[222:223], s[28:29], 0, v[128:129]
	s_barrier
	ds_read_b128 v[172:175], v152 offset:16384
	ds_read_b128 v[176:179], v152 offset:17408
	ds_read_b128 v[180:183], v152 offset:18432
	ds_read_b128 v[184:187], v152 offset:19456
	ds_read_b128 v[188:191], v152 offset:20480
	ds_read_b128 v[192:195], v152 offset:21504
	ds_read_b128 v[196:199], v152 offset:22528
	ds_read_b128 v[200:203], v152 offset:23552
	global_load_lds_dwordx4 v[222:223], off
	v_lshl_add_u64 v[224:225], s[28:29], 0, v[132:133]
	s_mov_b32 m0, s35
	s_nop 0
	global_load_lds_dwordx4 v[224:225], off
	s_barrier
	s_waitcnt lgkmcnt(0)
	s_setprio 1
	s_waitcnt lgkmcnt(0)
	v_mfma_f32_16x16x32_bf16 v[60:63], v[144:147], v[172:175], v[60:63]
	v_mfma_f32_16x16x32_bf16 v[56:59], v[160:163], v[172:175], v[56:59]
	v_mfma_f32_16x16x32_bf16 v[44:47], v[144:147], v[180:183], v[44:47]
	v_mfma_f32_16x16x32_bf16 v[40:43], v[160:163], v[180:183], v[40:43]
	v_mfma_f32_16x16x32_bf16 v[28:31], v[144:147], v[188:191], v[28:31]
	v_mfma_f32_16x16x32_bf16 v[24:27], v[160:163], v[188:191], v[24:27]
	v_mfma_f32_16x16x32_bf16 v[12:15], v[144:147], v[196:199], v[12:15]
	v_mfma_f32_16x16x32_bf16 v[8:11], v[160:163], v[196:199], v[8:11]
	v_mfma_f32_16x16x32_bf16 v[60:63], v[156:159], v[176:179], v[60:63]
	v_mfma_f32_16x16x32_bf16 v[56:59], v[164:167], v[176:179], v[56:59]
	v_mfma_f32_16x16x32_bf16 v[44:47], v[156:159], v[184:187], v[44:47]
	v_mfma_f32_16x16x32_bf16 v[40:43], v[164:167], v[184:187], v[40:43]
	v_mfma_f32_16x16x32_bf16 v[28:31], v[156:159], v[192:195], v[28:31]
	v_mfma_f32_16x16x32_bf16 v[24:27], v[164:167], v[192:195], v[24:27]
	v_mfma_f32_16x16x32_bf16 v[12:15], v[156:159], v[200:203], v[12:15]
	v_mfma_f32_16x16x32_bf16 v[8:11], v[164:167], v[200:203], v[8:11]
	s_setprio 0
	s_barrier
	s_add_u32 s50, s26, 0x200000
	s_addc_u32 s51, s27, 0
	s_add_i32 s52, s45, s34
	v_lshl_add_u64 v[144:145], s[50:51], 0, v[130:131]
	s_mov_b32 m0, s52
	s_nop 0
	global_load_lds_dwordx4 v[144:145], off
	v_lshl_add_u64 v[144:145], s[50:51], 0, v[134:135]
	s_add_i32 m0, s52, 0x2000
	s_nop 0
	global_load_lds_dwordx4 v[144:145], off
	s_waitcnt vmcnt(6)
	s_barrier
	s_setprio 1
	v_mfma_f32_16x16x32_bf16 v[52:55], v[204:207], v[172:175], v[52:55]
	v_mfma_f32_16x16x32_bf16 v[48:51], v[212:215], v[172:175], v[48:51]
	v_mfma_f32_16x16x32_bf16 v[36:39], v[204:207], v[180:183], v[36:39]
	v_mfma_f32_16x16x32_bf16 v[32:35], v[212:215], v[180:183], v[32:35]
	v_mfma_f32_16x16x32_bf16 v[20:23], v[204:207], v[188:191], v[20:23]
	v_mfma_f32_16x16x32_bf16 v[16:19], v[212:215], v[188:191], v[16:19]
	v_mfma_f32_16x16x32_bf16 v[4:7], v[204:207], v[196:199], v[4:7]
	v_mfma_f32_16x16x32_bf16 v[0:3], v[212:215], v[196:199], v[0:3]
	v_mfma_f32_16x16x32_bf16 v[52:55], v[208:211], v[176:179], v[52:55]
	v_mfma_f32_16x16x32_bf16 v[48:51], v[216:219], v[176:179], v[48:51]
	v_mfma_f32_16x16x32_bf16 v[36:39], v[208:211], v[184:187], v[36:39]
	v_mfma_f32_16x16x32_bf16 v[32:35], v[216:219], v[184:187], v[32:35]
	v_mfma_f32_16x16x32_bf16 v[20:23], v[208:211], v[192:195], v[20:23]
	v_mfma_f32_16x16x32_bf16 v[16:19], v[216:219], v[192:195], v[16:19]
	v_mfma_f32_16x16x32_bf16 v[4:7], v[208:211], v[200:203], v[4:7]
	v_mfma_f32_16x16x32_bf16 v[0:3], v[216:219], v[200:203], v[0:3]
	s_setprio 0
	s_add_i32 s50, 0, 0x18000
	v_add_u32_e32 v155, s50, v149
	s_barrier
	ds_read_b128 v[144:147], v155
	ds_read_b128 v[156:159], v155 offset:1024
	ds_read_b128 v[160:163], v155 offset:2048
	ds_read_b128 v[164:167], v155 offset:3072
	s_add_u32 s28, s28, 0x200000
	s_addc_u32 s29, s29, 0
	s_mov_b32 m0, s36
	v_lshl_add_u64 v[204:205], s[28:29], 0, v[128:129]
	ds_read_b128 v[172:175], v152 offset:32768
	ds_read_b128 v[176:179], v152 offset:33792
	ds_read_b128 v[180:183], v152 offset:34816
	ds_read_b128 v[184:187], v152 offset:35840
	ds_read_b128 v[188:191], v152 offset:36864
	ds_read_b128 v[192:195], v152 offset:37888
	ds_read_b128 v[196:199], v152 offset:38912
	ds_read_b128 v[200:203], v152 offset:39936
	global_load_lds_dwordx4 v[204:205], off
	v_lshl_add_u64 v[204:205], s[28:29], 0, v[132:133]
	s_mov_b32 m0, s37
	s_nop 0
	global_load_lds_dwordx4 v[204:205], off
	s_waitcnt lgkmcnt(8)
	s_barrier
	s_waitcnt lgkmcnt(0)
	s_setprio 1
	s_waitcnt lgkmcnt(0)
	v_mfma_f32_16x16x32_bf16 v[124:127], v[144:147], v[172:175], v[124:127]
	v_mfma_f32_16x16x32_bf16 v[120:123], v[160:163], v[172:175], v[120:123]
	v_mfma_f32_16x16x32_bf16 v[108:111], v[144:147], v[180:183], v[108:111]
	v_mfma_f32_16x16x32_bf16 v[104:107], v[160:163], v[180:183], v[104:107]
	v_mfma_f32_16x16x32_bf16 v[92:95], v[144:147], v[188:191], v[92:95]
	v_mfma_f32_16x16x32_bf16 v[88:91], v[160:163], v[188:191], v[88:91]
	v_mfma_f32_16x16x32_bf16 v[76:79], v[144:147], v[196:199], v[76:79]
	v_mfma_f32_16x16x32_bf16 v[72:75], v[160:163], v[196:199], v[72:75]
	v_mfma_f32_16x16x32_bf16 v[124:127], v[156:159], v[176:179], v[124:127]
	v_mfma_f32_16x16x32_bf16 v[120:123], v[164:167], v[176:179], v[120:123]
	v_mfma_f32_16x16x32_bf16 v[108:111], v[156:159], v[184:187], v[108:111]
	v_mfma_f32_16x16x32_bf16 v[104:107], v[164:167], v[184:187], v[104:107]
	v_mfma_f32_16x16x32_bf16 v[92:95], v[156:159], v[192:195], v[92:95]
	v_mfma_f32_16x16x32_bf16 v[88:91], v[164:167], v[192:195], v[88:91]
	v_mfma_f32_16x16x32_bf16 v[76:79], v[156:159], v[200:203], v[76:79]
	v_mfma_f32_16x16x32_bf16 v[72:75], v[164:167], v[200:203], v[72:75]
	s_setprio 0
	s_barrier
	s_add_i32 s28, 0, 0x1c000
	s_add_i32 s29, s50, s34
	v_add_u32_e32 v155, s28, v149
	v_lshl_add_u64 v[168:169], v[168:169], 0, s[10:11]
	s_mov_b32 m0, s29
	ds_read_b128 v[204:207], v155
	ds_read_b128 v[208:211], v155 offset:1024
	ds_read_b128 v[212:215], v155 offset:2048
	ds_read_b128 v[216:219], v155 offset:3072
	global_load_lds_dwordx4 v[168:169], off
	v_lshl_add_u64 v[168:169], v[220:221], 0, s[10:11]
	s_add_i32 m0, s29, 0x2000
	s_nop 0
	global_load_lds_dwordx4 v[168:169], off
	s_barrier
	s_waitcnt lgkmcnt(0)
	s_setprio 1
	s_waitcnt lgkmcnt(0)
	v_mfma_f32_16x16x32_bf16 v[116:119], v[204:207], v[172:175], v[116:119]
	v_mfma_f32_16x16x32_bf16 v[112:115], v[212:215], v[172:175], v[112:115]
	v_mfma_f32_16x16x32_bf16 v[100:103], v[204:207], v[180:183], v[100:103]
	v_mfma_f32_16x16x32_bf16 v[96:99], v[212:215], v[180:183], v[96:99]
	v_mfma_f32_16x16x32_bf16 v[84:87], v[204:207], v[188:191], v[84:87]
	v_mfma_f32_16x16x32_bf16 v[80:83], v[212:215], v[188:191], v[80:83]
	v_mfma_f32_16x16x32_bf16 v[68:71], v[204:207], v[196:199], v[68:71]
	v_mfma_f32_16x16x32_bf16 v[64:67], v[212:215], v[196:199], v[64:67]
	v_mfma_f32_16x16x32_bf16 v[116:119], v[208:211], v[176:179], v[116:119]
	v_mfma_f32_16x16x32_bf16 v[112:115], v[216:219], v[176:179], v[112:115]
	v_mfma_f32_16x16x32_bf16 v[100:103], v[208:211], v[184:187], v[100:103]
	v_mfma_f32_16x16x32_bf16 v[96:99], v[216:219], v[184:187], v[96:99]
	v_mfma_f32_16x16x32_bf16 v[84:87], v[208:211], v[192:195], v[84:87]
	v_mfma_f32_16x16x32_bf16 v[80:83], v[216:219], v[192:195], v[80:83]
	v_mfma_f32_16x16x32_bf16 v[68:71], v[208:211], v[200:203], v[68:71]
	v_mfma_f32_16x16x32_bf16 v[64:67], v[216:219], v[200:203], v[64:67]
	s_setprio 0
	s_mov_b32 m0, s39
	v_lshl_add_u64 v[168:169], v[222:223], 0, s[10:11]
	s_barrier
	ds_read_b128 v[172:175], v152 offset:49152
	ds_read_b128 v[176:179], v152 offset:50176
	ds_read_b128 v[180:183], v152 offset:51200
	ds_read_b128 v[184:187], v152 offset:52224
	ds_read_b128 v[188:191], v152 offset:53248
	ds_read_b128 v[192:195], v152 offset:54272
	ds_read_b128 v[196:199], v152 offset:55296
	ds_read_b128 v[200:203], v152 offset:56320
	global_load_lds_dwordx4 v[168:169], off
	v_lshl_add_u64 v[168:169], v[224:225], 0, s[10:11]
	s_mov_b32 m0, s40
	s_nop 0
	global_load_lds_dwordx4 v[168:169], off
	s_barrier
	s_waitcnt lgkmcnt(0)
	s_setprio 1
	s_waitcnt lgkmcnt(0)
	v_mfma_f32_16x16x32_bf16 v[60:63], v[144:147], v[172:175], v[60:63]
	v_mfma_f32_16x16x32_bf16 v[56:59], v[160:163], v[172:175], v[56:59]
	v_mfma_f32_16x16x32_bf16 v[44:47], v[144:147], v[180:183], v[44:47]
	v_mfma_f32_16x16x32_bf16 v[40:43], v[160:163], v[180:183], v[40:43]
	v_mfma_f32_16x16x32_bf16 v[28:31], v[144:147], v[188:191], v[28:31]
	v_mfma_f32_16x16x32_bf16 v[24:27], v[160:163], v[188:191], v[24:27]
	v_mfma_f32_16x16x32_bf16 v[12:15], v[144:147], v[196:199], v[12:15]
	v_mfma_f32_16x16x32_bf16 v[8:11], v[160:163], v[196:199], v[8:11]
	v_mfma_f32_16x16x32_bf16 v[60:63], v[156:159], v[176:179], v[60:63]
	v_mfma_f32_16x16x32_bf16 v[56:59], v[164:167], v[176:179], v[56:59]
	v_mfma_f32_16x16x32_bf16 v[44:47], v[156:159], v[184:187], v[44:47]
	v_mfma_f32_16x16x32_bf16 v[40:43], v[164:167], v[184:187], v[40:43]
	v_mfma_f32_16x16x32_bf16 v[28:31], v[156:159], v[192:195], v[28:31]
	v_mfma_f32_16x16x32_bf16 v[24:27], v[164:167], v[192:195], v[24:27]
	v_mfma_f32_16x16x32_bf16 v[12:15], v[156:159], v[200:203], v[12:15]
	v_mfma_f32_16x16x32_bf16 v[8:11], v[164:167], v[200:203], v[8:11]
	s_setprio 0
	s_barrier
	s_add_u32 s26, s26, 0x200080
	s_addc_u32 s27, s27, 0
	s_add_i32 s28, s28, s34
	v_lshl_add_u64 v[144:145], s[26:27], 0, v[130:131]
	s_mov_b32 m0, s28
	s_nop 0
	global_load_lds_dwordx4 v[144:145], off
	v_lshl_add_u64 v[144:145], s[26:27], 0, v[134:135]
	s_add_i32 m0, s28, 0x2000
	s_nop 0
	global_load_lds_dwordx4 v[144:145], off
	s_waitcnt vmcnt(6)
	s_barrier
	s_setprio 1
	v_mfma_f32_16x16x32_bf16 v[52:55], v[204:207], v[172:175], v[52:55]
	v_mfma_f32_16x16x32_bf16 v[48:51], v[212:215], v[172:175], v[48:51]
	v_mfma_f32_16x16x32_bf16 v[36:39], v[204:207], v[180:183], v[36:39]
	v_mfma_f32_16x16x32_bf16 v[32:35], v[212:215], v[180:183], v[32:35]
	v_mfma_f32_16x16x32_bf16 v[20:23], v[204:207], v[188:191], v[20:23]
	v_mfma_f32_16x16x32_bf16 v[16:19], v[212:215], v[188:191], v[16:19]
	v_mfma_f32_16x16x32_bf16 v[4:7], v[204:207], v[196:199], v[4:7]
	v_mfma_f32_16x16x32_bf16 v[0:3], v[212:215], v[196:199], v[0:3]
	v_mfma_f32_16x16x32_bf16 v[52:55], v[208:211], v[176:179], v[52:55]
	v_mfma_f32_16x16x32_bf16 v[48:51], v[216:219], v[176:179], v[48:51]
	v_mfma_f32_16x16x32_bf16 v[36:39], v[208:211], v[184:187], v[36:39]
	v_mfma_f32_16x16x32_bf16 v[32:35], v[216:219], v[184:187], v[32:35]
	v_mfma_f32_16x16x32_bf16 v[20:23], v[208:211], v[192:195], v[20:23]
	v_mfma_f32_16x16x32_bf16 v[16:19], v[216:219], v[192:195], v[16:19]
	v_mfma_f32_16x16x32_bf16 v[4:7], v[208:211], v[200:203], v[4:7]
	v_mfma_f32_16x16x32_bf16 v[0:3], v[216:219], v[200:203], v[0:3]
	s_setprio 0
	s_add_i32 s49, s49, 2
	s_add_u32 s24, s24, 0x100
	s_addc_u32 s25, s25, 0
	s_add_u32 s47, s47, 0x100
	s_addc_u32 s48, s48, 0
	s_cmpk_gt_u32 s49, 0x7d
	s_barrier
	s_cbranch_scc0 .LBB0_1350
	v_lshl_add_u32 v146, s20, 8, v148
	v_ashrrev_i32_e32 v147, 31, v146
	v_lshl_or_b32 v144, s22, 8, v150
	v_lshlrev_b32_e32 v179, 12, v146
	v_lshl_add_u32 v178, v144, 1, v179
	global_load_dwordx4 v[180:183], v178, s[6:7]
	global_load_dwordx4 v[184:187], v178, s[6:7] offset:256
	s_add_u32 s98, s6, 0x10000
	s_addc_u32 s99, s7, 0
	global_load_dwordx4 v[188:191], v178, s[98:99]
	global_load_dwordx4 v[192:195], v178, s[98:99] offset:256
	s_add_u32 s98, s6, 0x20000
	s_addc_u32 s99, s7, 0
	global_load_dwordx4 v[196:199], v178, s[98:99]
	global_load_dwordx4 v[200:203], v178, s[98:99] offset:256
	s_add_u32 s98, s6, 0x30000
	s_addc_u32 s99, s7, 0
	global_load_dwordx4 v[204:207], v178, s[98:99]
	global_load_dwordx4 v[208:211], v178, s[98:99] offset:256
	s_add_u32 s98, s6, 0x80000
	s_addc_u32 s99, s7, 0
	global_load_dwordx4 v[212:215], v178, s[98:99]
	global_load_dwordx4 v[216:219], v178, s[98:99] offset:256
	s_add_u32 s98, s6, 0x90000
	s_addc_u32 s99, s7, 0
	global_load_dwordx4 v[236:239], v178, s[98:99]
	global_load_dwordx4 v[240:243], v178, s[98:99] offset:256
	s_add_u32 s98, s6, 0xa0000
	s_addc_u32 s99, s7, 0
	global_load_dwordx4 v[244:247], v178, s[98:99]
	global_load_dwordx4 v[248:251], v178, s[98:99] offset:256
	s_add_u32 s98, s6, 0xb0000
	s_addc_u32 s99, s7, 0
	global_load_dwordx4 v[220:223], v178, s[98:99]
	global_load_dwordx4 v[252:255], v178, s[98:99] offset:256
	v_lshlrev_b64 v[156:157], 12, v[146:147]
	v_ashrrev_i32_e32 v145, 31, v144
	v_lshl_add_u64 v[156:157], s[6:7], 0, v[156:157]
	v_lshl_add_u64 v[166:167], v[144:145], 1, v[156:157]
	v_and_b32_e32 v156, 64, v154
	v_xor_b32_e32 v155, 16, v154
	v_add_u32_e32 v156, 64, v156
	v_xor_b32_e32 v157, 32, v154
	v_cmp_lt_i32_e32 vcc, v155, v156
	s_waitcnt vmcnt(14)
	v_lshlrev_b32_e32 v168, 16, v180
	v_and_b32_e32 v169, 0xffff0000, v180
	v_lshlrev_b32_e32 v180, 16, v181
	v_and_b32_e32 v181, 0xffff0000, v181
	v_lshlrev_b32_e32 v174, 16, v184
	v_and_b32_e32 v175, 0xffff0000, v184
	v_lshlrev_b32_e32 v184, 16, v185
	v_and_b32_e32 v185, 0xffff0000, v185
	v_cndmask_b32_e32 v155, v154, v155, vcc
	v_cmp_lt_i32_e32 vcc, v157, v156
	v_lshlrev_b32_e32 v172, 16, v182
	v_and_b32_e32 v173, 0xffff0000, v182
	v_lshlrev_b32_e32 v182, 16, v183
	v_and_b32_e32 v183, 0xffff0000, v183
	v_lshlrev_b32_e32 v176, 16, v186
	v_and_b32_e32 v177, 0xffff0000, v186
	v_lshlrev_b32_e32 v186, 16, v187
	v_and_b32_e32 v187, 0xffff0000, v187
	v_pk_add_f32 v[126:127], v[126:127], v[180:181]
	v_pk_add_f32 v[124:125], v[124:125], v[168:169]
	v_pk_add_f32 v[118:119], v[118:119], v[184:185]
	v_pk_add_f32 v[116:117], v[116:117], v[174:175]
	v_cndmask_b32_e32 v157, v154, v157, vcc
	v_pk_add_f32 v[122:123], v[122:123], v[182:183]
	v_pk_add_f32 v[120:121], v[120:121], v[172:173]
	v_pk_add_f32 v[180:181], v[114:115], v[186:187]
	v_pk_add_f32 v[182:183], v[112:113], v[176:177]
	v_mul_f32_e32 v114, v125, v125
	v_mul_f32_e32 v115, v127, v127
	v_cvt_pk_bf16_f32 v112, v124, v125
	v_cvt_pk_bf16_f32 v113, v126, v127
	v_mul_f32_e32 v125, v117, v117
	v_mul_f32_e32 v127, v119, v119
	v_lshlrev_b32_e32 v156, 2, v155
	v_lshlrev_b32_e32 v155, 2, v157
	v_mul_f32_e32 v157, v121, v121
	v_mul_f32_e32 v185, v183, v183
	v_fmac_f32_e32 v114, v124, v124
	v_fmac_f32_e32 v115, v126, v126
	v_fmac_f32_e32 v125, v116, v116
	v_fmac_f32_e32 v127, v118, v118
	v_mul_f32_e32 v184, v123, v123
	v_mul_f32_e32 v186, v181, v181
	v_fmac_f32_e32 v157, v120, v120
	v_fmac_f32_e32 v185, v182, v182
	v_add_f32_e32 v114, v114, v115
	v_add_f32_e32 v115, v125, v127
	v_fmac_f32_e32 v184, v122, v122
	v_fmac_f32_e32 v186, v180, v180
	v_add_f32_e32 v114, v157, v114
	v_add_f32_e32 v115, v185, v115
	v_add_f32_e32 v114, v184, v114
	v_add_f32_e32 v115, v186, v115
	v_add_f32_e32 v124, v114, v115
	ds_bpermute_b32 v125, v156, v124
	v_cvt_pk_bf16_f32 v114, v120, v121
	v_cvt_pk_bf16_f32 v115, v122, v123
	global_store_dwordx4 v[166:167], v[112:115], off
	s_waitcnt lgkmcnt(0)
	s_nop 0
	v_add_f32_e32 v112, v124, v125
	ds_bpermute_b32 v113, v155, v112
	v_cvt_pk_bf16_f32 v114, v116, v117
	v_cvt_pk_bf16_f32 v115, v118, v119
	v_cvt_pk_bf16_f32 v116, v182, v183
	v_cvt_pk_bf16_f32 v117, v180, v181
	global_store_dwordx4 v[166:167], v[114:117], off offset:256
	s_and_saveexec_b64 s[20:21], s[2:3]
	s_cbranch_execz .LBB0_1353
	v_lshl_add_u64 v[114:115], v[146:147], 2, s[8:9]
	s_waitcnt lgkmcnt(0)
	v_add_f32_e32 v112, v112, v113
	global_atomic_add_f32 v[114:115], v112, off

	.amdhsa_kernel _Z9hymba_fwd4Args
		.amdhsa_group_segment_fixed_size 0
		.amdhsa_private_segment_fixed_size 0
		.amdhsa_kernarg_size 536
		.amdhsa_user_sgpr_count 2
		.amdhsa_user_sgpr_dispatch_ptr 0
		.amdhsa_user_sgpr_queue_ptr 0
		.amdhsa_user_sgpr_kernarg_segment_ptr 1
		.amdhsa_user_sgpr_dispatch_id 0
		.amdhsa_user_sgpr_kernarg_preload_length 0
		.amdhsa_user_sgpr_kernarg_preload_offset 0
		.amdhsa_user_sgpr_private_segment_size 0
		.amdhsa_uses_dynamic_stack 0
		.amdhsa_enable_private_segment 0
		.amdhsa_system_sgpr_workgroup_id_x 1
		.amdhsa_system_sgpr_workgroup_id_y 0
		.amdhsa_system_sgpr_workgroup_id_z 0
		.amdhsa_system_sgpr_workgroup_info 0
		.amdhsa_system_vgpr_workitem_id 2
		.amdhsa_next_free_vgpr 256
		.amdhsa_next_free_sgpr 102
		.amdhsa_accum_offset 256
		.amdhsa_reserve_vcc 1
		.amdhsa_float_round_mode_32 0
		.amdhsa_float_round_mode_16_64 0
		.amdhsa_float_denorm_mode_32 3
		.amdhsa_float_denorm_mode_16_64 3
		.amdhsa_dx10_clamp 1
		.amdhsa_ieee_mode 1
		.amdhsa_fp16_overflow 0
		.amdhsa_tg_split 0
		.amdhsa_exception_fp_ieee_invalid_op 0
		.amdhsa_exception_fp_denorm_src 0
		.amdhsa_exception_fp_ieee_div_zero 0
		.amdhsa_exception_fp_ieee_overflow 0
		.amdhsa_exception_fp_ieee_underflow 0
		.amdhsa_exception_fp_ieee_inexact 0
		.amdhsa_exception_int_div_zero 0
	.end_amdhsa_kernel

.Lfunc_end0:
	.size	_Z9hymba_fwd4Args, .Lfunc_end0-_Z9hymba_fwd4Args
	.set _Z9hymba_fwd4Args.num_vgpr, 256
	.set _Z9hymba_fwd4Args.num_agpr, 0
	.set _Z9hymba_fwd4Args.numbered_sgpr, 102
	.set _Z9hymba_fwd4Args.num_named_barrier, 0
	.set _Z9hymba_fwd4Args.private_seg_size, 0
	.set _Z9hymba_fwd4Args.uses_vcc, 1
	.set _Z9hymba_fwd4Args.uses_flat_scratch, 0
	.set _Z9hymba_fwd4Args.has_dyn_sized_stack, 0
	.set _Z9hymba_fwd4Args.has_recursion, 0
	.set _Z9hymba_fwd4Args.has_indirect_call, 0

amdhsa.kernels:
  - .agpr_count:     0
    .args:
      - .offset:         0
        .size:           280
        .value_kind:     by_value
      - .offset:         280
        .size:           4
        .value_kind:     hidden_block_count_x
      - .offset:         284
        .size:           4
        .value_kind:     hidden_block_count_y
      - .offset:         288
        .size:           4
        .value_kind:     hidden_block_count_z
      - .offset:         292
        .size:           2
        .value_kind:     hidden_group_size_x
      - .offset:         294
        .size:           2
        .value_kind:     hidden_group_size_y
      - .offset:         296
        .size:           2
        .value_kind:     hidden_group_size_z
      - .offset:         298
        .size:           2
        .value_kind:     hidden_remainder_x
      - .offset:         300
        .size:           2
        .value_kind:     hidden_remainder_y
      - .offset:         302
        .size:           2
        .value_kind:     hidden_remainder_z
      - .offset:         320
        .size:           8
        .value_kind:     hidden_global_offset_x
      - .offset:         328
        .size:           8
        .value_kind:     hidden_global_offset_y
      - .offset:         336
        .size:           8
        .value_kind:     hidden_global_offset_z
      - .offset:         344
        .size:           2
        .value_kind:     hidden_grid_dims
      - .offset:         368
        .size:           8
        .value_kind:     hidden_multigrid_sync_arg
      - .offset:         400
        .size:           4
        .value_kind:     hidden_dynamic_lds_size
    .group_segment_fixed_size: 0
    .kernarg_segment_align: 8
    .kernarg_segment_size: 536
    .language:       OpenCL C
    .language_version:
      - 2
      - 0
    .max_flat_workgroup_size: 512
    .name:           _Z9hymba_fwd4Args
    .private_segment_fixed_size: 0
    .sgpr_count:     108
    .sgpr_spill_count: 89
    .symbol:         _Z9hymba_fwd4Args.kd
    .uniform_work_group_size: 1
    .uses_dynamic_stack: false
    .vgpr_count:     256
    .vgpr_spill_count: 0
    .wavefront_size: 64
